# combined: attention QK MFMA-first reorder + Q/GA/O L2 touches, hand-written P1 non-q/k epilogue, GEMM first-iteration waits tolerate the epilogue stores, odd XCDs start P1 13 us late
# speedup vs baseline: 1.0130x; 1.0052x over previous
.LBB0_257:
	s_lshr_b32 s35, s85, 8
	s_bfe_u32 s84, s85, 0x20006
	s_lshl_b32 s88, s96, 10
	s_lshl_b32 s34, s35, 6
	s_lshl_b32 s27, s35, 13
	s_add_u32 s2, s22, 0x2800000
	v_writelane_b32 v253, s2, 59
	s_addc_u32 s2, s23, 0
	v_writelane_b32 v253, s2, 60
	s_add_u32 s2, s22, 0x6800000
	v_writelane_b32 v253, s2, 23
	s_addc_u32 s2, s23, 0
	s_add_u32 s30, s22, 0xa800000
	s_addc_u32 s31, s23, 0
	s_add_u32 s74, s20, 0x4000000
	s_addc_u32 s75, s21, 0
	s_andn2_b64 vcc, exec, s[4:5]
	v_writelane_b32 v253, s2, 58
	s_cbranch_vccnz .LBB0_565
	v_lshlrev_b32_e32 v0, 4, v8
	v_and_b32_e32 v0, 0x3f0, v0
	s_ashr_i32 s2, s88, 31
	v_or_b32_e32 v0, s88, v0
	s_lshr_b32 s2, s2, 22
	v_add_u32_e32 v1, s2, v0
	v_ashrrev_i32_e32 v9, 10, v1
	v_mul_i32_i24_e32 v1, 0x400, v9
	v_sub_u32_e32 v1, v0, v1
	v_lshrrev_b32_e32 v2, 4, v1
	v_bitop3_b32 v1, v2, v1, 32 bitop3:0x6c
	v_ashrrev_i32_e32 v3, 31, v1
	v_lshrrev_b32_e32 v3, 26, v3
	v_add_u32_e32 v3, v1, v3
	v_lshlrev_b32_e32 v2, 3, v9
	v_ashrrev_i32_e32 v10, 6, v3
	v_and_b32_e32 v3, 0xc0, v3
	v_and_b32_e32 v2, -16, v2
	v_sub_u32_e32 v1, v1, v3
	v_mov_b32_e32 v3, 1
	v_add_u32_e32 v2, v10, v2
	v_ashrrev_i16_sdwa v1, v3, sext(v1) dst_sel:DWORD dst_unused:UNUSED_PAD src0_sel:DWORD src1_sel:BYTE_0
	v_lshlrev_b32_e32 v4, 5, v9
	v_bfe_i32 v11, v1, 0, 16
	v_lshlrev_b32_e32 v1, 1, v2
	v_lshrrev_b32_e32 v5, 2, v2
	v_and_b32_e32 v6, 3, v10
	s_mov_b32 s2, 0x1fffe0
	v_and_b32_e32 v4, 32, v4
	v_and_b32_e32 v1, 24, v1
	v_and_b32_e32 v5, 4, v5
	v_and_or_b32 v6, v2, s2, v6
	v_or3_b32 v1, v6, v5, v1
	v_add_lshl_u32 v4, v4, v11, 1
	v_add_u32_e32 v0, 0x2000, v0
	v_lshl_add_u32 v134, v1, 11, v4
	v_ashrrev_i32_e32 v1, 31, v0
	v_lshrrev_b32_e32 v1, 22, v1
	v_add_u32_e32 v1, v0, v1
	v_ashrrev_i32_e32 v12, 10, v1
	v_mul_i32_i24_e32 v1, 0x400, v12
	v_sub_u32_e32 v0, v0, v1
	v_lshrrev_b32_e32 v1, 4, v0
	v_bitop3_b32 v0, v1, v0, 32 bitop3:0x6c
	v_lshl_add_u32 v132, v2, 11, v4
	v_ashrrev_i32_e32 v2, 31, v0
	v_lshrrev_b32_e32 v2, 26, v2
	v_add_u32_e32 v2, v0, v2
	v_ashrrev_i32_e32 v13, 6, v2
	v_and_b32_e32 v2, 0xffc0, v2
	v_sub_u32_e32 v0, v0, v2
	v_lshrrev_b16_e32 v2, 7, v0
	v_lshlrev_b32_e32 v1, 3, v12
	v_and_b32_e32 v2, 1, v2
	v_and_b32_e32 v1, -16, v1
	v_add_u16_e32 v0, v0, v2
	v_add_u32_e32 v1, v13, v1
	v_ashrrev_i16_sdwa v0, v3, sext(v0) dst_sel:DWORD dst_unused:UNUSED_PAD src0_sel:DWORD src1_sel:BYTE_0
	v_and_b32_e32 v3, 3, v13
	s_ashr_i32 s53, s52, 31
	s_ashr_i32 s47, s46, 31
	v_and_or_b32 v3, v1, s2, v3
	s_lshl_b64 s[2:3], s[52:53], 19
	s_lshl_b64 s[4:5], s[46:47], 19
	s_add_u32 s56, s82, s4
	v_lshlrev_b32_e32 v4, 5, v12
	v_bfe_i32 v14, v0, 0, 16
	v_lshlrev_b32_e32 v0, 1, v1
	v_lshrrev_b32_e32 v2, 2, v1
	s_addc_u32 s57, s83, s5
	s_add_i32 s93, s88, 0
	v_and_b32_e32 v4, 32, v4
	v_and_b32_e32 v0, 24, v0
	v_and_b32_e32 v2, 4, v2
	s_add_i32 m0, s93, 0x10000
	v_or3_b32 v0, v3, v2, v0
	v_add_lshl_u32 v2, v4, v14, 1
	global_load_lds_dwordx4 v134, s[56:57]
	s_add_i32 m0, s93, 0x12000
	v_lshl_add_u32 v138, v0, 11, v2
	s_add_u32 s4, s56, 0x40000
	global_load_lds_dwordx4 v138, s[56:57]
	s_addc_u32 s5, s57, 0
	s_add_i32 m0, s93, 0x14000
	v_lshl_add_u32 v136, v1, 11, v2
	global_load_lds_dwordx4 v134, s[4:5]
	s_add_i32 m0, s93, 0x16000
	s_add_u32 s54, s20, s2
	s_addc_u32 s55, s21, s3
	s_add_i32 s60, s93, 0x2000
	global_load_lds_dwordx4 v138, s[4:5]
	s_mov_b32 m0, s93
	s_add_u32 s2, s54, 0x40000
	global_load_lds_dwordx4 v132, s[54:55]
	s_mov_b32 m0, s60
	s_addc_u32 s3, s55, 0
	s_add_i32 s61, s93, 0x4000
	global_load_lds_dwordx4 v136, s[54:55]
	s_mov_b32 m0, s61
	s_add_i32 s62, s93, 0x6000
	global_load_lds_dwordx4 v132, s[2:3]
	s_mov_b32 m0, s62
	v_mov_b32_e32 v141, 0
	global_load_lds_dwordx4 v136, s[2:3]
	v_mov_b32_e32 v135, v141
	v_mov_b32_e32 v139, v141
	v_mov_b32_e32 v133, v141
	v_mov_b32_e32 v137, v141
	s_cmp_eq_u32 s35, 1
	s_mov_b32 s63, 0
	s_mov_b32 s99, 0
	v_lshl_add_u64 v[6:7], s[56:57], 0, v[134:135]
	v_lshl_add_u64 v[4:5], s[56:57], 0, v[138:139]
	v_lshl_add_u64 v[0:1], s[54:55], 0, v[132:133]
	s_cselect_b64 s[6:7], -1, 0
	s_cmp_lg_u32 s35, 1
	v_lshl_add_u64 v[2:3], s[54:55], 0, v[136:137]
	s_cbranch_scc1 .LBB0_260
	s_barrier

.LBB0_262:
	s_mov_b32 s99, 1
	s_andn2_b64 vcc, exec, s[4:5]
	s_mov_b32 s46, s14
	s_mov_b32 s52, s16
	s_mov_b64 s[56:57], s[70:71]
	s_mov_b64 s[54:55], s[68:69]
	s_cbranch_vccz .LBB0_564

.LBB0_266:
	ds_read_b128 v[128:131], v169
	ds_read_b128 v[158:161], v169 offset:1024
	ds_read_b128 v[162:165], v169 offset:2048
	ds_read_b128 v[176:179], v169 offset:3072
	ds_read_b128 v[180:183], v170
	ds_read_b128 v[184:187], v170 offset:1024
	ds_read_b128 v[188:191], v170 offset:2048
	ds_read_b128 v[192:195], v170 offset:3072
	s_add_u32 s19, s54, 0xfffc0080
	s_addc_u32 s24, s55, -1
	s_cmp_eq_u32 s18, 12
	s_cselect_b32 s59, s2, s24
	s_cselect_b32 s58, s3, s19
	s_cselect_b32 s57, s12, s17
	s_cselect_b32 s56, s13, s15
	v_lshl_add_u64 v[166:167], s[54:55], 0, v[150:151]
	s_add_i32 m0, s93, 0xc000
	ds_read_b128 v[198:201], v171
	ds_read_b128 v[202:205], v171 offset:1024
	ds_read_b128 v[206:209], v171 offset:2048
	ds_read_b128 v[210:213], v171 offset:3072
	ds_read_b128 v[214:217], v171 offset:4096
	ds_read_b128 v[218:221], v171 offset:5120
	ds_read_b128 v[222:225], v171 offset:6144
	ds_read_b128 v[226:229], v171 offset:7168
	global_load_lds_dwordx4 v[166:167], off
	v_lshl_add_u64 v[166:167], s[54:55], 0, v[152:153]
	s_add_i32 m0, s93, 0xe000
	s_nop 0
	global_load_lds_dwordx4 v[166:167], off
	s_cmp_eq_u32 s99, 0
	s_cbranch_scc1 .Lmy_wa1n
	s_waitcnt vmcnt(24)
	s_branch .Lmy_wa1d
.Lmy_wa1n:
	s_waitcnt vmcnt(8)
.Lmy_wa1d:
	s_waitcnt lgkmcnt(0)
	s_barrier
	s_setprio 1
	s_waitcnt lgkmcnt(0)
	v_mfma_f32_16x16x32_bf16 v[124:127], v[128:131], v[198:201], v[124:127]
	v_mfma_f32_16x16x32_bf16 v[120:123], v[162:165], v[198:201], v[120:123]
	v_mfma_f32_16x16x32_bf16 v[108:111], v[128:131], v[206:209], v[108:111]
	v_mfma_f32_16x16x32_bf16 v[104:107], v[162:165], v[206:209], v[104:107]
	v_mfma_f32_16x16x32_bf16 v[92:95], v[128:131], v[214:217], v[92:95]
	v_mfma_f32_16x16x32_bf16 v[88:91], v[162:165], v[214:217], v[88:91]
	v_mfma_f32_16x16x32_bf16 v[76:79], v[128:131], v[222:225], v[76:79]
	v_mfma_f32_16x16x32_bf16 v[72:75], v[162:165], v[222:225], v[72:75]
	v_mfma_f32_16x16x32_bf16 v[124:127], v[158:161], v[202:205], v[124:127]
	v_mfma_f32_16x16x32_bf16 v[120:123], v[176:179], v[202:205], v[120:123]
	v_mfma_f32_16x16x32_bf16 v[108:111], v[158:161], v[210:213], v[108:111]
	v_mfma_f32_16x16x32_bf16 v[104:107], v[176:179], v[210:213], v[104:107]
	v_mfma_f32_16x16x32_bf16 v[92:95], v[158:161], v[218:221], v[92:95]
	v_mfma_f32_16x16x32_bf16 v[88:91], v[176:179], v[218:221], v[88:91]
	v_mfma_f32_16x16x32_bf16 v[76:79], v[158:161], v[226:229], v[76:79]
	v_mfma_f32_16x16x32_bf16 v[72:75], v[176:179], v[226:229], v[72:75]
	s_setprio 0
	s_setprio 1
	v_mfma_f32_16x16x32_bf16 v[116:119], v[180:183], v[198:201], v[116:119]
	v_mfma_f32_16x16x32_bf16 v[112:115], v[188:191], v[198:201], v[112:115]
	v_mfma_f32_16x16x32_bf16 v[100:103], v[180:183], v[206:209], v[100:103]
	v_mfma_f32_16x16x32_bf16 v[96:99], v[188:191], v[206:209], v[96:99]
	v_mfma_f32_16x16x32_bf16 v[84:87], v[180:183], v[214:217], v[84:87]
	v_mfma_f32_16x16x32_bf16 v[80:83], v[188:191], v[214:217], v[80:83]
	v_mfma_f32_16x16x32_bf16 v[68:71], v[180:183], v[222:225], v[68:71]
	v_mfma_f32_16x16x32_bf16 v[64:67], v[188:191], v[222:225], v[64:67]
	v_mfma_f32_16x16x32_bf16 v[116:119], v[184:187], v[202:205], v[116:119]
	v_mfma_f32_16x16x32_bf16 v[112:115], v[192:195], v[202:205], v[112:115]
	v_mfma_f32_16x16x32_bf16 v[100:103], v[184:187], v[210:213], v[100:103]
	v_mfma_f32_16x16x32_bf16 v[96:99], v[192:195], v[210:213], v[96:99]
	v_mfma_f32_16x16x32_bf16 v[84:87], v[184:187], v[218:221], v[84:87]
	v_mfma_f32_16x16x32_bf16 v[80:83], v[192:195], v[218:221], v[80:83]
	v_mfma_f32_16x16x32_bf16 v[68:71], v[184:187], v[226:229], v[68:71]
	v_mfma_f32_16x16x32_bf16 v[64:67], v[192:195], v[226:229], v[64:67]
	s_setprio 0
	s_barrier
	s_add_i32 s19, s79, s88
	v_lshl_add_u64 v[166:167], s[56:57], 0, v[134:135]
	s_mov_b32 m0, s19
	ds_read_b128 v[198:201], v171 offset:16384
	ds_read_b128 v[202:205], v171 offset:17408
	ds_read_b128 v[206:209], v171 offset:18432
	ds_read_b128 v[210:213], v171 offset:19456
	ds_read_b128 v[214:217], v171 offset:20480
	ds_read_b128 v[218:221], v171 offset:21504
	ds_read_b128 v[222:225], v171 offset:22528
	ds_read_b128 v[226:229], v171 offset:23552
	global_load_lds_dwordx4 v[166:167], off
	s_add_i32 m0, s19, 0x2000
	s_add_u32 s24, s56, 0x40000
	v_lshl_add_u64 v[230:231], s[56:57], 0, v[138:139]
	s_addc_u32 s25, s57, 0
	s_add_i32 s19, s80, s88
	global_load_lds_dwordx4 v[230:231], off
	v_lshl_add_u64 v[232:233], s[24:25], 0, v[134:135]
	s_mov_b32 m0, s19
	v_lshl_add_u64 v[236:237], s[58:59], 0, v[136:137]
	global_load_lds_dwordx4 v[232:233], off
	v_lshl_add_u64 v[232:233], s[24:25], 0, v[138:139]
	s_add_i32 m0, s19, 0x2000
	s_nop 0
	global_load_lds_dwordx4 v[232:233], off
	v_lshl_add_u64 v[232:233], s[58:59], 0, v[132:133]
	s_mov_b32 m0, s93
	s_nop 0
	global_load_lds_dwordx4 v[232:233], off
	s_mov_b32 m0, s60
	s_nop 0
	global_load_lds_dwordx4 v[236:237], off
	s_cmp_eq_u32 s99, 0
	s_cbranch_scc1 .Lmy_wa2n
	s_waitcnt vmcnt(24)
	s_mov_b32 s99, 0
	s_branch .Lmy_wa2d

.Lmy_wa2d:
	s_waitcnt lgkmcnt(0)
	s_barrier
	s_setprio 1
	s_waitcnt lgkmcnt(0)
	v_mfma_f32_16x16x32_bf16 v[60:63], v[128:131], v[198:201], v[60:63]
	v_mfma_f32_16x16x32_bf16 v[56:59], v[162:165], v[198:201], v[56:59]
	v_mfma_f32_16x16x32_bf16 v[44:47], v[128:131], v[206:209], v[44:47]
	v_mfma_f32_16x16x32_bf16 v[40:43], v[162:165], v[206:209], v[40:43]
	v_mfma_f32_16x16x32_bf16 v[28:31], v[128:131], v[214:217], v[28:31]
	v_mfma_f32_16x16x32_bf16 v[24:27], v[162:165], v[214:217], v[24:27]
	v_mfma_f32_16x16x32_bf16 v[12:15], v[128:131], v[222:225], v[12:15]
	v_mfma_f32_16x16x32_bf16 v[8:11], v[162:165], v[222:225], v[8:11]
	v_mfma_f32_16x16x32_bf16 v[60:63], v[158:161], v[202:205], v[60:63]
	v_mfma_f32_16x16x32_bf16 v[56:59], v[176:179], v[202:205], v[56:59]
	v_mfma_f32_16x16x32_bf16 v[44:47], v[158:161], v[210:213], v[44:47]
	v_mfma_f32_16x16x32_bf16 v[40:43], v[176:179], v[210:213], v[40:43]
	v_mfma_f32_16x16x32_bf16 v[28:31], v[158:161], v[218:221], v[28:31]
	v_mfma_f32_16x16x32_bf16 v[24:27], v[176:179], v[218:221], v[24:27]
	v_mfma_f32_16x16x32_bf16 v[12:15], v[158:161], v[226:229], v[12:15]
	v_mfma_f32_16x16x32_bf16 v[8:11], v[176:179], v[226:229], v[8:11]
	s_setprio 0
	s_setprio 1
	v_mfma_f32_16x16x32_bf16 v[52:55], v[180:183], v[198:201], v[52:55]
	v_mfma_f32_16x16x32_bf16 v[48:51], v[188:191], v[198:201], v[48:51]
	v_mfma_f32_16x16x32_bf16 v[36:39], v[180:183], v[206:209], v[36:39]
	v_mfma_f32_16x16x32_bf16 v[32:35], v[188:191], v[206:209], v[32:35]
	v_mfma_f32_16x16x32_bf16 v[20:23], v[180:183], v[214:217], v[20:23]
	v_mfma_f32_16x16x32_bf16 v[16:19], v[188:191], v[214:217], v[16:19]
	v_mfma_f32_16x16x32_bf16 v[4:7], v[180:183], v[222:225], v[4:7]
	v_mfma_f32_16x16x32_bf16 v[0:3], v[188:191], v[222:225], v[0:3]
	v_mfma_f32_16x16x32_bf16 v[52:55], v[184:187], v[202:205], v[52:55]
	v_mfma_f32_16x16x32_bf16 v[48:51], v[192:195], v[202:205], v[48:51]
	v_mfma_f32_16x16x32_bf16 v[36:39], v[184:187], v[210:213], v[36:39]
	v_mfma_f32_16x16x32_bf16 v[32:35], v[192:195], v[210:213], v[32:35]
	v_mfma_f32_16x16x32_bf16 v[20:23], v[184:187], v[218:221], v[20:23]
	v_mfma_f32_16x16x32_bf16 v[16:19], v[192:195], v[218:221], v[16:19]
	v_mfma_f32_16x16x32_bf16 v[4:7], v[184:187], v[226:229], v[4:7]
	v_mfma_f32_16x16x32_bf16 v[0:3], v[192:195], v[226:229], v[0:3]
	s_setprio 0
	s_barrier
	s_add_i32 s19, 0, 0x18000
	v_add_u32_e32 v140, s19, v145
	s_add_i32 s26, 0, 0x1c000
	ds_read_b128 v[128:131], v140
	ds_read_b128 v[158:161], v140 offset:1024
	ds_read_b128 v[162:165], v140 offset:2048
	ds_read_b128 v[176:179], v140 offset:3072
	v_add_u32_e32 v140, s26, v145
	ds_read_b128 v[180:183], v140
	ds_read_b128 v[184:187], v140 offset:1024
	ds_read_b128 v[188:191], v140 offset:2048
	ds_read_b128 v[192:195], v140 offset:3072
	s_add_u32 s24, s58, 0x40000
	s_addc_u32 s25, s59, 0
	s_mov_b32 m0, s61
	v_lshl_add_u64 v[238:239], s[24:25], 0, v[132:133]
	ds_read_b128 v[198:201], v171 offset:32768
	ds_read_b128 v[202:205], v171 offset:33792
	ds_read_b128 v[206:209], v171 offset:34816
	ds_read_b128 v[210:213], v171 offset:35840
	ds_read_b128 v[214:217], v171 offset:36864
	ds_read_b128 v[218:221], v171 offset:37888
	ds_read_b128 v[222:225], v171 offset:38912
	ds_read_b128 v[226:229], v171 offset:39936
	global_load_lds_dwordx4 v[238:239], off
	v_lshl_add_u64 v[238:239], s[24:25], 0, v[136:137]
	s_mov_b32 m0, s62
	s_nop 0
	global_load_lds_dwordx4 v[238:239], off
	s_waitcnt vmcnt(8)
	s_waitcnt lgkmcnt(0)
	s_barrier
	s_setprio 1
	s_waitcnt lgkmcnt(0)
	v_mfma_f32_16x16x32_bf16 v[124:127], v[128:131], v[198:201], v[124:127]
	v_mfma_f32_16x16x32_bf16 v[120:123], v[162:165], v[198:201], v[120:123]
	v_mfma_f32_16x16x32_bf16 v[108:111], v[128:131], v[206:209], v[108:111]
	v_mfma_f32_16x16x32_bf16 v[104:107], v[162:165], v[206:209], v[104:107]
	v_mfma_f32_16x16x32_bf16 v[92:95], v[128:131], v[214:217], v[92:95]
	v_mfma_f32_16x16x32_bf16 v[88:91], v[162:165], v[214:217], v[88:91]
	v_mfma_f32_16x16x32_bf16 v[76:79], v[128:131], v[222:225], v[76:79]
	v_mfma_f32_16x16x32_bf16 v[72:75], v[162:165], v[222:225], v[72:75]
	v_mfma_f32_16x16x32_bf16 v[124:127], v[158:161], v[202:205], v[124:127]
	v_mfma_f32_16x16x32_bf16 v[120:123], v[176:179], v[202:205], v[120:123]
	v_mfma_f32_16x16x32_bf16 v[108:111], v[158:161], v[210:213], v[108:111]
	v_mfma_f32_16x16x32_bf16 v[104:107], v[176:179], v[210:213], v[104:107]
	v_mfma_f32_16x16x32_bf16 v[92:95], v[158:161], v[218:221], v[92:95]
	v_mfma_f32_16x16x32_bf16 v[88:91], v[176:179], v[218:221], v[88:91]
	v_mfma_f32_16x16x32_bf16 v[76:79], v[158:161], v[226:229], v[76:79]
	v_mfma_f32_16x16x32_bf16 v[72:75], v[176:179], v[226:229], v[72:75]
	s_setprio 0
	s_setprio 1
	v_mfma_f32_16x16x32_bf16 v[116:119], v[180:183], v[198:201], v[116:119]
	v_mfma_f32_16x16x32_bf16 v[112:115], v[188:191], v[198:201], v[112:115]
	v_mfma_f32_16x16x32_bf16 v[100:103], v[180:183], v[206:209], v[100:103]
	v_mfma_f32_16x16x32_bf16 v[96:99], v[188:191], v[206:209], v[96:99]
	v_mfma_f32_16x16x32_bf16 v[84:87], v[180:183], v[214:217], v[84:87]
	v_mfma_f32_16x16x32_bf16 v[80:83], v[188:191], v[214:217], v[80:83]
	v_mfma_f32_16x16x32_bf16 v[68:71], v[180:183], v[222:225], v[68:71]
	v_mfma_f32_16x16x32_bf16 v[64:67], v[188:191], v[222:225], v[64:67]
	v_mfma_f32_16x16x32_bf16 v[116:119], v[184:187], v[202:205], v[116:119]
	v_mfma_f32_16x16x32_bf16 v[112:115], v[192:195], v[202:205], v[112:115]
	v_mfma_f32_16x16x32_bf16 v[100:103], v[184:187], v[210:213], v[100:103]
	v_mfma_f32_16x16x32_bf16 v[96:99], v[192:195], v[210:213], v[96:99]
	v_mfma_f32_16x16x32_bf16 v[84:87], v[184:187], v[218:221], v[84:87]
	v_mfma_f32_16x16x32_bf16 v[80:83], v[192:195], v[218:221], v[80:83]
	v_mfma_f32_16x16x32_bf16 v[68:71], v[184:187], v[226:229], v[68:71]
	v_mfma_f32_16x16x32_bf16 v[64:67], v[192:195], v[226:229], v[64:67]
	s_setprio 0
	s_barrier
	s_add_i32 s19, s19, s88
	v_lshl_add_u64 v[166:167], v[166:167], 0, s[8:9]
	s_mov_b32 m0, s19
	ds_read_b128 v[198:201], v171 offset:49152
	ds_read_b128 v[202:205], v171 offset:50176
	ds_read_b128 v[206:209], v171 offset:51200
	ds_read_b128 v[210:213], v171 offset:52224
	ds_read_b128 v[214:217], v171 offset:53248
	ds_read_b128 v[218:221], v171 offset:54272
	ds_read_b128 v[222:225], v171 offset:55296
	ds_read_b128 v[226:229], v171 offset:56320
	global_load_lds_dwordx4 v[166:167], off
	s_add_i32 m0, s19, 0x2000
	s_add_u32 s24, s56, 0x40080
	v_lshl_add_u64 v[166:167], v[230:231], 0, s[8:9]
	s_addc_u32 s25, s57, 0
	s_add_i32 s19, s26, s88
	global_load_lds_dwordx4 v[166:167], off
	v_lshl_add_u64 v[166:167], s[24:25], 0, v[134:135]
	s_mov_b32 m0, s19
	s_nop 0
	global_load_lds_dwordx4 v[166:167], off
	v_lshl_add_u64 v[166:167], s[24:25], 0, v[138:139]
	s_add_i32 m0, s19, 0x2000
	s_nop 0
	global_load_lds_dwordx4 v[166:167], off
	v_lshl_add_u64 v[166:167], v[232:233], 0, s[8:9]
	s_mov_b32 m0, s66
	s_nop 0
	global_load_lds_dwordx4 v[166:167], off
	v_lshl_add_u64 v[166:167], v[236:237], 0, s[8:9]
	s_mov_b32 m0, s67
	s_nop 0
	global_load_lds_dwordx4 v[166:167], off
	s_waitcnt vmcnt(8)
	s_waitcnt lgkmcnt(0)
	s_barrier
	s_setprio 1
	s_waitcnt lgkmcnt(0)
	v_mfma_f32_16x16x32_bf16 v[60:63], v[128:131], v[198:201], v[60:63]
	v_mfma_f32_16x16x32_bf16 v[56:59], v[162:165], v[198:201], v[56:59]
	v_mfma_f32_16x16x32_bf16 v[44:47], v[128:131], v[206:209], v[44:47]
	v_mfma_f32_16x16x32_bf16 v[40:43], v[162:165], v[206:209], v[40:43]
	v_mfma_f32_16x16x32_bf16 v[28:31], v[128:131], v[214:217], v[28:31]
	v_mfma_f32_16x16x32_bf16 v[24:27], v[162:165], v[214:217], v[24:27]
	v_mfma_f32_16x16x32_bf16 v[12:15], v[128:131], v[222:225], v[12:15]
	v_mfma_f32_16x16x32_bf16 v[8:11], v[162:165], v[222:225], v[8:11]
	v_mfma_f32_16x16x32_bf16 v[60:63], v[158:161], v[202:205], v[60:63]
	v_mfma_f32_16x16x32_bf16 v[56:59], v[176:179], v[202:205], v[56:59]
	v_mfma_f32_16x16x32_bf16 v[44:47], v[158:161], v[210:213], v[44:47]
	v_mfma_f32_16x16x32_bf16 v[40:43], v[176:179], v[210:213], v[40:43]
	v_mfma_f32_16x16x32_bf16 v[28:31], v[158:161], v[218:221], v[28:31]
	v_mfma_f32_16x16x32_bf16 v[24:27], v[176:179], v[218:221], v[24:27]
	v_mfma_f32_16x16x32_bf16 v[12:15], v[158:161], v[226:229], v[12:15]
	v_mfma_f32_16x16x32_bf16 v[8:11], v[176:179], v[226:229], v[8:11]
	s_setprio 0
	s_setprio 1
	v_mfma_f32_16x16x32_bf16 v[52:55], v[180:183], v[198:201], v[52:55]
	v_mfma_f32_16x16x32_bf16 v[48:51], v[188:191], v[198:201], v[48:51]
	v_mfma_f32_16x16x32_bf16 v[36:39], v[180:183], v[206:209], v[36:39]
	v_mfma_f32_16x16x32_bf16 v[32:35], v[188:191], v[206:209], v[32:35]
	v_mfma_f32_16x16x32_bf16 v[20:23], v[180:183], v[214:217], v[20:23]
	v_mfma_f32_16x16x32_bf16 v[16:19], v[188:191], v[214:217], v[16:19]
	v_mfma_f32_16x16x32_bf16 v[4:7], v[180:183], v[222:225], v[4:7]
	v_mfma_f32_16x16x32_bf16 v[0:3], v[188:191], v[222:225], v[0:3]
	v_mfma_f32_16x16x32_bf16 v[52:55], v[184:187], v[202:205], v[52:55]
	v_mfma_f32_16x16x32_bf16 v[48:51], v[192:195], v[202:205], v[48:51]
	v_mfma_f32_16x16x32_bf16 v[36:39], v[184:187], v[210:213], v[36:39]
	v_mfma_f32_16x16x32_bf16 v[32:35], v[192:195], v[210:213], v[32:35]
	v_mfma_f32_16x16x32_bf16 v[20:23], v[184:187], v[218:221], v[20:23]
	v_mfma_f32_16x16x32_bf16 v[16:19], v[192:195], v[218:221], v[16:19]
	v_mfma_f32_16x16x32_bf16 v[4:7], v[184:187], v[226:229], v[4:7]
	v_mfma_f32_16x16x32_bf16 v[0:3], v[192:195], v[226:229], v[0:3]
	s_setprio 0
	s_barrier
	s_add_i32 s18, s18, 2
	s_add_u32 s54, s54, 0x100
	s_addc_u32 s55, s55, 0
	s_add_u32 s15, s15, 0x100
	s_addc_u32 s17, s17, 0
	s_cmp_gt_u32 s18, 13
	s_cbranch_scc0 .LBB0_266
	s_and_b64 vcc, exec, s[10:11]
	s_cbranch_vccz .LBB0_269
	s_barrier
.LBB0_269:
	s_lshl_b32 s2, s52, 8
	s_ashr_i32 s17, s46, 2
	s_and_b32 s15, s46, 3
	s_add_i32 s2, s2, s34
	v_or_b32_e32 v158, s2, v143
	s_mov_b32 s50, s52
	s_cmp_lt_i32 s17, 2
	s_mov_b64 s[52:53], -1
	s_cbranch_scc1 .LBB0_272
	v_and_b32_e32 v185, 63, v234
	v_lshrrev_b32_e32 v186, 6, v234
	v_and_b32_e32 v187, 15, v185
	v_lshrrev_b32_e32 v188, 4, v185
	v_lshrrev_b32_e32 v189, 2, v186
	v_and_b32_e32 v190, 3, v186
	v_lshl_add_u32 v191, v189, 6, v187
	s_cmp_eq_u32 s17, 4
	s_cbranch_scc1 .Lmy_epi_u
	v_lshlrev_b32_e32 v175, 11, v191
	v_lshlrev_b32_e32 v192, 5, v190
	v_lshl_add_u32 v192, v188, 3, v192
	v_lshl_add_u32 v175, v192, 1, v175
	s_mov_b32 s40, 0xa800000
	s_mov_b32 s41, 0xe800000
	s_mov_b32 s42, 0x12800000
	s_cmp_eq_u32 s17, 3
	s_cselect_b32 s40, s41, s40
	s_cmp_eq_u32 s17, 5
	s_cselect_b32 s40, s42, s40
	s_lshl_b32 s41, s50, 19
	s_lshl_b32 s42, s15, 9
	s_add_u32 s41, s41, s42
	s_add_u32 s40, s40, s41
	s_add_u32 s40, s22, s40
	s_addc_u32 s41, s23, 0
	s_cmp_eq_u32 s17, 2
	s_cbranch_scc0 .Lmy_epi_silu
	s_mov_b64 s[42:43], s[40:41]
	v_cvt_pk_bf16_f32 v128, v124, v125
	v_cvt_pk_bf16_f32 v129, v126, v127
	v_cvt_pk_bf16_f32 v130, v120, v121
	v_cvt_pk_bf16_f32 v131, v122, v123
	global_store_dwordx4 v175, v[128:131], s[42:43]
	v_cvt_pk_bf16_f32 v160, v116, v117
	v_cvt_pk_bf16_f32 v161, v118, v119
	v_cvt_pk_bf16_f32 v162, v112, v113
	v_cvt_pk_bf16_f32 v163, v114, v115
	global_store_dwordx4 v175, v[160:163], s[42:43] offset:256
	s_add_u32 s42, s42, 0x8000
	s_addc_u32 s43, s43, 0
	v_cvt_pk_bf16_f32 v128, v108, v109
	v_cvt_pk_bf16_f32 v129, v110, v111
	v_cvt_pk_bf16_f32 v130, v104, v105
	v_cvt_pk_bf16_f32 v131, v106, v107
	global_store_dwordx4 v175, v[128:131], s[42:43]
	v_cvt_pk_bf16_f32 v160, v100, v101
	v_cvt_pk_bf16_f32 v161, v102, v103
	v_cvt_pk_bf16_f32 v162, v96, v97
	v_cvt_pk_bf16_f32 v163, v98, v99
	global_store_dwordx4 v175, v[160:163], s[42:43] offset:256
	s_add_u32 s42, s42, 0x8000
	s_addc_u32 s43, s43, 0
	v_cvt_pk_bf16_f32 v128, v92, v93
	v_cvt_pk_bf16_f32 v129, v94, v95
	v_cvt_pk_bf16_f32 v130, v88, v89
	v_cvt_pk_bf16_f32 v131, v90, v91
	global_store_dwordx4 v175, v[128:131], s[42:43]
	v_cvt_pk_bf16_f32 v160, v84, v85
	v_cvt_pk_bf16_f32 v161, v86, v87
	v_cvt_pk_bf16_f32 v162, v80, v81
	v_cvt_pk_bf16_f32 v163, v82, v83
	global_store_dwordx4 v175, v[160:163], s[42:43] offset:256
	s_add_u32 s42, s42, 0x8000
	s_addc_u32 s43, s43, 0
	v_cvt_pk_bf16_f32 v128, v76, v77
	v_cvt_pk_bf16_f32 v129, v78, v79
	v_cvt_pk_bf16_f32 v130, v72, v73
	v_cvt_pk_bf16_f32 v131, v74, v75
	global_store_dwordx4 v175, v[128:131], s[42:43]
	v_cvt_pk_bf16_f32 v160, v68, v69
	v_cvt_pk_bf16_f32 v161, v70, v71
	v_cvt_pk_bf16_f32 v162, v64, v65
	v_cvt_pk_bf16_f32 v163, v66, v67
	global_store_dwordx4 v175, v[160:163], s[42:43] offset:256
	s_add_u32 s42, s42, 0x28000
	s_addc_u32 s43, s43, 0
	v_cvt_pk_bf16_f32 v128, v60, v61
	v_cvt_pk_bf16_f32 v129, v62, v63
	v_cvt_pk_bf16_f32 v130, v56, v57
	v_cvt_pk_bf16_f32 v131, v58, v59
	global_store_dwordx4 v175, v[128:131], s[42:43]
	v_cvt_pk_bf16_f32 v160, v52, v53
	v_cvt_pk_bf16_f32 v161, v54, v55
	v_cvt_pk_bf16_f32 v162, v48, v49
	v_cvt_pk_bf16_f32 v163, v50, v51
	global_store_dwordx4 v175, v[160:163], s[42:43] offset:256
	s_add_u32 s42, s42, 0x8000
	s_addc_u32 s43, s43, 0
	v_cvt_pk_bf16_f32 v128, v44, v45
	v_cvt_pk_bf16_f32 v129, v46, v47
	v_cvt_pk_bf16_f32 v130, v40, v41
	v_cvt_pk_bf16_f32 v131, v42, v43
	global_store_dwordx4 v175, v[128:131], s[42:43]
	v_cvt_pk_bf16_f32 v160, v36, v37
	v_cvt_pk_bf16_f32 v161, v38, v39
	v_cvt_pk_bf16_f32 v162, v32, v33
	v_cvt_pk_bf16_f32 v163, v34, v35
	global_store_dwordx4 v175, v[160:163], s[42:43] offset:256
	s_add_u32 s42, s42, 0x8000
	s_addc_u32 s43, s43, 0
	v_cvt_pk_bf16_f32 v128, v28, v29
	v_cvt_pk_bf16_f32 v129, v30, v31
	v_cvt_pk_bf16_f32 v130, v24, v25
	v_cvt_pk_bf16_f32 v131, v26, v27
	global_store_dwordx4 v175, v[128:131], s[42:43]
	v_cvt_pk_bf16_f32 v160, v20, v21
	v_cvt_pk_bf16_f32 v161, v22, v23
	v_cvt_pk_bf16_f32 v162, v16, v17
	v_cvt_pk_bf16_f32 v163, v18, v19
	global_store_dwordx4 v175, v[160:163], s[42:43] offset:256
	s_add_u32 s42, s42, 0x8000
	s_addc_u32 s43, s43, 0
	v_cvt_pk_bf16_f32 v128, v12, v13
	v_cvt_pk_bf16_f32 v129, v14, v15
	v_cvt_pk_bf16_f32 v130, v8, v9
	v_cvt_pk_bf16_f32 v131, v10, v11
	global_store_dwordx4 v175, v[128:131], s[42:43]
	v_cvt_pk_bf16_f32 v160, v4, v5
	v_cvt_pk_bf16_f32 v161, v6, v7
	v_cvt_pk_bf16_f32 v162, v0, v1
	v_cvt_pk_bf16_f32 v163, v2, v3
	global_store_dwordx4 v175, v[160:163], s[42:43] offset:256
	s_branch .LBB0_561
.Lmy_epi_silu:
	s_mov_b64 s[42:43], s[40:41]
	v_mul_f32_e32 v177, 0xbfb8aa3b, v120
	v_mul_f32_e32 v178, 0xbfb8aa3b, v121
	v_mul_f32_e32 v179, 0xbfb8aa3b, v122
	v_mul_f32_e32 v180, 0xbfb8aa3b, v123
	v_mul_f32_e32 v181, 0xbfb8aa3b, v124
	v_mul_f32_e32 v182, 0xbfb8aa3b, v125
	v_mul_f32_e32 v183, 0xbfb8aa3b, v126
	v_mul_f32_e32 v184, 0xbfb8aa3b, v127
	v_exp_f32_e32 v177, v177
	v_exp_f32_e32 v178, v178
	v_exp_f32_e32 v179, v179
	v_exp_f32_e32 v180, v180
	v_exp_f32_e32 v181, v181
	v_exp_f32_e32 v182, v182
	v_exp_f32_e32 v183, v183
	v_exp_f32_e32 v184, v184
	v_add_f32_e32 v177, 1.0, v177
	v_add_f32_e32 v178, 1.0, v178
	v_add_f32_e32 v179, 1.0, v179
	v_add_f32_e32 v180, 1.0, v180
	v_add_f32_e32 v181, 1.0, v181
	v_add_f32_e32 v182, 1.0, v182
	v_add_f32_e32 v183, 1.0, v183
	v_add_f32_e32 v184, 1.0, v184
	v_rcp_f32_e32 v177, v177
	v_rcp_f32_e32 v178, v178
	v_rcp_f32_e32 v179, v179
	v_rcp_f32_e32 v180, v180
	v_rcp_f32_e32 v181, v181
	v_rcp_f32_e32 v182, v182
	v_rcp_f32_e32 v183, v183
	v_rcp_f32_e32 v184, v184
	v_mul_f32_e32 v177, v120, v177
	v_mul_f32_e32 v178, v121, v178
	v_mul_f32_e32 v179, v122, v179
	v_mul_f32_e32 v180, v123, v180
	v_mul_f32_e32 v181, v124, v181
	v_mul_f32_e32 v182, v125, v182
	v_mul_f32_e32 v183, v126, v183
	v_mul_f32_e32 v184, v127, v184
	v_cvt_pk_bf16_f32 v128, v181, v182
	v_cvt_pk_bf16_f32 v129, v183, v184
	v_cvt_pk_bf16_f32 v130, v177, v178
	v_cvt_pk_bf16_f32 v131, v179, v180
	global_store_dwordx4 v175, v[128:131], s[42:43] nt
	v_mul_f32_e32 v197, 0xbfb8aa3b, v112
	v_mul_f32_e32 v198, 0xbfb8aa3b, v113
	v_mul_f32_e32 v199, 0xbfb8aa3b, v114
	v_mul_f32_e32 v200, 0xbfb8aa3b, v115
	v_mul_f32_e32 v201, 0xbfb8aa3b, v116
	v_mul_f32_e32 v202, 0xbfb8aa3b, v117
	v_mul_f32_e32 v203, 0xbfb8aa3b, v118
	v_mul_f32_e32 v204, 0xbfb8aa3b, v119
	v_exp_f32_e32 v197, v197
	v_exp_f32_e32 v198, v198
	v_exp_f32_e32 v199, v199
	v_exp_f32_e32 v200, v200
	v_exp_f32_e32 v201, v201
	v_exp_f32_e32 v202, v202
	v_exp_f32_e32 v203, v203
	v_exp_f32_e32 v204, v204
	v_add_f32_e32 v197, 1.0, v197
	v_add_f32_e32 v198, 1.0, v198
	v_add_f32_e32 v199, 1.0, v199
	v_add_f32_e32 v200, 1.0, v200
	v_add_f32_e32 v201, 1.0, v201
	v_add_f32_e32 v202, 1.0, v202
	v_add_f32_e32 v203, 1.0, v203
	v_add_f32_e32 v204, 1.0, v204
	v_rcp_f32_e32 v197, v197
	v_rcp_f32_e32 v198, v198
	v_rcp_f32_e32 v199, v199
	v_rcp_f32_e32 v200, v200
	v_rcp_f32_e32 v201, v201
	v_rcp_f32_e32 v202, v202
	v_rcp_f32_e32 v203, v203
	v_rcp_f32_e32 v204, v204
	v_mul_f32_e32 v197, v112, v197
	v_mul_f32_e32 v198, v113, v198
	v_mul_f32_e32 v199, v114, v199
	v_mul_f32_e32 v200, v115, v200
	v_mul_f32_e32 v201, v116, v201
	v_mul_f32_e32 v202, v117, v202
	v_mul_f32_e32 v203, v118, v203
	v_mul_f32_e32 v204, v119, v204
	v_cvt_pk_bf16_f32 v160, v201, v202
	v_cvt_pk_bf16_f32 v161, v203, v204
	v_cvt_pk_bf16_f32 v162, v197, v198
	v_cvt_pk_bf16_f32 v163, v199, v200
	global_store_dwordx4 v175, v[160:163], s[42:43] offset:256 nt
	s_add_u32 s42, s42, 0x8000
	s_addc_u32 s43, s43, 0
	v_mul_f32_e32 v177, 0xbfb8aa3b, v104
	v_mul_f32_e32 v178, 0xbfb8aa3b, v105
	v_mul_f32_e32 v179, 0xbfb8aa3b, v106
	v_mul_f32_e32 v180, 0xbfb8aa3b, v107
	v_mul_f32_e32 v181, 0xbfb8aa3b, v108
	v_mul_f32_e32 v182, 0xbfb8aa3b, v109
	v_mul_f32_e32 v183, 0xbfb8aa3b, v110
	v_mul_f32_e32 v184, 0xbfb8aa3b, v111
	v_exp_f32_e32 v177, v177
	v_exp_f32_e32 v178, v178
	v_exp_f32_e32 v179, v179
	v_exp_f32_e32 v180, v180
	v_exp_f32_e32 v181, v181
	v_exp_f32_e32 v182, v182
	v_exp_f32_e32 v183, v183
	v_exp_f32_e32 v184, v184
	v_add_f32_e32 v177, 1.0, v177
	v_add_f32_e32 v178, 1.0, v178
	v_add_f32_e32 v179, 1.0, v179
	v_add_f32_e32 v180, 1.0, v180
	v_add_f32_e32 v181, 1.0, v181
	v_add_f32_e32 v182, 1.0, v182
	v_add_f32_e32 v183, 1.0, v183
	v_add_f32_e32 v184, 1.0, v184
	v_rcp_f32_e32 v177, v177
	v_rcp_f32_e32 v178, v178
	v_rcp_f32_e32 v179, v179
	v_rcp_f32_e32 v180, v180
	v_rcp_f32_e32 v181, v181
	v_rcp_f32_e32 v182, v182
	v_rcp_f32_e32 v183, v183
	v_rcp_f32_e32 v184, v184
	v_mul_f32_e32 v177, v104, v177
	v_mul_f32_e32 v178, v105, v178
	v_mul_f32_e32 v179, v106, v179
	v_mul_f32_e32 v180, v107, v180
	v_mul_f32_e32 v181, v108, v181
	v_mul_f32_e32 v182, v109, v182
	v_mul_f32_e32 v183, v110, v183
	v_mul_f32_e32 v184, v111, v184
	v_cvt_pk_bf16_f32 v128, v181, v182
	v_cvt_pk_bf16_f32 v129, v183, v184
	v_cvt_pk_bf16_f32 v130, v177, v178
	v_cvt_pk_bf16_f32 v131, v179, v180
	global_store_dwordx4 v175, v[128:131], s[42:43] nt
	v_mul_f32_e32 v197, 0xbfb8aa3b, v96
	v_mul_f32_e32 v198, 0xbfb8aa3b, v97
	v_mul_f32_e32 v199, 0xbfb8aa3b, v98
	v_mul_f32_e32 v200, 0xbfb8aa3b, v99
	v_mul_f32_e32 v201, 0xbfb8aa3b, v100
	v_mul_f32_e32 v202, 0xbfb8aa3b, v101
	v_mul_f32_e32 v203, 0xbfb8aa3b, v102
	v_mul_f32_e32 v204, 0xbfb8aa3b, v103
	v_exp_f32_e32 v197, v197
	v_exp_f32_e32 v198, v198
	v_exp_f32_e32 v199, v199
	v_exp_f32_e32 v200, v200
	v_exp_f32_e32 v201, v201
	v_exp_f32_e32 v202, v202
	v_exp_f32_e32 v203, v203
	v_exp_f32_e32 v204, v204
	v_add_f32_e32 v197, 1.0, v197
	v_add_f32_e32 v198, 1.0, v198
	v_add_f32_e32 v199, 1.0, v199
	v_add_f32_e32 v200, 1.0, v200
	v_add_f32_e32 v201, 1.0, v201
	v_add_f32_e32 v202, 1.0, v202
	v_add_f32_e32 v203, 1.0, v203
	v_add_f32_e32 v204, 1.0, v204
	v_rcp_f32_e32 v197, v197
	v_rcp_f32_e32 v198, v198
	v_rcp_f32_e32 v199, v199
	v_rcp_f32_e32 v200, v200
	v_rcp_f32_e32 v201, v201
	v_rcp_f32_e32 v202, v202
	v_rcp_f32_e32 v203, v203
	v_rcp_f32_e32 v204, v204
	v_mul_f32_e32 v197, v96, v197
	v_mul_f32_e32 v198, v97, v198
	v_mul_f32_e32 v199, v98, v199
	v_mul_f32_e32 v200, v99, v200
	v_mul_f32_e32 v201, v100, v201
	v_mul_f32_e32 v202, v101, v202
	v_mul_f32_e32 v203, v102, v203
	v_mul_f32_e32 v204, v103, v204
	v_cvt_pk_bf16_f32 v160, v201, v202
	v_cvt_pk_bf16_f32 v161, v203, v204
	v_cvt_pk_bf16_f32 v162, v197, v198
	v_cvt_pk_bf16_f32 v163, v199, v200
	global_store_dwordx4 v175, v[160:163], s[42:43] offset:256 nt
	s_add_u32 s42, s42, 0x8000
	s_addc_u32 s43, s43, 0
	v_mul_f32_e32 v177, 0xbfb8aa3b, v88
	v_mul_f32_e32 v178, 0xbfb8aa3b, v89
	v_mul_f32_e32 v179, 0xbfb8aa3b, v90
	v_mul_f32_e32 v180, 0xbfb8aa3b, v91
	v_mul_f32_e32 v181, 0xbfb8aa3b, v92
	v_mul_f32_e32 v182, 0xbfb8aa3b, v93
	v_mul_f32_e32 v183, 0xbfb8aa3b, v94
	v_mul_f32_e32 v184, 0xbfb8aa3b, v95
	v_exp_f32_e32 v177, v177
	v_exp_f32_e32 v178, v178
	v_exp_f32_e32 v179, v179
	v_exp_f32_e32 v180, v180
	v_exp_f32_e32 v181, v181
	v_exp_f32_e32 v182, v182
	v_exp_f32_e32 v183, v183
	v_exp_f32_e32 v184, v184
	v_add_f32_e32 v177, 1.0, v177
	v_add_f32_e32 v178, 1.0, v178
	v_add_f32_e32 v179, 1.0, v179
	v_add_f32_e32 v180, 1.0, v180
	v_add_f32_e32 v181, 1.0, v181
	v_add_f32_e32 v182, 1.0, v182
	v_add_f32_e32 v183, 1.0, v183
	v_add_f32_e32 v184, 1.0, v184
	v_rcp_f32_e32 v177, v177
	v_rcp_f32_e32 v178, v178
	v_rcp_f32_e32 v179, v179
	v_rcp_f32_e32 v180, v180
	v_rcp_f32_e32 v181, v181
	v_rcp_f32_e32 v182, v182
	v_rcp_f32_e32 v183, v183
	v_rcp_f32_e32 v184, v184
	v_mul_f32_e32 v177, v88, v177
	v_mul_f32_e32 v178, v89, v178
	v_mul_f32_e32 v179, v90, v179
	v_mul_f32_e32 v180, v91, v180
	v_mul_f32_e32 v181, v92, v181
	v_mul_f32_e32 v182, v93, v182
	v_mul_f32_e32 v183, v94, v183
	v_mul_f32_e32 v184, v95, v184
	v_cvt_pk_bf16_f32 v128, v181, v182
	v_cvt_pk_bf16_f32 v129, v183, v184
	v_cvt_pk_bf16_f32 v130, v177, v178
	v_cvt_pk_bf16_f32 v131, v179, v180
	global_store_dwordx4 v175, v[128:131], s[42:43] nt
	v_mul_f32_e32 v197, 0xbfb8aa3b, v80
	v_mul_f32_e32 v198, 0xbfb8aa3b, v81
	v_mul_f32_e32 v199, 0xbfb8aa3b, v82
	v_mul_f32_e32 v200, 0xbfb8aa3b, v83
	v_mul_f32_e32 v201, 0xbfb8aa3b, v84
	v_mul_f32_e32 v202, 0xbfb8aa3b, v85
	v_mul_f32_e32 v203, 0xbfb8aa3b, v86
	v_mul_f32_e32 v204, 0xbfb8aa3b, v87
	v_exp_f32_e32 v197, v197
	v_exp_f32_e32 v198, v198
	v_exp_f32_e32 v199, v199
	v_exp_f32_e32 v200, v200
	v_exp_f32_e32 v201, v201
	v_exp_f32_e32 v202, v202
	v_exp_f32_e32 v203, v203
	v_exp_f32_e32 v204, v204
	v_add_f32_e32 v197, 1.0, v197
	v_add_f32_e32 v198, 1.0, v198
	v_add_f32_e32 v199, 1.0, v199
	v_add_f32_e32 v200, 1.0, v200
	v_add_f32_e32 v201, 1.0, v201
	v_add_f32_e32 v202, 1.0, v202
	v_add_f32_e32 v203, 1.0, v203
	v_add_f32_e32 v204, 1.0, v204
	v_rcp_f32_e32 v197, v197
	v_rcp_f32_e32 v198, v198
	v_rcp_f32_e32 v199, v199
	v_rcp_f32_e32 v200, v200
	v_rcp_f32_e32 v201, v201
	v_rcp_f32_e32 v202, v202
	v_rcp_f32_e32 v203, v203
	v_rcp_f32_e32 v204, v204
	v_mul_f32_e32 v197, v80, v197
	v_mul_f32_e32 v198, v81, v198
	v_mul_f32_e32 v199, v82, v199
	v_mul_f32_e32 v200, v83, v200
	v_mul_f32_e32 v201, v84, v201
	v_mul_f32_e32 v202, v85, v202
	v_mul_f32_e32 v203, v86, v203
	v_mul_f32_e32 v204, v87, v204
	v_cvt_pk_bf16_f32 v160, v201, v202
	v_cvt_pk_bf16_f32 v161, v203, v204
	v_cvt_pk_bf16_f32 v162, v197, v198
	v_cvt_pk_bf16_f32 v163, v199, v200
	global_store_dwordx4 v175, v[160:163], s[42:43] offset:256 nt
	s_add_u32 s42, s42, 0x8000
	s_addc_u32 s43, s43, 0
	v_mul_f32_e32 v177, 0xbfb8aa3b, v72
	v_mul_f32_e32 v178, 0xbfb8aa3b, v73
	v_mul_f32_e32 v179, 0xbfb8aa3b, v74
	v_mul_f32_e32 v180, 0xbfb8aa3b, v75
	v_mul_f32_e32 v181, 0xbfb8aa3b, v76
	v_mul_f32_e32 v182, 0xbfb8aa3b, v77
	v_mul_f32_e32 v183, 0xbfb8aa3b, v78
	v_mul_f32_e32 v184, 0xbfb8aa3b, v79
	v_exp_f32_e32 v177, v177
	v_exp_f32_e32 v178, v178
	v_exp_f32_e32 v179, v179
	v_exp_f32_e32 v180, v180
	v_exp_f32_e32 v181, v181
	v_exp_f32_e32 v182, v182
	v_exp_f32_e32 v183, v183
	v_exp_f32_e32 v184, v184
	v_add_f32_e32 v177, 1.0, v177
	v_add_f32_e32 v178, 1.0, v178
	v_add_f32_e32 v179, 1.0, v179
	v_add_f32_e32 v180, 1.0, v180
	v_add_f32_e32 v181, 1.0, v181
	v_add_f32_e32 v182, 1.0, v182
	v_add_f32_e32 v183, 1.0, v183
	v_add_f32_e32 v184, 1.0, v184
	v_rcp_f32_e32 v177, v177
	v_rcp_f32_e32 v178, v178
	v_rcp_f32_e32 v179, v179
	v_rcp_f32_e32 v180, v180
	v_rcp_f32_e32 v181, v181
	v_rcp_f32_e32 v182, v182
	v_rcp_f32_e32 v183, v183
	v_rcp_f32_e32 v184, v184
	v_mul_f32_e32 v177, v72, v177
	v_mul_f32_e32 v178, v73, v178
	v_mul_f32_e32 v179, v74, v179
	v_mul_f32_e32 v180, v75, v180
	v_mul_f32_e32 v181, v76, v181
	v_mul_f32_e32 v182, v77, v182
	v_mul_f32_e32 v183, v78, v183
	v_mul_f32_e32 v184, v79, v184
	v_cvt_pk_bf16_f32 v128, v181, v182
	v_cvt_pk_bf16_f32 v129, v183, v184
	v_cvt_pk_bf16_f32 v130, v177, v178
	v_cvt_pk_bf16_f32 v131, v179, v180
	global_store_dwordx4 v175, v[128:131], s[42:43] nt
	v_mul_f32_e32 v197, 0xbfb8aa3b, v64
	v_mul_f32_e32 v198, 0xbfb8aa3b, v65
	v_mul_f32_e32 v199, 0xbfb8aa3b, v66
	v_mul_f32_e32 v200, 0xbfb8aa3b, v67
	v_mul_f32_e32 v201, 0xbfb8aa3b, v68
	v_mul_f32_e32 v202, 0xbfb8aa3b, v69
	v_mul_f32_e32 v203, 0xbfb8aa3b, v70
	v_mul_f32_e32 v204, 0xbfb8aa3b, v71
	v_exp_f32_e32 v197, v197
	v_exp_f32_e32 v198, v198
	v_exp_f32_e32 v199, v199
	v_exp_f32_e32 v200, v200
	v_exp_f32_e32 v201, v201
	v_exp_f32_e32 v202, v202
	v_exp_f32_e32 v203, v203
	v_exp_f32_e32 v204, v204
	v_add_f32_e32 v197, 1.0, v197
	v_add_f32_e32 v198, 1.0, v198
	v_add_f32_e32 v199, 1.0, v199
	v_add_f32_e32 v200, 1.0, v200
	v_add_f32_e32 v201, 1.0, v201
	v_add_f32_e32 v202, 1.0, v202
	v_add_f32_e32 v203, 1.0, v203
	v_add_f32_e32 v204, 1.0, v204
	v_rcp_f32_e32 v197, v197
	v_rcp_f32_e32 v198, v198
	v_rcp_f32_e32 v199, v199
	v_rcp_f32_e32 v200, v200
	v_rcp_f32_e32 v201, v201
	v_rcp_f32_e32 v202, v202
	v_rcp_f32_e32 v203, v203
	v_rcp_f32_e32 v204, v204
	v_mul_f32_e32 v197, v64, v197
	v_mul_f32_e32 v198, v65, v198
	v_mul_f32_e32 v199, v66, v199
	v_mul_f32_e32 v200, v67, v200
	v_mul_f32_e32 v201, v68, v201
	v_mul_f32_e32 v202, v69, v202
	v_mul_f32_e32 v203, v70, v203
	v_mul_f32_e32 v204, v71, v204
	v_cvt_pk_bf16_f32 v160, v201, v202
	v_cvt_pk_bf16_f32 v161, v203, v204
	v_cvt_pk_bf16_f32 v162, v197, v198
	v_cvt_pk_bf16_f32 v163, v199, v200
	global_store_dwordx4 v175, v[160:163], s[42:43] offset:256 nt
	s_add_u32 s42, s42, 0x28000
	s_addc_u32 s43, s43, 0
	v_mul_f32_e32 v177, 0xbfb8aa3b, v56
	v_mul_f32_e32 v178, 0xbfb8aa3b, v57
	v_mul_f32_e32 v179, 0xbfb8aa3b, v58
	v_mul_f32_e32 v180, 0xbfb8aa3b, v59
	v_mul_f32_e32 v181, 0xbfb8aa3b, v60
	v_mul_f32_e32 v182, 0xbfb8aa3b, v61
	v_mul_f32_e32 v183, 0xbfb8aa3b, v62
	v_mul_f32_e32 v184, 0xbfb8aa3b, v63
	v_exp_f32_e32 v177, v177
	v_exp_f32_e32 v178, v178
	v_exp_f32_e32 v179, v179
	v_exp_f32_e32 v180, v180
	v_exp_f32_e32 v181, v181
	v_exp_f32_e32 v182, v182
	v_exp_f32_e32 v183, v183
	v_exp_f32_e32 v184, v184
	v_add_f32_e32 v177, 1.0, v177
	v_add_f32_e32 v178, 1.0, v178
	v_add_f32_e32 v179, 1.0, v179
	v_add_f32_e32 v180, 1.0, v180
	v_add_f32_e32 v181, 1.0, v181
	v_add_f32_e32 v182, 1.0, v182
	v_add_f32_e32 v183, 1.0, v183
	v_add_f32_e32 v184, 1.0, v184
	v_rcp_f32_e32 v177, v177
	v_rcp_f32_e32 v178, v178
	v_rcp_f32_e32 v179, v179
	v_rcp_f32_e32 v180, v180
	v_rcp_f32_e32 v181, v181
	v_rcp_f32_e32 v182, v182
	v_rcp_f32_e32 v183, v183
	v_rcp_f32_e32 v184, v184
	v_mul_f32_e32 v177, v56, v177
	v_mul_f32_e32 v178, v57, v178
	v_mul_f32_e32 v179, v58, v179
	v_mul_f32_e32 v180, v59, v180
	v_mul_f32_e32 v181, v60, v181
	v_mul_f32_e32 v182, v61, v182
	v_mul_f32_e32 v183, v62, v183
	v_mul_f32_e32 v184, v63, v184
	v_cvt_pk_bf16_f32 v128, v181, v182
	v_cvt_pk_bf16_f32 v129, v183, v184
	v_cvt_pk_bf16_f32 v130, v177, v178
	v_cvt_pk_bf16_f32 v131, v179, v180
	global_store_dwordx4 v175, v[128:131], s[42:43] nt
	v_mul_f32_e32 v197, 0xbfb8aa3b, v48
	v_mul_f32_e32 v198, 0xbfb8aa3b, v49
	v_mul_f32_e32 v199, 0xbfb8aa3b, v50
	v_mul_f32_e32 v200, 0xbfb8aa3b, v51
	v_mul_f32_e32 v201, 0xbfb8aa3b, v52
	v_mul_f32_e32 v202, 0xbfb8aa3b, v53
	v_mul_f32_e32 v203, 0xbfb8aa3b, v54
	v_mul_f32_e32 v204, 0xbfb8aa3b, v55
	v_exp_f32_e32 v197, v197
	v_exp_f32_e32 v198, v198
	v_exp_f32_e32 v199, v199
	v_exp_f32_e32 v200, v200
	v_exp_f32_e32 v201, v201
	v_exp_f32_e32 v202, v202
	v_exp_f32_e32 v203, v203
	v_exp_f32_e32 v204, v204
	v_add_f32_e32 v197, 1.0, v197
	v_add_f32_e32 v198, 1.0, v198
	v_add_f32_e32 v199, 1.0, v199
	v_add_f32_e32 v200, 1.0, v200
	v_add_f32_e32 v201, 1.0, v201
	v_add_f32_e32 v202, 1.0, v202
	v_add_f32_e32 v203, 1.0, v203
	v_add_f32_e32 v204, 1.0, v204
	v_rcp_f32_e32 v197, v197
	v_rcp_f32_e32 v198, v198
	v_rcp_f32_e32 v199, v199
	v_rcp_f32_e32 v200, v200
	v_rcp_f32_e32 v201, v201
	v_rcp_f32_e32 v202, v202
	v_rcp_f32_e32 v203, v203
	v_rcp_f32_e32 v204, v204
	v_mul_f32_e32 v197, v48, v197
	v_mul_f32_e32 v198, v49, v198
	v_mul_f32_e32 v199, v50, v199
	v_mul_f32_e32 v200, v51, v200
	v_mul_f32_e32 v201, v52, v201
	v_mul_f32_e32 v202, v53, v202
	v_mul_f32_e32 v203, v54, v203
	v_mul_f32_e32 v204, v55, v204
	v_cvt_pk_bf16_f32 v160, v201, v202
	v_cvt_pk_bf16_f32 v161, v203, v204
	v_cvt_pk_bf16_f32 v162, v197, v198
	v_cvt_pk_bf16_f32 v163, v199, v200
	global_store_dwordx4 v175, v[160:163], s[42:43] offset:256 nt
	s_add_u32 s42, s42, 0x8000
	s_addc_u32 s43, s43, 0
	v_mul_f32_e32 v177, 0xbfb8aa3b, v40
	v_mul_f32_e32 v178, 0xbfb8aa3b, v41
	v_mul_f32_e32 v179, 0xbfb8aa3b, v42
	v_mul_f32_e32 v180, 0xbfb8aa3b, v43
	v_mul_f32_e32 v181, 0xbfb8aa3b, v44
	v_mul_f32_e32 v182, 0xbfb8aa3b, v45
	v_mul_f32_e32 v183, 0xbfb8aa3b, v46
	v_mul_f32_e32 v184, 0xbfb8aa3b, v47
	v_exp_f32_e32 v177, v177
	v_exp_f32_e32 v178, v178
	v_exp_f32_e32 v179, v179
	v_exp_f32_e32 v180, v180
	v_exp_f32_e32 v181, v181
	v_exp_f32_e32 v182, v182
	v_exp_f32_e32 v183, v183
	v_exp_f32_e32 v184, v184
	v_add_f32_e32 v177, 1.0, v177
	v_add_f32_e32 v178, 1.0, v178
	v_add_f32_e32 v179, 1.0, v179
	v_add_f32_e32 v180, 1.0, v180
	v_add_f32_e32 v181, 1.0, v181
	v_add_f32_e32 v182, 1.0, v182
	v_add_f32_e32 v183, 1.0, v183
	v_add_f32_e32 v184, 1.0, v184
	v_rcp_f32_e32 v177, v177
	v_rcp_f32_e32 v178, v178
	v_rcp_f32_e32 v179, v179
	v_rcp_f32_e32 v180, v180
	v_rcp_f32_e32 v181, v181
	v_rcp_f32_e32 v182, v182
	v_rcp_f32_e32 v183, v183
	v_rcp_f32_e32 v184, v184
	v_mul_f32_e32 v177, v40, v177
	v_mul_f32_e32 v178, v41, v178
	v_mul_f32_e32 v179, v42, v179
	v_mul_f32_e32 v180, v43, v180
	v_mul_f32_e32 v181, v44, v181
	v_mul_f32_e32 v182, v45, v182
	v_mul_f32_e32 v183, v46, v183
	v_mul_f32_e32 v184, v47, v184
	v_cvt_pk_bf16_f32 v128, v181, v182
	v_cvt_pk_bf16_f32 v129, v183, v184
	v_cvt_pk_bf16_f32 v130, v177, v178
	v_cvt_pk_bf16_f32 v131, v179, v180
	global_store_dwordx4 v175, v[128:131], s[42:43] nt
	v_mul_f32_e32 v197, 0xbfb8aa3b, v32
	v_mul_f32_e32 v198, 0xbfb8aa3b, v33
	v_mul_f32_e32 v199, 0xbfb8aa3b, v34
	v_mul_f32_e32 v200, 0xbfb8aa3b, v35
	v_mul_f32_e32 v201, 0xbfb8aa3b, v36
	v_mul_f32_e32 v202, 0xbfb8aa3b, v37
	v_mul_f32_e32 v203, 0xbfb8aa3b, v38
	v_mul_f32_e32 v204, 0xbfb8aa3b, v39
	v_exp_f32_e32 v197, v197
	v_exp_f32_e32 v198, v198
	v_exp_f32_e32 v199, v199
	v_exp_f32_e32 v200, v200
	v_exp_f32_e32 v201, v201
	v_exp_f32_e32 v202, v202
	v_exp_f32_e32 v203, v203
	v_exp_f32_e32 v204, v204
	v_add_f32_e32 v197, 1.0, v197
	v_add_f32_e32 v198, 1.0, v198
	v_add_f32_e32 v199, 1.0, v199
	v_add_f32_e32 v200, 1.0, v200
	v_add_f32_e32 v201, 1.0, v201
	v_add_f32_e32 v202, 1.0, v202
	v_add_f32_e32 v203, 1.0, v203
	v_add_f32_e32 v204, 1.0, v204
	v_rcp_f32_e32 v197, v197
	v_rcp_f32_e32 v198, v198
	v_rcp_f32_e32 v199, v199
	v_rcp_f32_e32 v200, v200
	v_rcp_f32_e32 v201, v201
	v_rcp_f32_e32 v202, v202
	v_rcp_f32_e32 v203, v203
	v_rcp_f32_e32 v204, v204
	v_mul_f32_e32 v197, v32, v197
	v_mul_f32_e32 v198, v33, v198
	v_mul_f32_e32 v199, v34, v199
	v_mul_f32_e32 v200, v35, v200
	v_mul_f32_e32 v201, v36, v201
	v_mul_f32_e32 v202, v37, v202
	v_mul_f32_e32 v203, v38, v203
	v_mul_f32_e32 v204, v39, v204
	v_cvt_pk_bf16_f32 v160, v201, v202
	v_cvt_pk_bf16_f32 v161, v203, v204
	v_cvt_pk_bf16_f32 v162, v197, v198
	v_cvt_pk_bf16_f32 v163, v199, v200
	global_store_dwordx4 v175, v[160:163], s[42:43] offset:256 nt
	s_add_u32 s42, s42, 0x8000
	s_addc_u32 s43, s43, 0
	v_mul_f32_e32 v177, 0xbfb8aa3b, v24
	v_mul_f32_e32 v178, 0xbfb8aa3b, v25
	v_mul_f32_e32 v179, 0xbfb8aa3b, v26
	v_mul_f32_e32 v180, 0xbfb8aa3b, v27
	v_mul_f32_e32 v181, 0xbfb8aa3b, v28
	v_mul_f32_e32 v182, 0xbfb8aa3b, v29
	v_mul_f32_e32 v183, 0xbfb8aa3b, v30
	v_mul_f32_e32 v184, 0xbfb8aa3b, v31
	v_exp_f32_e32 v177, v177
	v_exp_f32_e32 v178, v178
	v_exp_f32_e32 v179, v179
	v_exp_f32_e32 v180, v180
	v_exp_f32_e32 v181, v181
	v_exp_f32_e32 v182, v182
	v_exp_f32_e32 v183, v183
	v_exp_f32_e32 v184, v184
	v_add_f32_e32 v177, 1.0, v177
	v_add_f32_e32 v178, 1.0, v178
	v_add_f32_e32 v179, 1.0, v179
	v_add_f32_e32 v180, 1.0, v180
	v_add_f32_e32 v181, 1.0, v181
	v_add_f32_e32 v182, 1.0, v182
	v_add_f32_e32 v183, 1.0, v183
	v_add_f32_e32 v184, 1.0, v184
	v_rcp_f32_e32 v177, v177
	v_rcp_f32_e32 v178, v178
	v_rcp_f32_e32 v179, v179
	v_rcp_f32_e32 v180, v180
	v_rcp_f32_e32 v181, v181
	v_rcp_f32_e32 v182, v182
	v_rcp_f32_e32 v183, v183
	v_rcp_f32_e32 v184, v184
	v_mul_f32_e32 v177, v24, v177
	v_mul_f32_e32 v178, v25, v178
	v_mul_f32_e32 v179, v26, v179
	v_mul_f32_e32 v180, v27, v180
	v_mul_f32_e32 v181, v28, v181
	v_mul_f32_e32 v182, v29, v182
	v_mul_f32_e32 v183, v30, v183
	v_mul_f32_e32 v184, v31, v184
	v_cvt_pk_bf16_f32 v128, v181, v182
	v_cvt_pk_bf16_f32 v129, v183, v184
	v_cvt_pk_bf16_f32 v130, v177, v178
	v_cvt_pk_bf16_f32 v131, v179, v180
	global_store_dwordx4 v175, v[128:131], s[42:43] nt
	v_mul_f32_e32 v197, 0xbfb8aa3b, v16
	v_mul_f32_e32 v198, 0xbfb8aa3b, v17
	v_mul_f32_e32 v199, 0xbfb8aa3b, v18
	v_mul_f32_e32 v200, 0xbfb8aa3b, v19
	v_mul_f32_e32 v201, 0xbfb8aa3b, v20
	v_mul_f32_e32 v202, 0xbfb8aa3b, v21
	v_mul_f32_e32 v203, 0xbfb8aa3b, v22
	v_mul_f32_e32 v204, 0xbfb8aa3b, v23
	v_exp_f32_e32 v197, v197
	v_exp_f32_e32 v198, v198
	v_exp_f32_e32 v199, v199
	v_exp_f32_e32 v200, v200
	v_exp_f32_e32 v201, v201
	v_exp_f32_e32 v202, v202
	v_exp_f32_e32 v203, v203
	v_exp_f32_e32 v204, v204
	v_add_f32_e32 v197, 1.0, v197
	v_add_f32_e32 v198, 1.0, v198
	v_add_f32_e32 v199, 1.0, v199
	v_add_f32_e32 v200, 1.0, v200
	v_add_f32_e32 v201, 1.0, v201
	v_add_f32_e32 v202, 1.0, v202
	v_add_f32_e32 v203, 1.0, v203
	v_add_f32_e32 v204, 1.0, v204
	v_rcp_f32_e32 v197, v197
	v_rcp_f32_e32 v198, v198
	v_rcp_f32_e32 v199, v199
	v_rcp_f32_e32 v200, v200
	v_rcp_f32_e32 v201, v201
	v_rcp_f32_e32 v202, v202
	v_rcp_f32_e32 v203, v203
	v_rcp_f32_e32 v204, v204
	v_mul_f32_e32 v197, v16, v197
	v_mul_f32_e32 v198, v17, v198
	v_mul_f32_e32 v199, v18, v199
	v_mul_f32_e32 v200, v19, v200
	v_mul_f32_e32 v201, v20, v201
	v_mul_f32_e32 v202, v21, v202
	v_mul_f32_e32 v203, v22, v203
	v_mul_f32_e32 v204, v23, v204
	v_cvt_pk_bf16_f32 v160, v201, v202
	v_cvt_pk_bf16_f32 v161, v203, v204
	v_cvt_pk_bf16_f32 v162, v197, v198
	v_cvt_pk_bf16_f32 v163, v199, v200
	global_store_dwordx4 v175, v[160:163], s[42:43] offset:256 nt
	s_add_u32 s42, s42, 0x8000
	s_addc_u32 s43, s43, 0
	v_mul_f32_e32 v177, 0xbfb8aa3b, v8
	v_mul_f32_e32 v178, 0xbfb8aa3b, v9
	v_mul_f32_e32 v179, 0xbfb8aa3b, v10
	v_mul_f32_e32 v180, 0xbfb8aa3b, v11
	v_mul_f32_e32 v181, 0xbfb8aa3b, v12
	v_mul_f32_e32 v182, 0xbfb8aa3b, v13
	v_mul_f32_e32 v183, 0xbfb8aa3b, v14
	v_mul_f32_e32 v184, 0xbfb8aa3b, v15
	v_exp_f32_e32 v177, v177
	v_exp_f32_e32 v178, v178
	v_exp_f32_e32 v179, v179
	v_exp_f32_e32 v180, v180
	v_exp_f32_e32 v181, v181
	v_exp_f32_e32 v182, v182
	v_exp_f32_e32 v183, v183
	v_exp_f32_e32 v184, v184
	v_add_f32_e32 v177, 1.0, v177
	v_add_f32_e32 v178, 1.0, v178
	v_add_f32_e32 v179, 1.0, v179
	v_add_f32_e32 v180, 1.0, v180
	v_add_f32_e32 v181, 1.0, v181
	v_add_f32_e32 v182, 1.0, v182
	v_add_f32_e32 v183, 1.0, v183
	v_add_f32_e32 v184, 1.0, v184
	v_rcp_f32_e32 v177, v177
	v_rcp_f32_e32 v178, v178
	v_rcp_f32_e32 v179, v179
	v_rcp_f32_e32 v180, v180
	v_rcp_f32_e32 v181, v181
	v_rcp_f32_e32 v182, v182
	v_rcp_f32_e32 v183, v183
	v_rcp_f32_e32 v184, v184
	v_mul_f32_e32 v177, v8, v177
	v_mul_f32_e32 v178, v9, v178
	v_mul_f32_e32 v179, v10, v179
	v_mul_f32_e32 v180, v11, v180
	v_mul_f32_e32 v181, v12, v181
	v_mul_f32_e32 v182, v13, v182
	v_mul_f32_e32 v183, v14, v183
	v_mul_f32_e32 v184, v15, v184
	v_cvt_pk_bf16_f32 v128, v181, v182
	v_cvt_pk_bf16_f32 v129, v183, v184
	v_cvt_pk_bf16_f32 v130, v177, v178
	v_cvt_pk_bf16_f32 v131, v179, v180
	global_store_dwordx4 v175, v[128:131], s[42:43] nt
	v_mul_f32_e32 v197, 0xbfb8aa3b, v0
	v_mul_f32_e32 v198, 0xbfb8aa3b, v1
	v_mul_f32_e32 v199, 0xbfb8aa3b, v2
	v_mul_f32_e32 v200, 0xbfb8aa3b, v3
	v_mul_f32_e32 v201, 0xbfb8aa3b, v4
	v_mul_f32_e32 v202, 0xbfb8aa3b, v5
	v_mul_f32_e32 v203, 0xbfb8aa3b, v6
	v_mul_f32_e32 v204, 0xbfb8aa3b, v7
	v_exp_f32_e32 v197, v197
	v_exp_f32_e32 v198, v198
	v_exp_f32_e32 v199, v199
	v_exp_f32_e32 v200, v200
	v_exp_f32_e32 v201, v201
	v_exp_f32_e32 v202, v202
	v_exp_f32_e32 v203, v203
	v_exp_f32_e32 v204, v204
	v_add_f32_e32 v197, 1.0, v197
	v_add_f32_e32 v198, 1.0, v198
	v_add_f32_e32 v199, 1.0, v199
	v_add_f32_e32 v200, 1.0, v200
	v_add_f32_e32 v201, 1.0, v201
	v_add_f32_e32 v202, 1.0, v202
	v_add_f32_e32 v203, 1.0, v203
	v_add_f32_e32 v204, 1.0, v204
	v_rcp_f32_e32 v197, v197
	v_rcp_f32_e32 v198, v198
	v_rcp_f32_e32 v199, v199
	v_rcp_f32_e32 v200, v200
	v_rcp_f32_e32 v201, v201
	v_rcp_f32_e32 v202, v202
	v_rcp_f32_e32 v203, v203
	v_rcp_f32_e32 v204, v204
	v_mul_f32_e32 v197, v0, v197
	v_mul_f32_e32 v198, v1, v198
	v_mul_f32_e32 v199, v2, v199
	v_mul_f32_e32 v200, v3, v200
	v_mul_f32_e32 v201, v4, v201
	v_mul_f32_e32 v202, v5, v202
	v_mul_f32_e32 v203, v6, v203
	v_mul_f32_e32 v204, v7, v204
	v_cvt_pk_bf16_f32 v160, v201, v202
	v_cvt_pk_bf16_f32 v161, v203, v204
	v_cvt_pk_bf16_f32 v162, v197, v198
	v_cvt_pk_bf16_f32 v163, v199, v200
	global_store_dwordx4 v175, v[160:163], s[42:43] offset:256 nt
	s_branch .LBB0_561
.Lmy_epi_u:
	v_lshrrev_b32_e32 v192, 1, v188
	v_lshl_add_u32 v192, v190, 1, v192
	v_lshlrev_b32_e32 v176, 18, v192
	v_lshl_add_u32 v176, v191, 5, v176
	v_and_b32_e32 v192, 1, v188
	v_lshl_add_u32 v176, v192, 4, v176
	s_lshr_b32 s40, s50, 5
	s_lshl_b32 s40, s40, 24
	s_lshl_b32 s41, s15, 22
	s_add_u32 s40, s40, s41
	s_and_b32 s41, s50, 31
	s_lshl_b32 s41, s41, 13
	s_add_u32 s40, s40, s41
	s_add_u32 s40, s40, 0x4000000
	s_add_u32 s40, s20, s40
	s_addc_u32 s41, s21, 0
	s_mov_b64 s[42:43], s[40:41]
	v_cvt_pk_bf16_f32 v128, v124, v125
	v_cvt_pk_bf16_f32 v129, v126, v127
	v_cvt_pk_bf16_f32 v130, v120, v121
	v_cvt_pk_bf16_f32 v131, v122, v123
	global_store_dwordx4 v176, v[128:131], s[42:43]
	v_cvt_pk_bf16_f32 v160, v108, v109
	v_cvt_pk_bf16_f32 v161, v110, v111
	v_cvt_pk_bf16_f32 v162, v104, v105
	v_cvt_pk_bf16_f32 v163, v106, v107
	global_store_dwordx4 v176, v[160:163], s[42:43] offset:512
	v_cvt_pk_bf16_f32 v128, v92, v93
	v_cvt_pk_bf16_f32 v129, v94, v95
	v_cvt_pk_bf16_f32 v130, v88, v89
	v_cvt_pk_bf16_f32 v131, v90, v91
	global_store_dwordx4 v176, v[128:131], s[42:43] offset:1024
	v_cvt_pk_bf16_f32 v160, v76, v77
	v_cvt_pk_bf16_f32 v161, v78, v79
	v_cvt_pk_bf16_f32 v162, v72, v73
	v_cvt_pk_bf16_f32 v163, v74, v75
	global_store_dwordx4 v176, v[160:163], s[42:43] offset:1536
	s_add_u32 s42, s40, 0x200000
	s_addc_u32 s43, s41, 0
	v_cvt_pk_bf16_f32 v128, v116, v117
	v_cvt_pk_bf16_f32 v129, v118, v119
	v_cvt_pk_bf16_f32 v130, v112, v113
	v_cvt_pk_bf16_f32 v131, v114, v115
	global_store_dwordx4 v176, v[128:131], s[42:43]
	v_cvt_pk_bf16_f32 v160, v100, v101
	v_cvt_pk_bf16_f32 v161, v102, v103
	v_cvt_pk_bf16_f32 v162, v96, v97
	v_cvt_pk_bf16_f32 v163, v98, v99
	global_store_dwordx4 v176, v[160:163], s[42:43] offset:512
	v_cvt_pk_bf16_f32 v128, v84, v85
	v_cvt_pk_bf16_f32 v129, v86, v87
	v_cvt_pk_bf16_f32 v130, v80, v81
	v_cvt_pk_bf16_f32 v131, v82, v83
	global_store_dwordx4 v176, v[128:131], s[42:43] offset:1024
	v_cvt_pk_bf16_f32 v160, v68, v69
	v_cvt_pk_bf16_f32 v161, v70, v71
	v_cvt_pk_bf16_f32 v162, v64, v65
	v_cvt_pk_bf16_f32 v163, v66, v67
	global_store_dwordx4 v176, v[160:163], s[42:43] offset:1536
	s_add_u32 s42, s40, 0x1000
	s_addc_u32 s43, s41, 0
	v_cvt_pk_bf16_f32 v128, v60, v61
	v_cvt_pk_bf16_f32 v129, v62, v63
	v_cvt_pk_bf16_f32 v130, v56, v57
	v_cvt_pk_bf16_f32 v131, v58, v59
	global_store_dwordx4 v176, v[128:131], s[42:43]
	v_cvt_pk_bf16_f32 v160, v44, v45
	v_cvt_pk_bf16_f32 v161, v46, v47
	v_cvt_pk_bf16_f32 v162, v40, v41
	v_cvt_pk_bf16_f32 v163, v42, v43
	global_store_dwordx4 v176, v[160:163], s[42:43] offset:512
	v_cvt_pk_bf16_f32 v128, v28, v29
	v_cvt_pk_bf16_f32 v129, v30, v31
	v_cvt_pk_bf16_f32 v130, v24, v25
	v_cvt_pk_bf16_f32 v131, v26, v27
	global_store_dwordx4 v176, v[128:131], s[42:43] offset:1024
	v_cvt_pk_bf16_f32 v160, v12, v13
	v_cvt_pk_bf16_f32 v161, v14, v15
	v_cvt_pk_bf16_f32 v162, v8, v9
	v_cvt_pk_bf16_f32 v163, v10, v11
	global_store_dwordx4 v176, v[160:163], s[42:43] offset:1536
	s_add_u32 s42, s40, 0x201000
	s_addc_u32 s43, s41, 0
	v_cvt_pk_bf16_f32 v128, v52, v53
	v_cvt_pk_bf16_f32 v129, v54, v55
	v_cvt_pk_bf16_f32 v130, v48, v49
	v_cvt_pk_bf16_f32 v131, v50, v51
	global_store_dwordx4 v176, v[128:131], s[42:43]
	v_cvt_pk_bf16_f32 v160, v36, v37
	v_cvt_pk_bf16_f32 v161, v38, v39
	v_cvt_pk_bf16_f32 v162, v32, v33
	v_cvt_pk_bf16_f32 v163, v34, v35
	global_store_dwordx4 v176, v[160:163], s[42:43] offset:512
	v_cvt_pk_bf16_f32 v128, v20, v21
	v_cvt_pk_bf16_f32 v129, v22, v23
	v_cvt_pk_bf16_f32 v130, v16, v17
	v_cvt_pk_bf16_f32 v131, v18, v19
	global_store_dwordx4 v176, v[128:131], s[42:43] offset:1024
	v_cvt_pk_bf16_f32 v160, v4, v5
	v_cvt_pk_bf16_f32 v161, v6, v7
	v_cvt_pk_bf16_f32 v162, v0, v1
	v_cvt_pk_bf16_f32 v163, v2, v3
	global_store_dwordx4 v176, v[160:163], s[42:43] offset:1536
	s_branch .LBB0_561
.LBB0_272:
	s_and_b64 vcc, exec, s[52:53]
	s_cbranch_vccz .LBB0_561
	s_cmp_lt_u32 s46, 4
	s_cselect_b64 vcc, -1, 0
	v_readlane_b32 s36, v253, 25
	s_and_b64 s[2:3], vcc, exec
	v_readlane_b32 s48, v253, 37
	v_readlane_b32 s49, v253, 38
	v_readlane_b32 s50, v253, 39
	v_readlane_b32 s51, v253, 40
	s_cselect_b32 s3, s49, s51
	s_cselect_b32 s2, s48, s50
	v_lshlrev_b32_e32 v128, 2, v142
	global_load_dwordx4 v[160:163], v128, s[2:3]
	global_load_dwordx4 v[176:179], v128, s[2:3] offset:16
	global_load_dwordx4 v[180:183], v128, s[2:3] offset:128
	global_load_dwordx4 v[184:187], v128, s[2:3] offset:144
	v_readlane_b32 s2, v253, 60
	v_readlane_b32 s3, v253, 58
	s_cselect_b32 s3, s2, s3
	v_readlane_b32 s2, v253, 59
	v_readlane_b32 s12, v253, 23
	s_cselect_b32 s2, s2, s12
	s_lshl_b32 s12, s15, 9
	s_or_b32 s12, s12, s81
	s_add_u32 s2, s2, s12
	v_lshlrev_b32_e32 v140, 1, v142
	v_lshlrev_b32_e32 v130, 7, v158
	s_addc_u32 s3, s3, 0
	v_lshl_add_u64 v[128:129], s[2:3], 0, v[140:141]
	v_and_b32_e32 v140, 0xfe780, v130
	v_lshl_add_u64 v[130:131], v[148:149], 0, v[140:141]
	global_load_dwordx4 v[188:191], v[130:131], off
	v_lshl_add_u64 v[164:165], v[146:147], 0, v[140:141]
	global_load_dwordx4 v[192:195], v[164:165], off
	global_load_dwordx4 v[198:201], v[130:131], off offset:16
	global_load_dwordx4 v[202:205], v[164:165], off offset:16
	v_pk_mul_f32 v[130:131], v[126:127], v[126:127]
	v_pk_mul_f32 v[164:165], v[124:125], v[124:125]
	v_pk_mul_f32 v[206:207], v[122:123], v[122:123]
	v_pk_mul_f32 v[208:209], v[120:121], v[120:121]
	v_pk_mul_f32 v[212:213], v[116:117], v[116:117]
	v_pk_mov_b32 v[218:219], v[164:165], v[130:131] op_sel:[1,0]
	v_mov_b32_e32 v165, v131
	v_pk_mov_b32 v[130:131], v[208:209], v[206:207] op_sel:[1,0]
	v_mov_b32_e32 v209, v207
	v_add_f32_e32 v206, v212, v213
	v_pk_add_f32 v[212:213], v[218:219], v[164:165]
	v_pk_add_f32 v[130:131], v[130:131], v[208:209]
	v_and_b32_e32 v159, 64, v174
	v_pk_mul_f32 v[210:211], v[118:119], v[118:119]
	v_pk_mul_f32 v[214:215], v[114:115], v[114:115]
	v_pk_mul_f32 v[216:217], v[112:113], v[112:113]
	v_pk_add_f32 v[208:209], v[212:213], v[212:213] op_sel:[0,1] op_sel_hi:[1,0]
	v_pk_add_f32 v[130:131], v[130:131], v[130:131] op_sel:[0,1] op_sel_hi:[1,0]
	v_xor_b32_e32 v140, 16, v174
	v_add_u32_e32 v159, 64, v159
	v_add_f32_e32 v210, v210, v211
	v_mov_b32_e32 v207, v214
	v_mov_b32_e32 v211, v215
	v_mov_b32_e32 v209, v216
	v_mov_b32_e32 v131, v217
	v_cndmask_b32_e32 v166, 1.0, v173, vcc
	v_cmp_lt_i32_e32 vcc, v140, v159
	v_pk_add_f32 v[206:207], v[206:207], v[210:211]
	v_pk_add_f32 v[130:131], v[208:209], v[130:131]
	v_cndmask_b32_e32 v140, v174, v140, vcc
	v_pk_add_f32 v[130:131], v[130:131], v[206:207]
	v_lshlrev_b32_e32 v164, 2, v140
	v_add_f32_e32 v130, v130, v131
	ds_bpermute_b32 v131, v164, v130
	v_xor_b32_e32 v140, 32, v174
	v_cmp_lt_i32_e32 vcc, v140, v159
	v_ashrrev_i32_e32 v159, 31, v158
	v_readlane_b32 s37, v253, 26
	v_cndmask_b32_e32 v140, v174, v140, vcc
	v_lshlrev_b32_e32 v165, 2, v140
	s_waitcnt lgkmcnt(0)
	v_add_f32_e32 v130, v130, v131
	ds_bpermute_b32 v131, v165, v130
	v_readlane_b32 s38, v253, 27
	v_readlane_b32 s39, v253, 28
	v_readlane_b32 s40, v253, 29
	v_readlane_b32 s41, v253, 30
	s_waitcnt lgkmcnt(0)
	v_add_f32_e32 v130, v130, v131
	v_fmamk_f32 v130, v130, 0x3c800000, v172
	v_rsq_f32_e32 v140, v130
	v_readlane_b32 s42, v253, 31
	v_readlane_b32 s43, v253, 32
	v_readlane_b32 s44, v253, 33
	v_pk_mul_f32 v[210:211], v[122:123], v[140:141] op_sel_hi:[1,0]
	v_pk_mul_f32 v[118:119], v[118:119], v[140:141] op_sel_hi:[1,0]
	v_pk_mul_f32 v[206:207], v[126:127], v[140:141] op_sel_hi:[1,0]
	v_pk_mul_f32 v[208:209], v[124:125], v[140:141] op_sel_hi:[1,0]
	v_pk_mul_f32 v[212:213], v[120:121], v[140:141] op_sel_hi:[1,0]
	v_pk_mul_f32 v[214:215], v[116:117], v[140:141] op_sel_hi:[1,0]
	s_waitcnt vmcnt(0)
	v_pk_mul_f32 v[130:131], v[166:167], v[162:163] op_sel_hi:[0,1]
	v_pk_mul_f32 v[112:113], v[112:113], v[140:141] op_sel_hi:[1,0]
	v_pk_mul_f32 v[122:123], v[166:167], v[182:183] op_sel_hi:[0,1]
	v_pk_mul_f32 v[124:125], v[166:167], v[180:181] op_sel_hi:[0,1]
	v_pk_mul_f32 v[116:117], v[166:167], v[186:187] op_sel_hi:[0,1]
	v_pk_mul_f32 v[120:121], v[166:167], v[184:185] op_sel_hi:[0,1]
	v_pk_mul_f32 v[118:119], v[122:123], v[118:119]
	v_pk_mul_f32 v[114:115], v[114:115], v[140:141] op_sel_hi:[1,0]
	v_pk_mul_f32 v[162:163], v[166:167], v[160:161] op_sel_hi:[0,1]
	v_pk_mul_f32 v[126:127], v[166:167], v[178:179] op_sel_hi:[0,1]
	v_pk_mul_f32 v[160:161], v[166:167], v[176:177] op_sel_hi:[0,1]
	v_pk_mul_f32 v[176:177], v[130:131], v[206:207]
	v_pk_mul_f32 v[182:183], v[124:125], v[214:215]
	v_pk_mul_f32 v[114:115], v[116:117], v[114:115]
	v_pk_mul_f32 v[112:113], v[120:121], v[112:113]
	v_pk_mul_f32 v[166:167], v[162:163], v[208:209]
	v_pk_mul_f32 v[178:179], v[160:161], v[212:213]
	v_pk_mul_f32 v[180:181], v[126:127], v[210:211]
	v_readlane_b32 s45, v253, 34
	v_pk_mul_f32 v[186:187], v[190:191], v[118:119]
	v_pk_mul_f32 v[118:119], v[194:195], v[118:119]
	v_pk_mul_f32 v[184:185], v[188:189], v[182:183]
	v_pk_mul_f32 v[206:207], v[198:199], v[112:113]
	v_pk_mul_f32 v[208:209], v[200:201], v[114:115]
	v_pk_mul_f32 v[182:183], v[192:193], v[182:183]
	v_pk_fma_f32 v[118:119], v[190:191], v[176:177], v[118:119]
	v_pk_mul_f32 v[112:113], v[202:203], v[112:113]
	v_pk_mul_f32 v[114:115], v[204:205], v[114:115]
	v_pk_fma_f32 v[186:187], v[194:195], v[176:177], v[186:187] neg_lo:[0,0,1] neg_hi:[0,0,1]
	v_pk_fma_f32 v[184:185], v[192:193], v[166:167], v[184:185] neg_lo:[0,0,1] neg_hi:[0,0,1]
	v_pk_fma_f32 v[208:209], v[204:205], v[180:181], v[208:209] neg_lo:[0,0,1] neg_hi:[0,0,1]
	v_pk_fma_f32 v[206:207], v[202:203], v[178:179], v[206:207] neg_lo:[0,0,1] neg_hi:[0,0,1]
	v_pk_fma_f32 v[166:167], v[188:189], v[166:167], v[182:183]
	v_pk_fma_f32 v[180:181], v[200:201], v[180:181], v[114:115]
	v_pk_fma_f32 v[178:179], v[198:199], v[178:179], v[112:113]
	v_cvt_pk_bf16_f32 v112, v184, v185
	v_cvt_pk_bf16_f32 v113, v186, v187
	v_cvt_pk_bf16_f32 v114, v206, v207
	v_cvt_pk_bf16_f32 v115, v208, v209
	v_cvt_pk_bf16_f32 v176, v166, v167
	v_cvt_pk_bf16_f32 v177, v118, v119
	v_lshlrev_b64 v[118:119], 11, v[158:159]
	v_lshl_add_u64 v[118:119], v[128:129], 0, v[118:119]
	v_cvt_pk_bf16_f32 v178, v178, v179
	v_cvt_pk_bf16_f32 v179, v180, v181
	global_store_dwordx4 v[118:119], v[112:115], off
	global_store_dwordx4 v[118:119], v[176:179], off offset:64
	v_or_b32_e32 v118, 16, v158
	v_lshlrev_b32_e32 v112, 7, v118
	v_and_b32_e32 v140, 0xfef80, v112
	v_lshl_add_u64 v[166:167], v[148:149], 0, v[140:141]
	v_lshl_add_u64 v[184:185], v[146:147], 0, v[140:141]
	global_load_dwordx4 v[112:115], v[166:167], off
	global_load_dwordx4 v[176:179], v[184:185], off
	global_load_dwordx4 v[180:183], v[166:167], off offset:16
	s_nop 0
	global_load_dwordx4 v[184:187], v[184:185], off offset:16
	v_pk_mul_f32 v[166:167], v[110:111], v[110:111]
	v_pk_mul_f32 v[188:189], v[108:109], v[108:109]
	v_pk_mul_f32 v[194:195], v[98:99], v[98:99]
	v_pk_mov_b32 v[190:191], v[188:189], v[166:167] op_sel:[1,0]
	v_mov_b32_e32 v189, v167
	v_pk_add_f32 v[166:167], v[190:191], v[188:189]
	v_pk_mul_f32 v[188:189], v[106:107], v[106:107]
	v_pk_mul_f32 v[190:191], v[104:105], v[104:105]
	v_pk_add_f32 v[166:167], v[166:167], v[166:167] op_sel:[0,1] op_sel_hi:[1,0]
	v_pk_mov_b32 v[192:193], v[190:191], v[188:189] op_sel:[1,0]
	v_mov_b32_e32 v191, v189
	v_pk_add_f32 v[188:189], v[192:193], v[190:191]
	v_pk_mul_f32 v[190:191], v[102:103], v[102:103]
	v_pk_add_f32 v[188:189], v[188:189], v[188:189] op_sel:[0,1] op_sel_hi:[1,0]
	v_pk_mul_f32 v[192:193], v[100:101], v[100:101]
	v_pk_mul_f32 v[198:199], v[96:97], v[96:97]
	v_add_f32_e32 v192, v192, v193
	v_add_f32_e32 v190, v190, v191
	v_mov_b32_e32 v167, v198
	v_mov_b32_e32 v189, v199
	v_mov_b32_e32 v193, v194
	v_mov_b32_e32 v191, v195
	v_pk_add_f32 v[166:167], v[166:167], v[188:189]
	v_pk_add_f32 v[188:189], v[192:193], v[190:191]
	v_readlane_b32 s46, v253, 35
	v_pk_add_f32 v[166:167], v[166:167], v[188:189]
	v_readlane_b32 s47, v253, 36
	v_add_f32_e32 v119, v166, v167
	ds_bpermute_b32 v140, v164, v119
	s_waitcnt lgkmcnt(0)
	v_add_f32_e32 v119, v119, v140
	ds_bpermute_b32 v140, v165, v119
	s_waitcnt lgkmcnt(0)
	v_add_f32_e32 v119, v119, v140
	v_fmamk_f32 v119, v119, 0x3c800000, v172
	v_rsq_f32_e32 v140, v119
	v_ashrrev_i32_e32 v119, 31, v118
	v_pk_mul_f32 v[100:101], v[100:101], v[140:141] op_sel_hi:[1,0]
	v_pk_mul_f32 v[102:103], v[102:103], v[140:141] op_sel_hi:[1,0]
	v_pk_mul_f32 v[96:97], v[96:97], v[140:141] op_sel_hi:[1,0]
	v_pk_mul_f32 v[110:111], v[110:111], v[140:141] op_sel_hi:[1,0]
	v_pk_mul_f32 v[108:109], v[108:109], v[140:141] op_sel_hi:[1,0]
	v_pk_mul_f32 v[104:105], v[104:105], v[140:141] op_sel_hi:[1,0]
	v_pk_mul_f32 v[102:103], v[122:123], v[102:103]
	v_pk_mul_f32 v[100:101], v[124:125], v[100:101]
	v_pk_mul_f32 v[98:99], v[98:99], v[140:141] op_sel_hi:[1,0]
	v_pk_mul_f32 v[96:97], v[120:121], v[96:97]
	v_pk_mul_f32 v[108:109], v[162:163], v[108:109]
	v_pk_mul_f32 v[110:111], v[130:131], v[110:111]
	v_pk_mul_f32 v[106:107], v[106:107], v[140:141] op_sel_hi:[1,0]
	v_pk_mul_f32 v[104:105], v[160:161], v[104:105]
	v_pk_mul_f32 v[98:99], v[116:117], v[98:99]
	v_pk_mul_f32 v[106:107], v[126:127], v[106:107]
	s_waitcnt vmcnt(3)
	v_pk_mul_f32 v[166:167], v[112:113], v[100:101]
	v_pk_mul_f32 v[188:189], v[114:115], v[102:103]
	s_waitcnt vmcnt(1)
	v_pk_mul_f32 v[190:191], v[180:181], v[96:97]
	v_pk_mul_f32 v[100:101], v[176:177], v[100:101]
	v_pk_mul_f32 v[102:103], v[178:179], v[102:103]
	s_waitcnt vmcnt(0)
	v_pk_mul_f32 v[96:97], v[184:185], v[96:97]
	v_pk_mul_f32 v[192:193], v[182:183], v[98:99]
	v_pk_fma_f32 v[190:191], v[184:185], v[104:105], v[190:191] neg_lo:[0,0,1] neg_hi:[0,0,1]
	v_pk_fma_f32 v[102:103], v[114:115], v[110:111], v[102:103]
	v_pk_fma_f32 v[100:101], v[112:113], v[108:109], v[100:101]
	v_pk_mul_f32 v[98:99], v[186:187], v[98:99]
	v_pk_fma_f32 v[104:105], v[180:181], v[104:105], v[96:97]
	v_pk_fma_f32 v[188:189], v[178:179], v[110:111], v[188:189] neg_lo:[0,0,1] neg_hi:[0,0,1]
	v_pk_fma_f32 v[166:167], v[176:177], v[108:109], v[166:167] neg_lo:[0,0,1] neg_hi:[0,0,1]
	v_pk_fma_f32 v[192:193], v[186:187], v[106:107], v[192:193] neg_lo:[0,0,1] neg_hi:[0,0,1]
	v_pk_fma_f32 v[106:107], v[182:183], v[106:107], v[98:99]
	v_cvt_pk_bf16_f32 v96, v166, v167
	v_cvt_pk_bf16_f32 v97, v188, v189
	v_cvt_pk_bf16_f32 v98, v190, v191
	v_cvt_pk_bf16_f32 v99, v192, v193
	v_cvt_pk_bf16_f32 v100, v100, v101
	v_cvt_pk_bf16_f32 v101, v102, v103
	v_cvt_pk_bf16_f32 v102, v104, v105
	v_lshlrev_b64 v[104:105], 11, v[118:119]
	v_lshl_add_u64 v[104:105], v[128:129], 0, v[104:105]
	v_or_b32_e32 v112, 32, v158
	v_cvt_pk_bf16_f32 v103, v106, v107
	global_store_dwordx4 v[104:105], v[96:99], off
	global_store_dwordx4 v[104:105], v[100:103], off offset:64
	v_pk_mul_f32 v[114:115], v[94:95], v[94:95]
	v_lshlrev_b32_e32 v96, 7, v112
	v_and_b32_e32 v140, 0xff780, v96
	v_lshl_add_u64 v[104:105], v[148:149], 0, v[140:141]
	v_lshl_add_u64 v[108:109], v[146:147], 0, v[140:141]
	global_load_dwordx4 v[96:99], v[104:105], off
	global_load_dwordx4 v[100:103], v[108:109], off
	s_nop 0
	global_load_dwordx4 v[104:107], v[104:105], off offset:16
	s_nop 0
	global_load_dwordx4 v[108:111], v[108:109], off offset:16
	v_pk_mul_f32 v[118:119], v[92:93], v[92:93]
	v_pk_mul_f32 v[178:179], v[82:83], v[82:83]
	v_pk_mov_b32 v[166:167], v[118:119], v[114:115] op_sel:[1,0]
	v_mov_b32_e32 v119, v115
	v_pk_add_f32 v[114:115], v[166:167], v[118:119]
	v_pk_mul_f32 v[118:119], v[90:91], v[90:91]
	v_pk_mul_f32 v[166:167], v[88:89], v[88:89]
	v_pk_add_f32 v[114:115], v[114:115], v[114:115] op_sel:[0,1] op_sel_hi:[1,0]
	v_pk_mov_b32 v[176:177], v[166:167], v[118:119] op_sel:[1,0]
	v_mov_b32_e32 v167, v119
	v_pk_add_f32 v[118:119], v[176:177], v[166:167]
	v_pk_mul_f32 v[166:167], v[86:87], v[86:87]
	v_pk_add_f32 v[118:119], v[118:119], v[118:119] op_sel:[0,1] op_sel_hi:[1,0]
	v_pk_mul_f32 v[176:177], v[84:85], v[84:85]
	v_pk_mul_f32 v[180:181], v[80:81], v[80:81]
	v_add_f32_e32 v176, v176, v177
	v_add_f32_e32 v166, v166, v167
	v_mov_b32_e32 v115, v180
	v_mov_b32_e32 v119, v181
	v_mov_b32_e32 v177, v178
	v_mov_b32_e32 v167, v179
	v_pk_add_f32 v[114:115], v[114:115], v[118:119]
	v_pk_add_f32 v[118:119], v[176:177], v[166:167]
	s_nop 0
	v_pk_add_f32 v[114:115], v[114:115], v[118:119]
	s_nop 0
	v_add_f32_e32 v113, v114, v115
	ds_bpermute_b32 v114, v164, v113
	s_waitcnt lgkmcnt(0)
	v_add_f32_e32 v113, v113, v114
	ds_bpermute_b32 v114, v165, v113
	s_waitcnt lgkmcnt(0)
	v_add_f32_e32 v113, v113, v114
	v_fmamk_f32 v113, v113, 0x3c800000, v172
	v_rsq_f32_e32 v114, v113
	v_ashrrev_i32_e32 v113, 31, v112
	v_pk_mul_f32 v[84:85], v[84:85], v[114:115] op_sel_hi:[1,0]
	v_pk_mul_f32 v[86:87], v[86:87], v[114:115] op_sel_hi:[1,0]
	v_pk_mul_f32 v[80:81], v[80:81], v[114:115] op_sel_hi:[1,0]
	v_pk_mul_f32 v[94:95], v[94:95], v[114:115] op_sel_hi:[1,0]
	v_pk_mul_f32 v[92:93], v[92:93], v[114:115] op_sel_hi:[1,0]
	v_pk_mul_f32 v[88:89], v[88:89], v[114:115] op_sel_hi:[1,0]
	v_pk_mul_f32 v[86:87], v[122:123], v[86:87]
	v_pk_mul_f32 v[84:85], v[124:125], v[84:85]
	v_pk_mul_f32 v[82:83], v[82:83], v[114:115] op_sel_hi:[1,0]
	v_pk_mul_f32 v[80:81], v[120:121], v[80:81]
	v_pk_mul_f32 v[92:93], v[162:163], v[92:93]
	v_pk_mul_f32 v[94:95], v[130:131], v[94:95]
	v_pk_mul_f32 v[90:91], v[90:91], v[114:115] op_sel_hi:[1,0]
	v_pk_mul_f32 v[88:89], v[160:161], v[88:89]
	v_pk_mul_f32 v[82:83], v[116:117], v[82:83]
	v_pk_mul_f32 v[90:91], v[126:127], v[90:91]
	s_waitcnt vmcnt(3)
	v_pk_mul_f32 v[114:115], v[96:97], v[84:85]
	v_pk_mul_f32 v[118:119], v[98:99], v[86:87]
	s_waitcnt vmcnt(1)
	v_pk_mul_f32 v[166:167], v[104:105], v[80:81]
	v_pk_mul_f32 v[84:85], v[100:101], v[84:85]
	v_pk_mul_f32 v[86:87], v[102:103], v[86:87]
	s_waitcnt vmcnt(0)
	v_pk_mul_f32 v[80:81], v[108:109], v[80:81]
	v_pk_mul_f32 v[176:177], v[106:107], v[82:83]
	v_pk_fma_f32 v[166:167], v[108:109], v[88:89], v[166:167] neg_lo:[0,0,1] neg_hi:[0,0,1]
	v_pk_fma_f32 v[86:87], v[98:99], v[94:95], v[86:87]
	v_pk_fma_f32 v[84:85], v[96:97], v[92:93], v[84:85]
	v_pk_mul_f32 v[82:83], v[110:111], v[82:83]
	v_pk_fma_f32 v[88:89], v[104:105], v[88:89], v[80:81]
	v_pk_fma_f32 v[118:119], v[102:103], v[94:95], v[118:119] neg_lo:[0,0,1] neg_hi:[0,0,1]
	v_pk_fma_f32 v[114:115], v[100:101], v[92:93], v[114:115] neg_lo:[0,0,1] neg_hi:[0,0,1]
	v_pk_fma_f32 v[176:177], v[110:111], v[90:91], v[176:177] neg_lo:[0,0,1] neg_hi:[0,0,1]
	v_pk_fma_f32 v[90:91], v[106:107], v[90:91], v[82:83]
	v_cvt_pk_bf16_f32 v80, v114, v115
	v_cvt_pk_bf16_f32 v81, v118, v119
	v_cvt_pk_bf16_f32 v82, v166, v167
	v_cvt_pk_bf16_f32 v83, v176, v177
	v_cvt_pk_bf16_f32 v84, v84, v85
	v_cvt_pk_bf16_f32 v85, v86, v87
	v_cvt_pk_bf16_f32 v86, v88, v89
	v_lshlrev_b64 v[88:89], 11, v[112:113]
	v_lshl_add_u64 v[88:89], v[128:129], 0, v[88:89]
	v_or_b32_e32 v96, 48, v158
	v_cvt_pk_bf16_f32 v87, v90, v91
	global_store_dwordx4 v[88:89], v[80:83], off
	global_store_dwordx4 v[88:89], v[84:87], off offset:64
	v_pk_mul_f32 v[98:99], v[78:79], v[78:79]
	v_lshlrev_b32_e32 v80, 7, v96
	v_and_b32_e32 v140, 0xfff80, v80
	v_lshl_add_u64 v[88:89], v[148:149], 0, v[140:141]
	v_lshl_add_u64 v[92:93], v[146:147], 0, v[140:141]
	global_load_dwordx4 v[80:83], v[88:89], off
	global_load_dwordx4 v[84:87], v[92:93], off
	s_nop 0
	global_load_dwordx4 v[88:91], v[88:89], off offset:16
	s_nop 0
	global_load_dwordx4 v[92:95], v[92:93], off offset:16
	v_pk_mul_f32 v[100:101], v[76:77], v[76:77]
	v_pk_mul_f32 v[106:107], v[66:67], v[66:67]
	v_pk_mov_b32 v[102:103], v[100:101], v[98:99] op_sel:[1,0]
	v_mov_b32_e32 v101, v99
	v_pk_add_f32 v[98:99], v[102:103], v[100:101]
	v_pk_mul_f32 v[100:101], v[74:75], v[74:75]
	v_pk_mul_f32 v[102:103], v[72:73], v[72:73]
	v_pk_add_f32 v[98:99], v[98:99], v[98:99] op_sel:[0,1] op_sel_hi:[1,0]
	v_pk_mov_b32 v[104:105], v[102:103], v[100:101] op_sel:[1,0]
	v_mov_b32_e32 v103, v101
	v_pk_add_f32 v[100:101], v[104:105], v[102:103]
	v_pk_mul_f32 v[102:103], v[70:71], v[70:71]
	v_pk_add_f32 v[100:101], v[100:101], v[100:101] op_sel:[0,1] op_sel_hi:[1,0]
	v_pk_mul_f32 v[104:105], v[68:69], v[68:69]
	v_pk_mul_f32 v[108:109], v[64:65], v[64:65]
	v_add_f32_e32 v104, v104, v105
	v_add_f32_e32 v102, v102, v103
	v_mov_b32_e32 v99, v108
	v_mov_b32_e32 v101, v109
	v_mov_b32_e32 v105, v106
	v_mov_b32_e32 v103, v107
	v_pk_add_f32 v[98:99], v[98:99], v[100:101]
	v_pk_add_f32 v[100:101], v[104:105], v[102:103]
	s_nop 0
	v_pk_add_f32 v[98:99], v[98:99], v[100:101]
	s_nop 0
	v_add_f32_e32 v97, v98, v99
	ds_bpermute_b32 v98, v164, v97
	s_waitcnt lgkmcnt(0)
	v_add_f32_e32 v97, v97, v98
	ds_bpermute_b32 v98, v165, v97
	s_waitcnt lgkmcnt(0)
	v_add_f32_e32 v97, v97, v98
	v_fmamk_f32 v97, v97, 0x3c800000, v172
	v_rsq_f32_e32 v98, v97
	v_ashrrev_i32_e32 v97, 31, v96
	v_pk_mul_f32 v[68:69], v[68:69], v[98:99] op_sel_hi:[1,0]
	v_pk_mul_f32 v[70:71], v[70:71], v[98:99] op_sel_hi:[1,0]
	v_pk_mul_f32 v[64:65], v[64:65], v[98:99] op_sel_hi:[1,0]
	v_pk_mul_f32 v[78:79], v[78:79], v[98:99] op_sel_hi:[1,0]
	v_pk_mul_f32 v[76:77], v[76:77], v[98:99] op_sel_hi:[1,0]
	v_pk_mul_f32 v[72:73], v[72:73], v[98:99] op_sel_hi:[1,0]
	v_pk_mul_f32 v[70:71], v[122:123], v[70:71]
	v_pk_mul_f32 v[68:69], v[124:125], v[68:69]
	v_pk_mul_f32 v[66:67], v[66:67], v[98:99] op_sel_hi:[1,0]
	v_pk_mul_f32 v[64:65], v[120:121], v[64:65]
	v_pk_mul_f32 v[76:77], v[162:163], v[76:77]
	v_pk_mul_f32 v[78:79], v[130:131], v[78:79]
	v_pk_mul_f32 v[74:75], v[74:75], v[98:99] op_sel_hi:[1,0]
	v_pk_mul_f32 v[72:73], v[160:161], v[72:73]
	v_pk_mul_f32 v[66:67], v[116:117], v[66:67]
	v_pk_mul_f32 v[74:75], v[126:127], v[74:75]
	s_waitcnt vmcnt(3)
	v_pk_mul_f32 v[98:99], v[80:81], v[68:69]
	v_pk_mul_f32 v[100:101], v[82:83], v[70:71]
	s_waitcnt vmcnt(1)
	v_pk_mul_f32 v[102:103], v[88:89], v[64:65]
	v_pk_mul_f32 v[68:69], v[84:85], v[68:69]
	v_pk_mul_f32 v[70:71], v[86:87], v[70:71]
	s_waitcnt vmcnt(0)
	v_pk_mul_f32 v[64:65], v[92:93], v[64:65]
	v_pk_mul_f32 v[104:105], v[90:91], v[66:67]
	v_pk_fma_f32 v[102:103], v[92:93], v[72:73], v[102:103] neg_lo:[0,0,1] neg_hi:[0,0,1]
	v_pk_fma_f32 v[70:71], v[82:83], v[78:79], v[70:71]
	v_pk_fma_f32 v[68:69], v[80:81], v[76:77], v[68:69]
	v_pk_mul_f32 v[66:67], v[94:95], v[66:67]
	v_pk_fma_f32 v[72:73], v[88:89], v[72:73], v[64:65]
	v_pk_fma_f32 v[100:101], v[86:87], v[78:79], v[100:101] neg_lo:[0,0,1] neg_hi:[0,0,1]
	v_pk_fma_f32 v[98:99], v[84:85], v[76:77], v[98:99] neg_lo:[0,0,1] neg_hi:[0,0,1]
	v_pk_fma_f32 v[104:105], v[94:95], v[74:75], v[104:105] neg_lo:[0,0,1] neg_hi:[0,0,1]
	v_pk_fma_f32 v[74:75], v[90:91], v[74:75], v[66:67]
	v_cvt_pk_bf16_f32 v64, v98, v99
	v_cvt_pk_bf16_f32 v65, v100, v101
	v_cvt_pk_bf16_f32 v66, v102, v103
	v_cvt_pk_bf16_f32 v67, v104, v105
	v_cvt_pk_bf16_f32 v68, v68, v69
	v_cvt_pk_bf16_f32 v69, v70, v71
	v_cvt_pk_bf16_f32 v70, v72, v73
	v_lshlrev_b64 v[72:73], 11, v[96:97]
	v_lshl_add_u64 v[72:73], v[128:129], 0, v[72:73]
	v_add_u32_e32 v80, 0x80, v158
	v_cvt_pk_bf16_f32 v71, v74, v75
	global_store_dwordx4 v[72:73], v[64:67], off
	global_store_dwordx4 v[72:73], v[68:71], off offset:64
	v_pk_mul_f32 v[82:83], v[62:63], v[62:63]
	v_lshlrev_b32_e32 v64, 7, v80
	v_and_b32_e32 v140, 0xfe780, v64
	v_lshl_add_u64 v[72:73], v[148:149], 0, v[140:141]
	v_lshl_add_u64 v[76:77], v[146:147], 0, v[140:141]
	global_load_dwordx4 v[64:67], v[72:73], off
	global_load_dwordx4 v[68:71], v[76:77], off
	s_nop 0
	global_load_dwordx4 v[72:75], v[72:73], off offset:16
	s_nop 0
	global_load_dwordx4 v[76:79], v[76:77], off offset:16
	v_pk_mul_f32 v[84:85], v[60:61], v[60:61]
	v_pk_mul_f32 v[90:91], v[50:51], v[50:51]
	v_pk_mov_b32 v[86:87], v[84:85], v[82:83] op_sel:[1,0]
	v_mov_b32_e32 v85, v83
	v_pk_add_f32 v[82:83], v[86:87], v[84:85]
	v_pk_mul_f32 v[84:85], v[58:59], v[58:59]
	v_pk_mul_f32 v[86:87], v[56:57], v[56:57]
	v_pk_add_f32 v[82:83], v[82:83], v[82:83] op_sel:[0,1] op_sel_hi:[1,0]
	v_pk_mov_b32 v[88:89], v[86:87], v[84:85] op_sel:[1,0]
	v_mov_b32_e32 v87, v85
	v_pk_add_f32 v[84:85], v[88:89], v[86:87]
	v_pk_mul_f32 v[86:87], v[54:55], v[54:55]
	v_pk_add_f32 v[84:85], v[84:85], v[84:85] op_sel:[0,1] op_sel_hi:[1,0]
	v_pk_mul_f32 v[88:89], v[52:53], v[52:53]
	v_pk_mul_f32 v[92:93], v[48:49], v[48:49]
	v_add_f32_e32 v88, v88, v89
	v_add_f32_e32 v86, v86, v87
	v_mov_b32_e32 v83, v92
	v_mov_b32_e32 v85, v93
	v_mov_b32_e32 v89, v90
	v_mov_b32_e32 v87, v91
	v_pk_add_f32 v[82:83], v[82:83], v[84:85]
	v_pk_add_f32 v[84:85], v[88:89], v[86:87]
	s_nop 0
	v_pk_add_f32 v[82:83], v[82:83], v[84:85]
	s_nop 0
	v_add_f32_e32 v81, v82, v83
	ds_bpermute_b32 v82, v164, v81
	s_waitcnt lgkmcnt(0)
	v_add_f32_e32 v81, v81, v82
	ds_bpermute_b32 v82, v165, v81
	s_waitcnt lgkmcnt(0)
	v_add_f32_e32 v81, v81, v82
	v_fmamk_f32 v81, v81, 0x3c800000, v172
	v_rsq_f32_e32 v82, v81
	v_ashrrev_i32_e32 v81, 31, v80
	v_pk_mul_f32 v[52:53], v[52:53], v[82:83] op_sel_hi:[1,0]
	v_pk_mul_f32 v[54:55], v[54:55], v[82:83] op_sel_hi:[1,0]
	v_pk_mul_f32 v[48:49], v[48:49], v[82:83] op_sel_hi:[1,0]
	v_pk_mul_f32 v[62:63], v[62:63], v[82:83] op_sel_hi:[1,0]
	v_pk_mul_f32 v[60:61], v[60:61], v[82:83] op_sel_hi:[1,0]
	v_pk_mul_f32 v[56:57], v[56:57], v[82:83] op_sel_hi:[1,0]
	v_pk_mul_f32 v[54:55], v[122:123], v[54:55]
	v_pk_mul_f32 v[52:53], v[124:125], v[52:53]
	v_pk_mul_f32 v[50:51], v[50:51], v[82:83] op_sel_hi:[1,0]
	v_pk_mul_f32 v[48:49], v[120:121], v[48:49]
	v_pk_mul_f32 v[60:61], v[162:163], v[60:61]
	v_pk_mul_f32 v[62:63], v[130:131], v[62:63]
	v_pk_mul_f32 v[58:59], v[58:59], v[82:83] op_sel_hi:[1,0]
	v_pk_mul_f32 v[56:57], v[160:161], v[56:57]
	v_pk_mul_f32 v[50:51], v[116:117], v[50:51]
	v_pk_mul_f32 v[58:59], v[126:127], v[58:59]
	s_waitcnt vmcnt(3)
	v_pk_mul_f32 v[82:83], v[64:65], v[52:53]
	v_pk_mul_f32 v[84:85], v[66:67], v[54:55]
	s_waitcnt vmcnt(1)
	v_pk_mul_f32 v[86:87], v[72:73], v[48:49]
	v_pk_mul_f32 v[52:53], v[68:69], v[52:53]
	v_pk_mul_f32 v[54:55], v[70:71], v[54:55]
	s_waitcnt vmcnt(0)
	v_pk_mul_f32 v[48:49], v[76:77], v[48:49]
	v_pk_mul_f32 v[88:89], v[74:75], v[50:51]
	v_pk_fma_f32 v[86:87], v[76:77], v[56:57], v[86:87] neg_lo:[0,0,1] neg_hi:[0,0,1]
	v_pk_fma_f32 v[54:55], v[66:67], v[62:63], v[54:55]
	v_pk_fma_f32 v[52:53], v[64:65], v[60:61], v[52:53]
	v_pk_mul_f32 v[50:51], v[78:79], v[50:51]
	v_pk_fma_f32 v[56:57], v[72:73], v[56:57], v[48:49]
	v_pk_fma_f32 v[84:85], v[70:71], v[62:63], v[84:85] neg_lo:[0,0,1] neg_hi:[0,0,1]
	v_pk_fma_f32 v[82:83], v[68:69], v[60:61], v[82:83] neg_lo:[0,0,1] neg_hi:[0,0,1]
	v_pk_fma_f32 v[88:89], v[78:79], v[58:59], v[88:89] neg_lo:[0,0,1] neg_hi:[0,0,1]
	v_pk_fma_f32 v[58:59], v[74:75], v[58:59], v[50:51]
	v_cvt_pk_bf16_f32 v48, v82, v83
	v_cvt_pk_bf16_f32 v49, v84, v85
	v_cvt_pk_bf16_f32 v50, v86, v87
	v_cvt_pk_bf16_f32 v51, v88, v89
	v_cvt_pk_bf16_f32 v52, v52, v53
	v_cvt_pk_bf16_f32 v53, v54, v55
	v_cvt_pk_bf16_f32 v54, v56, v57
	v_lshlrev_b64 v[56:57], 11, v[80:81]
	v_lshl_add_u64 v[56:57], v[128:129], 0, v[56:57]
	v_add_u32_e32 v64, 0x90, v158
	v_cvt_pk_bf16_f32 v55, v58, v59
	global_store_dwordx4 v[56:57], v[48:51], off
	global_store_dwordx4 v[56:57], v[52:55], off offset:64
	v_pk_mul_f32 v[66:67], v[46:47], v[46:47]
	v_lshlrev_b32_e32 v48, 7, v64
	v_and_b32_e32 v140, 0xfef80, v48
	v_lshl_add_u64 v[56:57], v[148:149], 0, v[140:141]
	v_lshl_add_u64 v[60:61], v[146:147], 0, v[140:141]
	global_load_dwordx4 v[48:51], v[56:57], off
	global_load_dwordx4 v[52:55], v[60:61], off
	s_nop 0
	global_load_dwordx4 v[56:59], v[56:57], off offset:16
	s_nop 0
	global_load_dwordx4 v[60:63], v[60:61], off offset:16
	v_pk_mul_f32 v[68:69], v[44:45], v[44:45]
	v_pk_mul_f32 v[74:75], v[34:35], v[34:35]
	v_pk_mov_b32 v[70:71], v[68:69], v[66:67] op_sel:[1,0]
	v_mov_b32_e32 v69, v67
	v_pk_add_f32 v[66:67], v[70:71], v[68:69]
	v_pk_mul_f32 v[68:69], v[42:43], v[42:43]
	v_pk_mul_f32 v[70:71], v[40:41], v[40:41]
	v_pk_add_f32 v[66:67], v[66:67], v[66:67] op_sel:[0,1] op_sel_hi:[1,0]
	v_pk_mov_b32 v[72:73], v[70:71], v[68:69] op_sel:[1,0]
	v_mov_b32_e32 v71, v69
	v_pk_add_f32 v[68:69], v[72:73], v[70:71]
	v_pk_mul_f32 v[70:71], v[38:39], v[38:39]
	v_pk_add_f32 v[68:69], v[68:69], v[68:69] op_sel:[0,1] op_sel_hi:[1,0]
	v_pk_mul_f32 v[72:73], v[36:37], v[36:37]
	v_pk_mul_f32 v[76:77], v[32:33], v[32:33]
	v_add_f32_e32 v72, v72, v73
	v_add_f32_e32 v70, v70, v71
	v_mov_b32_e32 v67, v76
	v_mov_b32_e32 v69, v77
	v_mov_b32_e32 v73, v74
	v_mov_b32_e32 v71, v75
	v_pk_add_f32 v[66:67], v[66:67], v[68:69]
	v_pk_add_f32 v[68:69], v[72:73], v[70:71]
	s_nop 0
	v_pk_add_f32 v[66:67], v[66:67], v[68:69]
	s_nop 0
	v_add_f32_e32 v65, v66, v67
	ds_bpermute_b32 v66, v164, v65
	s_waitcnt lgkmcnt(0)
	v_add_f32_e32 v65, v65, v66
	ds_bpermute_b32 v66, v165, v65
	s_waitcnt lgkmcnt(0)
	v_add_f32_e32 v65, v65, v66
	v_fmamk_f32 v65, v65, 0x3c800000, v172
	v_rsq_f32_e32 v66, v65
	v_ashrrev_i32_e32 v65, 31, v64
	v_pk_mul_f32 v[36:37], v[36:37], v[66:67] op_sel_hi:[1,0]
	v_pk_mul_f32 v[38:39], v[38:39], v[66:67] op_sel_hi:[1,0]
	v_pk_mul_f32 v[32:33], v[32:33], v[66:67] op_sel_hi:[1,0]
	v_pk_mul_f32 v[46:47], v[46:47], v[66:67] op_sel_hi:[1,0]
	v_pk_mul_f32 v[44:45], v[44:45], v[66:67] op_sel_hi:[1,0]
	v_pk_mul_f32 v[40:41], v[40:41], v[66:67] op_sel_hi:[1,0]
	v_pk_mul_f32 v[38:39], v[122:123], v[38:39]
	v_pk_mul_f32 v[36:37], v[124:125], v[36:37]
	v_pk_mul_f32 v[34:35], v[34:35], v[66:67] op_sel_hi:[1,0]
	v_pk_mul_f32 v[32:33], v[120:121], v[32:33]
	v_pk_mul_f32 v[44:45], v[162:163], v[44:45]
	v_pk_mul_f32 v[46:47], v[130:131], v[46:47]
	v_pk_mul_f32 v[42:43], v[42:43], v[66:67] op_sel_hi:[1,0]
	v_pk_mul_f32 v[40:41], v[160:161], v[40:41]
	v_pk_mul_f32 v[34:35], v[116:117], v[34:35]
	v_pk_mul_f32 v[42:43], v[126:127], v[42:43]
	s_waitcnt vmcnt(3)
	v_pk_mul_f32 v[66:67], v[48:49], v[36:37]
	v_pk_mul_f32 v[68:69], v[50:51], v[38:39]
	s_waitcnt vmcnt(1)
	v_pk_mul_f32 v[70:71], v[56:57], v[32:33]
	v_pk_mul_f32 v[36:37], v[52:53], v[36:37]
	v_pk_mul_f32 v[38:39], v[54:55], v[38:39]
	s_waitcnt vmcnt(0)
	v_pk_mul_f32 v[32:33], v[60:61], v[32:33]
	v_pk_mul_f32 v[72:73], v[58:59], v[34:35]
	v_pk_fma_f32 v[70:71], v[60:61], v[40:41], v[70:71] neg_lo:[0,0,1] neg_hi:[0,0,1]
	v_pk_fma_f32 v[38:39], v[50:51], v[46:47], v[38:39]
	v_pk_fma_f32 v[36:37], v[48:49], v[44:45], v[36:37]
	v_pk_mul_f32 v[34:35], v[62:63], v[34:35]
	v_pk_fma_f32 v[40:41], v[56:57], v[40:41], v[32:33]
	v_pk_fma_f32 v[68:69], v[54:55], v[46:47], v[68:69] neg_lo:[0,0,1] neg_hi:[0,0,1]
	v_pk_fma_f32 v[66:67], v[52:53], v[44:45], v[66:67] neg_lo:[0,0,1] neg_hi:[0,0,1]
	v_pk_fma_f32 v[72:73], v[62:63], v[42:43], v[72:73] neg_lo:[0,0,1] neg_hi:[0,0,1]
	v_pk_fma_f32 v[42:43], v[58:59], v[42:43], v[34:35]
	v_cvt_pk_bf16_f32 v32, v66, v67
	v_cvt_pk_bf16_f32 v33, v68, v69
	v_cvt_pk_bf16_f32 v34, v70, v71
	v_cvt_pk_bf16_f32 v35, v72, v73
	v_cvt_pk_bf16_f32 v36, v36, v37
	v_cvt_pk_bf16_f32 v37, v38, v39
	v_cvt_pk_bf16_f32 v38, v40, v41
	v_lshlrev_b64 v[40:41], 11, v[64:65]
	v_lshl_add_u64 v[40:41], v[128:129], 0, v[40:41]
	v_add_u32_e32 v48, 0xa0, v158
	v_cvt_pk_bf16_f32 v39, v42, v43
	global_store_dwordx4 v[40:41], v[32:35], off
	global_store_dwordx4 v[40:41], v[36:39], off offset:64
	v_pk_mul_f32 v[50:51], v[30:31], v[30:31]
	v_lshlrev_b32_e32 v32, 7, v48
	v_and_b32_e32 v140, 0xff780, v32
	v_lshl_add_u64 v[40:41], v[148:149], 0, v[140:141]
	v_lshl_add_u64 v[44:45], v[146:147], 0, v[140:141]
	global_load_dwordx4 v[32:35], v[40:41], off
	global_load_dwordx4 v[36:39], v[44:45], off
	s_nop 0
	global_load_dwordx4 v[40:43], v[40:41], off offset:16
	s_nop 0
	global_load_dwordx4 v[44:47], v[44:45], off offset:16
	v_pk_mul_f32 v[52:53], v[28:29], v[28:29]
	v_pk_mul_f32 v[58:59], v[18:19], v[18:19]
	v_pk_mov_b32 v[54:55], v[52:53], v[50:51] op_sel:[1,0]
	v_mov_b32_e32 v53, v51
	v_pk_add_f32 v[50:51], v[54:55], v[52:53]
	v_pk_mul_f32 v[52:53], v[26:27], v[26:27]
	v_pk_mul_f32 v[54:55], v[24:25], v[24:25]
	v_pk_add_f32 v[50:51], v[50:51], v[50:51] op_sel:[0,1] op_sel_hi:[1,0]
	v_pk_mov_b32 v[56:57], v[54:55], v[52:53] op_sel:[1,0]
	v_mov_b32_e32 v55, v53
	v_pk_add_f32 v[52:53], v[56:57], v[54:55]
	v_pk_mul_f32 v[54:55], v[22:23], v[22:23]
	v_pk_add_f32 v[52:53], v[52:53], v[52:53] op_sel:[0,1] op_sel_hi:[1,0]
	v_pk_mul_f32 v[56:57], v[20:21], v[20:21]
	v_pk_mul_f32 v[60:61], v[16:17], v[16:17]
	v_add_f32_e32 v56, v56, v57
	v_add_f32_e32 v54, v54, v55
	v_mov_b32_e32 v51, v60
	v_mov_b32_e32 v53, v61
	v_mov_b32_e32 v57, v58
	v_mov_b32_e32 v55, v59
	v_pk_add_f32 v[50:51], v[50:51], v[52:53]
	v_pk_add_f32 v[52:53], v[56:57], v[54:55]
	s_nop 0
	v_pk_add_f32 v[50:51], v[50:51], v[52:53]
	s_nop 0
	v_add_f32_e32 v49, v50, v51
	ds_bpermute_b32 v50, v164, v49
	s_waitcnt lgkmcnt(0)
	v_add_f32_e32 v49, v49, v50
	ds_bpermute_b32 v50, v165, v49
	s_waitcnt lgkmcnt(0)
	v_add_f32_e32 v49, v49, v50
	v_fmamk_f32 v49, v49, 0x3c800000, v172
	v_rsq_f32_e32 v50, v49
	v_ashrrev_i32_e32 v49, 31, v48
	v_pk_mul_f32 v[20:21], v[20:21], v[50:51] op_sel_hi:[1,0]
	v_pk_mul_f32 v[22:23], v[22:23], v[50:51] op_sel_hi:[1,0]
	v_pk_mul_f32 v[16:17], v[16:17], v[50:51] op_sel_hi:[1,0]
	v_pk_mul_f32 v[30:31], v[30:31], v[50:51] op_sel_hi:[1,0]
	v_pk_mul_f32 v[28:29], v[28:29], v[50:51] op_sel_hi:[1,0]
	v_pk_mul_f32 v[24:25], v[24:25], v[50:51] op_sel_hi:[1,0]
	v_pk_mul_f32 v[22:23], v[122:123], v[22:23]
	v_pk_mul_f32 v[20:21], v[124:125], v[20:21]
	v_pk_mul_f32 v[18:19], v[18:19], v[50:51] op_sel_hi:[1,0]
	v_pk_mul_f32 v[16:17], v[120:121], v[16:17]
	v_pk_mul_f32 v[28:29], v[162:163], v[28:29]
	v_pk_mul_f32 v[30:31], v[130:131], v[30:31]
	v_pk_mul_f32 v[26:27], v[26:27], v[50:51] op_sel_hi:[1,0]
	v_pk_mul_f32 v[24:25], v[160:161], v[24:25]
	v_pk_mul_f32 v[18:19], v[116:117], v[18:19]
	v_pk_mul_f32 v[26:27], v[126:127], v[26:27]
	s_waitcnt vmcnt(3)
	v_pk_mul_f32 v[50:51], v[32:33], v[20:21]
	v_pk_mul_f32 v[52:53], v[34:35], v[22:23]
	s_waitcnt vmcnt(1)
	v_pk_mul_f32 v[54:55], v[40:41], v[16:17]
	v_pk_mul_f32 v[20:21], v[36:37], v[20:21]
	v_pk_mul_f32 v[22:23], v[38:39], v[22:23]
	s_waitcnt vmcnt(0)
	v_pk_mul_f32 v[16:17], v[44:45], v[16:17]
	v_pk_mul_f32 v[56:57], v[42:43], v[18:19]
	v_pk_fma_f32 v[54:55], v[44:45], v[24:25], v[54:55] neg_lo:[0,0,1] neg_hi:[0,0,1]
	v_pk_fma_f32 v[22:23], v[34:35], v[30:31], v[22:23]
	v_pk_fma_f32 v[20:21], v[32:33], v[28:29], v[20:21]
	v_pk_mul_f32 v[18:19], v[46:47], v[18:19]
	v_pk_fma_f32 v[24:25], v[40:41], v[24:25], v[16:17]
	v_pk_fma_f32 v[52:53], v[38:39], v[30:31], v[52:53] neg_lo:[0,0,1] neg_hi:[0,0,1]
	v_pk_fma_f32 v[50:51], v[36:37], v[28:29], v[50:51] neg_lo:[0,0,1] neg_hi:[0,0,1]
	v_pk_fma_f32 v[56:57], v[46:47], v[26:27], v[56:57] neg_lo:[0,0,1] neg_hi:[0,0,1]
	v_pk_fma_f32 v[26:27], v[42:43], v[26:27], v[18:19]
	v_cvt_pk_bf16_f32 v16, v50, v51
	v_cvt_pk_bf16_f32 v17, v52, v53
	v_cvt_pk_bf16_f32 v18, v54, v55
	v_cvt_pk_bf16_f32 v19, v56, v57
	v_cvt_pk_bf16_f32 v20, v20, v21
	v_cvt_pk_bf16_f32 v21, v22, v23
	v_cvt_pk_bf16_f32 v22, v24, v25
	v_lshlrev_b64 v[24:25], 11, v[48:49]
	v_lshl_add_u64 v[24:25], v[128:129], 0, v[24:25]
	v_add_u32_e32 v32, 0xb0, v158
	v_cvt_pk_bf16_f32 v23, v26, v27
	global_store_dwordx4 v[24:25], v[16:19], off
	global_store_dwordx4 v[24:25], v[20:23], off offset:64
	v_pk_mul_f32 v[34:35], v[14:15], v[14:15]
	v_lshlrev_b32_e32 v16, 7, v32
	v_and_b32_e32 v140, 0xfff80, v16
	v_lshl_add_u64 v[24:25], v[148:149], 0, v[140:141]
	v_lshl_add_u64 v[28:29], v[146:147], 0, v[140:141]
	global_load_dwordx4 v[16:19], v[24:25], off
	global_load_dwordx4 v[20:23], v[28:29], off
	s_nop 0
	global_load_dwordx4 v[24:27], v[24:25], off offset:16
	s_nop 0
	global_load_dwordx4 v[28:31], v[28:29], off offset:16
	v_pk_mul_f32 v[36:37], v[12:13], v[12:13]
	v_pk_mul_f32 v[42:43], v[2:3], v[2:3]
	v_pk_mov_b32 v[38:39], v[36:37], v[34:35] op_sel:[1,0]
	v_mov_b32_e32 v37, v35
	v_pk_add_f32 v[34:35], v[38:39], v[36:37]
	v_pk_mul_f32 v[36:37], v[10:11], v[10:11]
	v_pk_mul_f32 v[38:39], v[8:9], v[8:9]
	v_pk_add_f32 v[34:35], v[34:35], v[34:35] op_sel:[0,1] op_sel_hi:[1,0]
	v_pk_mov_b32 v[40:41], v[38:39], v[36:37] op_sel:[1,0]
	v_mov_b32_e32 v39, v37
	v_pk_add_f32 v[36:37], v[40:41], v[38:39]
	v_pk_mul_f32 v[38:39], v[6:7], v[6:7]
	v_pk_add_f32 v[36:37], v[36:37], v[36:37] op_sel:[0,1] op_sel_hi:[1,0]
	v_pk_mul_f32 v[40:41], v[4:5], v[4:5]
	v_pk_mul_f32 v[44:45], v[0:1], v[0:1]
	v_add_f32_e32 v40, v40, v41
	v_add_f32_e32 v38, v38, v39
	v_mov_b32_e32 v35, v44
	v_mov_b32_e32 v37, v45
	v_mov_b32_e32 v41, v42
	v_mov_b32_e32 v39, v43
	v_pk_add_f32 v[34:35], v[34:35], v[36:37]
	v_pk_add_f32 v[36:37], v[40:41], v[38:39]
	s_nop 0
	v_pk_add_f32 v[34:35], v[34:35], v[36:37]
	s_nop 0
	v_add_f32_e32 v33, v34, v35
	ds_bpermute_b32 v34, v164, v33
	s_waitcnt lgkmcnt(0)
	v_add_f32_e32 v33, v33, v34
	ds_bpermute_b32 v34, v165, v33
	s_waitcnt lgkmcnt(0)
	v_add_f32_e32 v33, v33, v34
	v_fmamk_f32 v33, v33, 0x3c800000, v172
	v_rsq_f32_e32 v34, v33
	v_ashrrev_i32_e32 v33, 31, v32
	v_pk_mul_f32 v[4:5], v[4:5], v[34:35] op_sel_hi:[1,0]
	v_pk_mul_f32 v[6:7], v[6:7], v[34:35] op_sel_hi:[1,0]
	v_pk_mul_f32 v[0:1], v[0:1], v[34:35] op_sel_hi:[1,0]
	v_pk_mul_f32 v[14:15], v[14:15], v[34:35] op_sel_hi:[1,0]
	v_pk_mul_f32 v[12:13], v[12:13], v[34:35] op_sel_hi:[1,0]
	v_pk_mul_f32 v[8:9], v[8:9], v[34:35] op_sel_hi:[1,0]
	v_pk_mul_f32 v[6:7], v[122:123], v[6:7]
	v_pk_mul_f32 v[4:5], v[124:125], v[4:5]
	v_pk_mul_f32 v[2:3], v[2:3], v[34:35] op_sel_hi:[1,0]
	v_pk_mul_f32 v[0:1], v[120:121], v[0:1]
	v_pk_mul_f32 v[12:13], v[162:163], v[12:13]
	v_pk_mul_f32 v[14:15], v[130:131], v[14:15]
	v_pk_mul_f32 v[10:11], v[10:11], v[34:35] op_sel_hi:[1,0]
	v_pk_mul_f32 v[8:9], v[160:161], v[8:9]
	v_pk_mul_f32 v[2:3], v[116:117], v[2:3]
	v_pk_mul_f32 v[10:11], v[126:127], v[10:11]
	s_waitcnt vmcnt(3)
	v_pk_mul_f32 v[34:35], v[16:17], v[4:5]
	v_pk_mul_f32 v[36:37], v[18:19], v[6:7]
	s_waitcnt vmcnt(1)
	v_pk_mul_f32 v[38:39], v[24:25], v[0:1]
	v_pk_mul_f32 v[4:5], v[20:21], v[4:5]
	v_pk_mul_f32 v[6:7], v[22:23], v[6:7]
	s_waitcnt vmcnt(0)
	v_pk_mul_f32 v[0:1], v[28:29], v[0:1]
	v_pk_mul_f32 v[40:41], v[26:27], v[2:3]
	v_pk_fma_f32 v[38:39], v[28:29], v[8:9], v[38:39] neg_lo:[0,0,1] neg_hi:[0,0,1]
	v_pk_fma_f32 v[6:7], v[18:19], v[14:15], v[6:7]
	v_pk_fma_f32 v[4:5], v[16:17], v[12:13], v[4:5]
	v_pk_mul_f32 v[2:3], v[30:31], v[2:3]
	v_pk_fma_f32 v[8:9], v[24:25], v[8:9], v[0:1]
	v_pk_fma_f32 v[36:37], v[22:23], v[14:15], v[36:37] neg_lo:[0,0,1] neg_hi:[0,0,1]
	v_pk_fma_f32 v[34:35], v[20:21], v[12:13], v[34:35] neg_lo:[0,0,1] neg_hi:[0,0,1]
	v_pk_fma_f32 v[40:41], v[30:31], v[10:11], v[40:41] neg_lo:[0,0,1] neg_hi:[0,0,1]
	v_pk_fma_f32 v[10:11], v[26:27], v[10:11], v[2:3]
	v_cvt_pk_bf16_f32 v0, v34, v35
	v_cvt_pk_bf16_f32 v1, v36, v37
	v_cvt_pk_bf16_f32 v2, v38, v39
	v_cvt_pk_bf16_f32 v3, v40, v41
	v_cvt_pk_bf16_f32 v4, v4, v5
	v_cvt_pk_bf16_f32 v5, v6, v7
	v_cvt_pk_bf16_f32 v6, v8, v9
	v_lshlrev_b64 v[8:9], 11, v[32:33]
	v_lshl_add_u64 v[8:9], v[128:129], 0, v[8:9]
	v_cvt_pk_bf16_f32 v7, v10, v11
	global_store_dwordx4 v[8:9], v[0:3], off
	global_store_dwordx4 v[8:9], v[4:7], off offset:64
	s_andn2_b64 vcc, exec, s[4:5]
	s_mov_b64 s[4:5], -1
	s_cbranch_vccnz .LBB0_262
	s_branch .LBB0_562
.LBB0_561:
	s_andn2_b64 vcc, exec, s[4:5]
	s_mov_b64 s[4:5], -1
	s_cbranch_vccnz .LBB0_262

.Lmy_t_last:
.Lmy_t_done:
	s_cmp_lg_u32 0, -1
	s_cselect_b32 s0, 0, 0
	s_addk_i32 s0, 0x6000
	v_add3_u32 v65, v247, s0, v245
	v_add_u32_e32 v66, s76, v248
	ds_read_b64_tr_b16 v[208:209], v66 offset:24576
	ds_read_b64_tr_b16 v[210:211], v66 offset:25088
	v_add_f32_e32 v67, v96, v97
	v_add_f32_e32 v67, v98, v67
	v_add_f32_e32 v67, v99, v67
	v_add_f32_e32 v67, v100, v67
	v_add_f32_e32 v67, v101, v67
	v_cvt_pk_bf16_f32 v160, v96, v97
	v_cvt_pk_bf16_f32 v161, v98, v99
	s_waitcnt lgkmcnt(9)
	v_mfma_f32_32x32x16_bf16 v[112:127], v[204:207], v[172:175], 0
	ds_read_b64_tr_b16 v[204:205], v66 offset:28672
	ds_read_b64_tr_b16 v[206:207], v66 offset:29184
	v_add_f32_e32 v67, v102, v67
	v_add_f32_e32 v67, v103, v67
	v_add_f32_e32 v67, v104, v67
	v_add_f32_e32 v67, v105, v67
	v_cvt_pk_bf16_f32 v162, v100, v101
	v_cvt_pk_bf16_f32 v163, v102, v103
	s_waitcnt lgkmcnt(10)
	v_mfma_f32_32x32x16_bf16 v[128:143], v[200:203], v[172:175], 0
	ds_read_b64_tr_b16 v[98:99], v66 offset:25600
	ds_read_b64_tr_b16 v[100:101], v66 offset:26112
	v_add_f32_e32 v67, v106, v67
	v_add_f32_e32 v67, v107, v67
	v_add_f32_e32 v67, v108, v67
	v_add_f32_e32 v67, v109, v67
	v_cvt_pk_bf16_f32 v152, v104, v105
	v_cvt_pk_bf16_f32 v153, v106, v107
	s_waitcnt lgkmcnt(11)
	v_mfma_f32_32x32x16_bf16 v[112:127], v[196:199], v[168:171], v[112:127]
	ds_read_b64_tr_b16 v[102:103], v66 offset:29696
	ds_read_b64_tr_b16 v[104:105], v66 offset:30208
	v_add_f32_e32 v67, v110, v67
	v_add_f32_e32 v67, v111, v67
	v_add_f32_e32 v67, v80, v67
	v_add_f32_e32 v67, v81, v67
	v_cvt_pk_bf16_f32 v154, v108, v109
	v_cvt_pk_bf16_f32 v155, v110, v111
	s_waitcnt lgkmcnt(12)
	v_mfma_f32_32x32x16_bf16 v[128:143], v[192:195], v[168:171], v[128:143]
	ds_read_b64_tr_b16 v[106:107], v66 offset:26624
	ds_read_b64_tr_b16 v[108:109], v66 offset:27136
	v_add_f32_e32 v67, v82, v67
	v_add_f32_e32 v67, v83, v67
	v_add_f32_e32 v67, v84, v67
	v_add_f32_e32 v67, v85, v67
	v_cvt_pk_bf16_f32 v148, v80, v81
	v_cvt_pk_bf16_f32 v149, v82, v83
	s_waitcnt lgkmcnt(13)
	v_mfma_f32_32x32x16_bf16 v[112:127], v[188:191], v[164:167], v[112:127]
	ds_read_b64_tr_b16 v[168:169], v66 offset:30720
	ds_read_b64_tr_b16 v[170:171], v66 offset:31232
	v_add_f32_e32 v67, v86, v67
	v_add_f32_e32 v67, v87, v67
	v_add_f32_e32 v67, v88, v67
	v_add_f32_e32 v67, v89, v67
	v_cvt_pk_bf16_f32 v150, v84, v85
	v_cvt_pk_bf16_f32 v151, v86, v87
	s_waitcnt lgkmcnt(14)
	v_mfma_f32_32x32x16_bf16 v[128:143], v[184:187], v[164:167], v[128:143]
	ds_read_b64_tr_b16 v[164:165], v66 offset:27648
	ds_read_b64_tr_b16 v[166:167], v66 offset:28160
	v_add_f32_e32 v67, v90, v67
	v_add_f32_e32 v67, v91, v67
	v_add_f32_e32 v67, v92, v67
	v_add_f32_e32 v67, v93, v67
	v_cvt_pk_bf16_f32 v144, v88, v89
	v_cvt_pk_bf16_f32 v145, v90, v91
	s_waitcnt lgkmcnt(14)
	v_mfma_f32_32x32x16_bf16 v[112:127], v[180:183], v[156:159], v[112:127]
	ds_read_b64_tr_b16 v[172:173], v66 offset:31744
	ds_read_b64_tr_b16 v[174:175], v66 offset:32256
	v_add_f32_e32 v67, v94, v67
	v_add_f32_e32 v67, v95, v67
	v_add_f32_e32 v180, 0, v67
	v_cvt_pk_bf16_f32 v146, v92, v93
	v_cvt_pk_bf16_f32 v147, v94, v95
	v_mfma_f32_32x32x16_bf16 v[128:143], v[176:179], v[156:159], v[128:143]
	s_nop 3
	v_cndmask_b32_e64 v97, v127, v236, s[4:5]
	v_cndmask_b32_e64 v96, v126, v236, s[4:5]
	v_cndmask_b32_e64 v95, v125, v236, s[4:5]
	v_cndmask_b32_e64 v94, v124, v236, s[4:5]
	v_cndmask_b32_e64 v93, v123, v236, s[4:5]
	v_cndmask_b32_e64 v92, v122, v236, s[4:5]
	v_cndmask_b32_e64 v91, v121, v236, s[4:5]
	v_cndmask_b32_e64 v90, v120, v236, s[4:5]
	v_cndmask_b32_e64 v89, v119, v236, s[4:5]
	v_cndmask_b32_e64 v88, v118, v236, s[4:5]
	v_cndmask_b32_e64 v87, v117, v236, s[4:5]
	v_cndmask_b32_e64 v86, v116, v236, s[4:5]
	v_cndmask_b32_e64 v85, v115, v236, s[4:5]
	v_cndmask_b32_e64 v84, v114, v236, s[4:5]
	v_cndmask_b32_e64 v67, v113, v236, s[4:5]
	v_cndmask_b32_e64 v82, v112, v236, s[4:5]
	v_cndmask_b32_e64 v81, v143, v236, s[4:5]
	v_cndmask_b32_e64 v80, v142, v236, s[4:5]
	v_cndmask_b32_e64 v79, v141, v236, s[4:5]
	v_cndmask_b32_e64 v78, v140, v236, s[4:5]
	v_cndmask_b32_e64 v77, v139, v236, s[4:5]
	v_cndmask_b32_e64 v76, v138, v236, s[4:5]
	v_cndmask_b32_e64 v75, v137, v236, s[4:5]
	v_cndmask_b32_e64 v74, v136, v236, s[4:5]
	v_cndmask_b32_e64 v73, v135, v236, s[4:5]
	v_cndmask_b32_e64 v72, v134, v236, s[4:5]
	v_cndmask_b32_e64 v71, v133, v236, s[4:5]
	v_cndmask_b32_e64 v70, v132, v236, s[4:5]
	v_cndmask_b32_e64 v69, v131, v236, s[4:5]
	v_cndmask_b32_e64 v68, v130, v236, s[4:5]
	v_cndmask_b32_e64 v130, v129, v236, s[4:5]
	v_cndmask_b32_e64 v131, v128, v236, s[4:5]
	s_waitcnt lgkmcnt(14)
	v_mfma_f32_32x32x16_bf16 v[16:31], v[160:163], v[208:211], v[16:31]
	ds_read_b64_tr_b16 v[110:111], v66 offset:32768
	ds_read_b64_tr_b16 v[112:113], v66 offset:33280
	v_exp_f32_e32 v82, v82
	v_exp_f32_e32 v83, v67
	s_waitcnt lgkmcnt(14)
	v_mfma_f32_32x32x16_bf16 v[48:63], v[160:163], v[204:207], v[48:63]
	ds_read_b64_tr_b16 v[114:115], v66 offset:36864
	ds_read_b64_tr_b16 v[116:117], v66 offset:37376
	v_exp_f32_e32 v84, v84
	v_exp_f32_e32 v85, v85
	s_waitcnt lgkmcnt(14)
	v_mfma_f32_32x32x16_bf16 v[16:31], v[152:155], v[98:101], v[16:31]
	ds_read_b64_tr_b16 v[118:119], v66 offset:33792
	ds_read_b64_tr_b16 v[120:121], v66 offset:34304
	v_exp_f32_e32 v86, v86
	v_exp_f32_e32 v87, v87
	s_waitcnt lgkmcnt(14)
	v_mfma_f32_32x32x16_bf16 v[48:63], v[152:155], v[102:105], v[48:63]
	ds_read_b64_tr_b16 v[98:99], v66 offset:37888
	ds_read_b64_tr_b16 v[100:101], v66 offset:38400
	v_exp_f32_e32 v88, v88
	v_exp_f32_e32 v89, v89
	s_waitcnt lgkmcnt(14)
	v_mfma_f32_32x32x16_bf16 v[16:31], v[148:151], v[106:109], v[16:31]
	ds_read_b64_tr_b16 v[102:103], v66 offset:34816
	ds_read_b64_tr_b16 v[104:105], v66 offset:35328
	v_exp_f32_e32 v90, v90
	v_exp_f32_e32 v91, v91
	s_waitcnt lgkmcnt(14)
	v_mfma_f32_32x32x16_bf16 v[48:63], v[148:151], v[168:171], v[48:63]
	ds_read_b64_tr_b16 v[106:107], v66 offset:38912
	ds_read_b64_tr_b16 v[108:109], v66 offset:39424
	v_exp_f32_e32 v92, v92
	v_exp_f32_e32 v93, v93
	s_waitcnt lgkmcnt(14)
	v_mfma_f32_32x32x16_bf16 v[16:31], v[144:147], v[164:167], v[16:31]
	ds_read_b64_tr_b16 v[122:123], v66 offset:35840
	ds_read_b64_tr_b16 v[124:125], v66 offset:36352
	v_exp_f32_e32 v94, v94
	v_exp_f32_e32 v95, v95
	s_waitcnt lgkmcnt(14)
	v_mfma_f32_32x32x16_bf16 v[48:63], v[144:147], v[172:175], v[48:63]
	ds_read_b64_tr_b16 v[126:127], v66 offset:39936
	ds_read_b64_tr_b16 v[128:129], v66 offset:40448
	v_exp_f32_e32 v96, v96
	v_exp_f32_e32 v97, v97
	s_waitcnt lgkmcnt(14)
	v_mfma_f32_32x32x16_bf16 v[0:15], v[160:163], v[110:113], v[0:15]
	v_exp_f32_e32 v66, v131
	v_exp_f32_e32 v67, v130
	s_waitcnt lgkmcnt(12)
	v_mfma_f32_32x32x16_bf16 v[32:47], v[160:163], v[114:117], v[32:47]
	v_exp_f32_e32 v68, v68
	v_exp_f32_e32 v69, v69
	s_waitcnt lgkmcnt(10)
	v_mfma_f32_32x32x16_bf16 v[0:15], v[152:155], v[118:121], v[0:15]
	v_exp_f32_e32 v70, v70
	v_exp_f32_e32 v71, v71
	s_waitcnt lgkmcnt(8)
	v_mfma_f32_32x32x16_bf16 v[32:47], v[152:155], v[98:101], v[32:47]
	v_exp_f32_e32 v72, v72
	v_exp_f32_e32 v73, v73
	s_waitcnt lgkmcnt(6)
	v_mfma_f32_32x32x16_bf16 v[0:15], v[148:151], v[102:105], v[0:15]
	v_exp_f32_e32 v74, v74
	v_exp_f32_e32 v75, v75
	s_waitcnt lgkmcnt(4)
	v_mfma_f32_32x32x16_bf16 v[32:47], v[148:151], v[106:109], v[32:47]
	v_exp_f32_e32 v76, v76
	v_exp_f32_e32 v77, v77
	s_waitcnt lgkmcnt(2)
	v_mfma_f32_32x32x16_bf16 v[0:15], v[144:147], v[122:125], v[0:15]
	v_exp_f32_e32 v78, v78
	v_exp_f32_e32 v79, v79
	s_waitcnt lgkmcnt(0)
	v_mfma_f32_32x32x16_bf16 v[32:47], v[144:147], v[126:129], v[32:47]
	v_exp_f32_e32 v80, v80
	v_exp_f32_e32 v81, v81
	v_add_f32_e32 v98, v82, v83
	v_add_f32_e32 v98, v84, v98
	v_add_f32_e32 v98, v85, v98
	v_add_f32_e32 v98, v86, v98
	v_add_f32_e32 v98, v87, v98
	v_add_f32_e32 v98, v88, v98
	v_add_f32_e32 v98, v89, v98
	v_add_f32_e32 v98, v90, v98
	v_add_f32_e32 v98, v91, v98
	v_add_f32_e32 v98, v92, v98
	v_add_f32_e32 v98, v93, v98
	v_add_f32_e32 v98, v94, v98
	v_add_f32_e32 v98, v95, v98
	v_add_f32_e32 v98, v96, v98
	v_add_f32_e32 v98, v97, v98
	v_add_f32_e32 v98, v98, v66
	v_add_f32_e32 v98, v67, v98
	v_add_f32_e32 v98, v68, v98
	v_add_f32_e32 v98, v69, v98
	v_add_f32_e32 v98, v70, v98
	v_add_f32_e32 v98, v71, v98
	v_add_f32_e32 v98, v72, v98
	v_add_f32_e32 v98, v73, v98
	v_add_f32_e32 v98, v74, v98
	v_add_f32_e32 v98, v75, v98
	v_add_f32_e32 v98, v76, v98
	v_add_f32_e32 v98, v77, v98
	v_add_f32_e32 v98, v78, v98
	v_add_f32_e32 v98, v79, v98
	v_add_f32_e32 v98, v80, v98
	v_add_f32_e32 v98, v81, v98
	v_add_f32_e32 v64, v64, v180
	v_add_f32_e32 v64, v64, v98
	v_cvt_pk_bf16_f32 v82, v82, v83
	v_cvt_pk_bf16_f32 v83, v84, v85
	v_cvt_pk_bf16_f32 v84, v86, v87
	v_cvt_pk_bf16_f32 v85, v88, v89
	v_cvt_pk_bf16_f32 v86, v90, v91
	v_cvt_pk_bf16_f32 v87, v92, v93
	v_cvt_pk_bf16_f32 v88, v94, v95
	v_cvt_pk_bf16_f32 v89, v96, v97
	v_cvt_pk_bf16_f32 v66, v66, v67
	v_cvt_pk_bf16_f32 v67, v68, v69
	v_cvt_pk_bf16_f32 v68, v70, v71
	v_cvt_pk_bf16_f32 v69, v72, v73
	v_cvt_pk_bf16_f32 v70, v74, v75
	v_cvt_pk_bf16_f32 v71, v76, v77
	v_cvt_pk_bf16_f32 v72, v78, v79
	v_cvt_pk_bf16_f32 v73, v80, v81
	s_lshl_b32 s0, s2, 1
	v_add3_u32 v65, v65, v220, s0
	ds_read_b64_tr_b16 v[74:75],v65 offset:0
	ds_read_b64_tr_b16 v[76:77],v65 offset:512
	ds_read_b64_tr_b16 v[78:79],v65 offset:1024
	ds_read_b64_tr_b16 v[80:81],v65 offset:1536
	ds_read_b64_tr_b16 v[90:91],v65 offset:2048
	ds_read_b64_tr_b16 v[92:93],v65 offset:2560
	ds_read_b64_tr_b16 v[94:95],v65 offset:3072
	ds_read_b64_tr_b16 v[96:97],v65 offset:3584
	s_waitcnt lgkmcnt(0)
	s_nop 0
	v_mfma_f32_32x32x16_bf16 v[16:31], v[82:85], v[74:77], v[16:31]
	ds_read_b64_tr_b16 v[74:75],v65 offset:4096
	ds_read_b64_tr_b16 v[76:77],v65 offset:4608
	v_mfma_f32_32x32x16_bf16 v[16:31], v[86:89], v[78:81], v[16:31]
	ds_read_b64_tr_b16 v[78:79],v65 offset:5120
	ds_read_b64_tr_b16 v[80:81],v65 offset:5632
	v_mfma_f32_32x32x16_bf16 v[16:31], v[66:69], v[90:93], v[16:31]
	ds_read_b64_tr_b16 v[90:91],v65 offset:6144
	ds_read_b64_tr_b16 v[92:93],v65 offset:6656
	ds_read_b64_tr_b16 v[98:99],v65 offset:7168
	ds_read_b64_tr_b16 v[100:101],v65 offset:7680
	s_waitcnt lgkmcnt(0)
	v_mfma_f32_32x32x16_bf16 v[16:31], v[70:73], v[94:97], v[16:31]
	v_mfma_f32_32x32x16_bf16 v[48:63], v[82:85], v[74:77], v[48:63]
	ds_read_b64_tr_b16 v[74:75],v65 offset:8192
	ds_read_b64_tr_b16 v[76:77],v65 offset:8704
	v_mfma_f32_32x32x16_bf16 v[48:63], v[86:89], v[78:81], v[48:63]
	ds_read_b64_tr_b16 v[78:79],v65 offset:9216
	ds_read_b64_tr_b16 v[80:81],v65 offset:9728
	v_mfma_f32_32x32x16_bf16 v[48:63], v[66:69], v[90:93], v[48:63]
	ds_read_b64_tr_b16 v[90:91],v65 offset:10240
	ds_read_b64_tr_b16 v[92:93],v65 offset:10752
	ds_read_b64_tr_b16 v[94:95],v65 offset:11264
	ds_read_b64_tr_b16 v[96:97],v65 offset:11776
	s_waitcnt lgkmcnt(0)
	v_mfma_f32_32x32x16_bf16 v[48:63], v[70:73], v[98:101], v[48:63]
	v_mfma_f32_32x32x16_bf16 v[0:15], v[82:85], v[74:77], v[0:15]
	ds_read_b64_tr_b16 v[74:75],v65 offset:12288
	ds_read_b64_tr_b16 v[76:77],v65 offset:12800
	v_mfma_f32_32x32x16_bf16 v[0:15], v[86:89], v[78:81], v[0:15]
	ds_read_b64_tr_b16 v[78:79],v65 offset:13312
	ds_read_b64_tr_b16 v[80:81],v65 offset:13824
	v_mfma_f32_32x32x16_bf16 v[0:15], v[66:69], v[90:93], v[0:15]
	ds_read_b64_tr_b16 v[90:91],v65 offset:14336
	ds_read_b64_tr_b16 v[92:93],v65 offset:14848
	ds_read_b64_tr_b16 v[98:99],v65 offset:15360
	ds_read_b64_tr_b16 v[100:101],v65 offset:15872
	s_waitcnt lgkmcnt(0)
	v_mfma_f32_32x32x16_bf16 v[0:15], v[70:73], v[94:97], v[0:15]
	v_mfma_f32_32x32x16_bf16 v[32:47], v[82:85], v[74:77], v[32:47]
	v_mov_b32_e32 v65, v64
	s_nop 1
	v_permlane32_swap_b32_e32 v64, v65
	v_cmp_gt_u32_e32 vcc, 32, v242
	v_mfma_f32_32x32x16_bf16 v[32:47], v[86:89], v[78:81], v[32:47]
	v_mfma_f32_32x32x16_bf16 v[32:47], v[66:69], v[90:93], v[32:47]
	v_mfma_f32_32x32x16_bf16 v[32:47], v[70:73], v[98:101], v[32:47]
	s_and_saveexec_b64 s[0:1], vcc
	v_lshl_add_u32 v66, v242, 2, s70
	v_add_f32_e32 v64, v64, v65
	ds_write_b32 v66, v64 offset:128
	s_or_b64 exec, exec, s[0:1]
	s_waitcnt lgkmcnt(0)
	v_lshl_add_u32 v72, v244, 4, s70
	ds_read_b128 v[64:67], v72 offset:128
	ds_read_b128 v[68:71], v72 offset:160
	s_lshl_b64 s[0:1], s[48:49], 12
	s_add_u32 s0, s6, s0
	s_addc_u32 s1, s7, s1
	s_waitcnt lgkmcnt(1)
	v_rcp_f32_e32 v73, v64
	v_rcp_f32_e32 v74, v65
	v_rcp_f32_e32 v75, v66
	v_rcp_f32_e32 v76, v67
	s_waitcnt lgkmcnt(0)
	v_rcp_f32_e32 v77, v68
	ds_read_b128 v[64:67], v72 offset:192
	v_rcp_f32_e32 v78, v69
	v_rcp_f32_e32 v79, v70
	v_rcp_f32_e32 v80, v71
	ds_read_b128 v[68:71], v72 offset:224
	s_waitcnt lgkmcnt(1)
	v_rcp_f32_e32 v64, v64
	v_rcp_f32_e32 v65, v65
	v_rcp_f32_e32 v66, v66
	v_rcp_f32_e32 v67, v67
	s_waitcnt lgkmcnt(0)
	v_rcp_f32_e32 v68, v68
	v_rcp_f32_e32 v69, v69
	v_rcp_f32_e32 v70, v70
	v_rcp_f32_e32 v71, v71
	s_add_u32 s0, s0, s50
	s_addc_u32 s1, s1, s51
	s_bitcmp1_b32 s19, 0
	v_lshrrev_b32_e32 v230, 3, v242
	s_cselect_b64 s[24:25], -1, 0
	v_lshlrev_b32_e32 v72, 9, v244
	v_lshlrev_b32_e32 v81, 1, v243
	v_or_b32_e32 v185, 8, v230
	v_or_b32_e32 v177, 16, v230
	v_or_b32_e32 v171, 24, v230
	v_add3_u32 v166, s74, v72, v81
	s_mov_b64 s[52:53], -1
	s_and_b64 vcc, exec, s[24:25]
	v_lshlrev_b32_e32 v84, 12, v230
	v_mul_f32_e32 v246, v16, v73
	v_mul_f32_e32 v245, v48, v73
	v_mul_f32_e32 v244, v17, v74
	v_mul_f32_e32 v243, v49, v74
	v_mul_f32_e32 v242, v18, v75
	v_mul_f32_e32 v233, v50, v75
	v_mul_f32_e32 v232, v19, v76
	v_mul_f32_e32 v231, v51, v76
	v_mul_f32_e32 v229, v20, v77
	v_mul_f32_e32 v228, v52, v77
	v_mul_f32_e32 v227, v21, v78
	v_mul_f32_e32 v226, v53, v78
	v_mul_f32_e32 v225, v22, v79
	v_mul_f32_e32 v224, v54, v79
	v_mul_f32_e32 v219, v23, v80
	v_mul_f32_e32 v218, v55, v80
	v_mul_f32_e32 v217, v24, v64
	v_mul_f32_e32 v216, v56, v64
	v_mul_f32_e32 v215, v25, v65
	v_mul_f32_e32 v214, v57, v65
	v_mul_f32_e32 v213, v26, v66
	v_mul_f32_e32 v212, v58, v66
	v_mul_f32_e32 v211, v27, v67
	v_mul_f32_e32 v210, v59, v67
	v_mul_f32_e32 v209, v28, v68
	v_mul_f32_e32 v208, v60, v68
	v_mul_f32_e32 v207, v29, v69
	v_mul_f32_e32 v206, v61, v69
	v_mul_f32_e32 v205, v30, v70
	v_mul_f32_e32 v204, v62, v70
	v_mul_f32_e32 v203, v31, v71
	v_mul_f32_e32 v202, v63, v71
	v_lshlrev_b32_e32 v90, 12, v185
	v_lshlrev_b32_e32 v88, 12, v177
	v_lshlrev_b32_e32 v86, 12, v171
	v_mul_f32_e32 v201, v0, v73
	v_mul_f32_e32 v200, v32, v73
	v_mul_f32_e32 v199, v1, v74
	v_mul_f32_e32 v198, v33, v74
	v_mul_f32_e32 v197, v2, v75
	v_mul_f32_e32 v196, v34, v75
	v_mul_f32_e32 v195, v3, v76
	v_mul_f32_e32 v194, v35, v76
	v_mul_f32_e32 v193, v4, v77
	v_mul_f32_e32 v192, v36, v77
	v_mul_f32_e32 v191, v5, v78
	v_mul_f32_e32 v190, v37, v78
	v_mul_f32_e32 v189, v6, v79
	v_mul_f32_e32 v188, v38, v79
	v_mul_f32_e32 v187, v7, v80
	v_mul_f32_e32 v186, v39, v80
	v_mul_f32_e32 v184, v8, v64
	v_mul_f32_e32 v183, v40, v64
	v_mul_f32_e32 v182, v9, v65
	v_mul_f32_e32 v181, v41, v65
	v_mul_f32_e32 v180, v10, v66
	v_mul_f32_e32 v179, v42, v66
	v_mul_f32_e32 v178, v11, v67
	v_mul_f32_e32 v176, v43, v67
	v_mul_f32_e32 v175, v12, v68
	v_mul_f32_e32 v174, v44, v68
	v_mul_f32_e32 v173, v13, v69
	v_mul_f32_e32 v172, v45, v69
	v_mul_f32_e32 v170, v14, v70
	v_mul_f32_e32 v169, v46, v70
	v_mul_f32_e32 v168, v15, v71
	v_mul_f32_e32 v167, v47, v71
	s_cbranch_vccz .LBB0_692
	v_cvt_pk_bf16_f32 v3, v246, s0
	ds_write_b16 v166, v3
	v_cvt_pk_bf16_f32 v3, v245, s0
	ds_write_b16 v166, v3 offset:64
	v_cvt_pk_bf16_f32 v3, v244, s0
	ds_write_b16 v166, v3 offset:128
	v_cvt_pk_bf16_f32 v3, v243, s0
	ds_write_b16 v166, v3 offset:192
	v_cvt_pk_bf16_f32 v3, v242, s0
	ds_write_b16 v166, v3 offset:256
	v_cvt_pk_bf16_f32 v3, v233, s0
	ds_write_b16 v166, v3 offset:320
	v_cvt_pk_bf16_f32 v3, v232, s0
	ds_write_b16 v166, v3 offset:384
	v_cvt_pk_bf16_f32 v3, v231, s0
	ds_write_b16 v166, v3 offset:448
	v_cvt_pk_bf16_f32 v3, v229, s0
	ds_write_b16 v166, v3 offset:1024
	v_cvt_pk_bf16_f32 v3, v228, s0
	ds_write_b16 v166, v3 offset:1088
	v_cvt_pk_bf16_f32 v3, v227, s0
	ds_write_b16 v166, v3 offset:1152
	v_cvt_pk_bf16_f32 v3, v226, s0
	ds_write_b16 v166, v3 offset:1216
	v_cvt_pk_bf16_f32 v3, v225, s0
	ds_write_b16 v166, v3 offset:1280
	v_cvt_pk_bf16_f32 v3, v224, s0
	ds_write_b16 v166, v3 offset:1344
	v_cvt_pk_bf16_f32 v3, v219, s0
	ds_write_b16 v166, v3 offset:1408
	v_cvt_pk_bf16_f32 v3, v218, s0
	ds_write_b16 v166, v3 offset:1472
	v_cvt_pk_bf16_f32 v3, v217, s0
	ds_write_b16 v166, v3 offset:2048
	v_cvt_pk_bf16_f32 v3, v216, s0
	ds_write_b16 v166, v3 offset:2112
	v_cvt_pk_bf16_f32 v3, v215, s0
	ds_write_b16 v166, v3 offset:2176
	v_cvt_pk_bf16_f32 v3, v214, s0
	ds_write_b16 v166, v3 offset:2240
	v_cvt_pk_bf16_f32 v3, v213, s0
	ds_write_b16 v166, v3 offset:2304
	v_cvt_pk_bf16_f32 v3, v212, s0
	ds_write_b16 v166, v3 offset:2368
	v_cvt_pk_bf16_f32 v3, v211, s0
	ds_write_b16 v166, v3 offset:2432
	v_cvt_pk_bf16_f32 v3, v210, s0
	ds_write_b16 v166, v3 offset:2496
	v_cvt_pk_bf16_f32 v3, v209, s0
	ds_write_b16 v166, v3 offset:3072
	v_cvt_pk_bf16_f32 v3, v208, s0
	ds_write_b16 v166, v3 offset:3136
	v_cvt_pk_bf16_f32 v3, v207, s0
	ds_write_b16 v166, v3 offset:3200
	v_cvt_pk_bf16_f32 v3, v206, s0
	ds_write_b16 v166, v3 offset:3264
	v_cvt_pk_bf16_f32 v3, v205, s0
	v_lshlrev_b32_e32 v0, 3, v241
	ds_write_b16 v166, v3 offset:3328
	v_cvt_pk_bf16_f32 v3, v204, s0
	v_and_b32_e32 v36, 56, v0
	ds_write_b16 v166, v3 offset:3392
	v_cvt_pk_bf16_f32 v3, v203, s0
	v_lshlrev_b32_e32 v220, 1, v36
	ds_write_b16 v166, v3 offset:3456
	v_cvt_pk_bf16_f32 v3, v202, s0
	v_add_u32_e32 v2, s74, v220
	v_lshl_add_u64 v[0:1], s[0:1], 0, v[220:221]
	ds_write_b16 v166, v3 offset:3520
	v_mov_b32_e32 v85, v221
	v_mov_b32_e32 v91, v221
	v_mov_b32_e32 v89, v221
	v_mov_b32_e32 v87, v221
	s_waitcnt lgkmcnt(0)
	v_lshl_add_u32 v3, v230, 7, v2
	v_lshl_add_u64 v[98:99], v[0:1], 0, v[84:85]
	v_lshl_add_u32 v4, v185, 7, v2
	v_lshl_add_u64 v[96:97], v[0:1], 0, v[90:91]
	v_lshl_add_u32 v5, v177, 7, v2
	v_lshl_add_u64 v[94:95], v[0:1], 0, v[88:89]
	v_lshl_add_u32 v2, v171, 7, v2
	v_lshl_add_u64 v[92:93], v[0:1], 0, v[86:87]
	v_cvt_pk_bf16_f32 v0, v201, s0
	ds_read_b128 v[62:65], v3
	ds_read_b128 v[16:19], v2
	global_load_dwordx4 v[66:69], v[98:99], off
	global_load_dwordx4 v[50:53], v[96:97], off
	ds_read_b128 v[46:49], v4
	ds_read_b128 v[38:41], v5
	global_load_dwordx4 v[42:45], v[94:95], off
	global_load_dwordx4 v[20:23], v[92:93], off
	s_waitcnt lgkmcnt(0)
	ds_write_b16 v166, v0
	v_cvt_pk_bf16_f32 v0, v200, s0
	ds_write_b16 v166, v0 offset:64
	v_cvt_pk_bf16_f32 v0, v199, s0
	ds_write_b16 v166, v0 offset:128
	v_cvt_pk_bf16_f32 v0, v198, s0
	ds_write_b16 v166, v0 offset:192
	v_cvt_pk_bf16_f32 v0, v197, s0
	ds_write_b16 v166, v0 offset:256
	v_cvt_pk_bf16_f32 v0, v196, s0
	ds_write_b16 v166, v0 offset:320
	v_cvt_pk_bf16_f32 v0, v195, s0
	ds_write_b16 v166, v0 offset:384
	v_cvt_pk_bf16_f32 v0, v194, s0
	ds_write_b16 v166, v0 offset:448
	v_cvt_pk_bf16_f32 v0, v193, s0
	ds_write_b16 v166, v0 offset:1024
	v_cvt_pk_bf16_f32 v0, v192, s0
	ds_write_b16 v166, v0 offset:1088
	v_cvt_pk_bf16_f32 v0, v191, s0
	ds_write_b16 v166, v0 offset:1152
	v_cvt_pk_bf16_f32 v0, v190, s0
	ds_write_b16 v166, v0 offset:1216
	v_cvt_pk_bf16_f32 v0, v189, s0
	ds_write_b16 v166, v0 offset:1280
	v_cvt_pk_bf16_f32 v0, v188, s0
	ds_write_b16 v166, v0 offset:1344
	v_cvt_pk_bf16_f32 v0, v187, s0
	ds_write_b16 v166, v0 offset:1408
	v_cvt_pk_bf16_f32 v0, v186, s0
	ds_write_b16 v166, v0 offset:1472
	v_cvt_pk_bf16_f32 v0, v184, s0
	ds_write_b16 v166, v0 offset:2048
	v_cvt_pk_bf16_f32 v0, v183, s0
	ds_write_b16 v166, v0 offset:2112
	v_cvt_pk_bf16_f32 v0, v182, s0
	ds_write_b16 v166, v0 offset:2176
	v_cvt_pk_bf16_f32 v0, v181, s0
	ds_write_b16 v166, v0 offset:2240
	v_cvt_pk_bf16_f32 v0, v180, s0
	ds_write_b16 v166, v0 offset:2304
	v_cvt_pk_bf16_f32 v0, v179, s0
	ds_write_b16 v166, v0 offset:2368
	v_cvt_pk_bf16_f32 v0, v178, s0
	ds_write_b16 v166, v0 offset:2432
	v_cvt_pk_bf16_f32 v0, v176, s0
	ds_write_b16 v166, v0 offset:2496
	v_cvt_pk_bf16_f32 v0, v175, s0
	ds_write_b16 v166, v0 offset:3072
	v_cvt_pk_bf16_f32 v0, v174, s0
	ds_write_b16 v166, v0 offset:3136
	v_cvt_pk_bf16_f32 v0, v173, s0
	ds_write_b16 v166, v0 offset:3200
	v_cvt_pk_bf16_f32 v0, v172, s0
	ds_write_b16 v166, v0 offset:3264
	v_cvt_pk_bf16_f32 v0, v170, s0
	ds_write_b16 v166, v0 offset:3328
	v_cvt_pk_bf16_f32 v0, v169, s0
	ds_write_b16 v166, v0 offset:3392
	v_cvt_pk_bf16_f32 v0, v168, s0
	ds_write_b16 v166, v0 offset:3456
	v_cvt_pk_bf16_f32 v0, v167, s0
	ds_write_b16 v166, v0 offset:3520
	s_waitcnt lgkmcnt(0)
	global_load_dwordx4 v[54:57], v[98:99], off offset:128
	global_load_dwordx4 v[28:31], v[96:97], off offset:128
	global_load_dwordx4 v[8:11], v[94:95], off offset:128
	s_add_u32 s24, s3, s50
	ds_read_b128 v[58:61], v3
	ds_read_b128 v[24:27], v4
	ds_read_b128 v[12:15], v5
	ds_read_b128 v[0:3], v2
	s_addc_u32 s25, s18, s51
	v_or_b32_e32 v124, s48, v230
	v_mov_b32_e32 v125, s49
	v_lshl_add_u64 v[122:123], s[24:25], 0, v[220:221]
	v_lshlrev_b64 v[32:33], 11, v[124:125]
	v_lshl_add_u64 v[70:71], v[122:123], 0, v[32:33]
	s_waitcnt lgkmcnt(3)
	v_and_b32_e32 v34, 0xffff0000, v59
	v_lshlrev_b32_e32 v35, 16, v59
	v_or_b32_e32 v124, s48, v185
	global_load_dwordx4 v[4:7], v[92:93], off offset:128
	s_waitcnt lgkmcnt(0)
	global_load_dwordx4 v[76:79], v[70:71], off
	s_waitcnt vmcnt(8)
	v_lshlrev_b32_e32 v80, 16, v68
	v_and_b32_e32 v81, 0xffff0000, v68
	v_lshlrev_b32_e32 v68, 16, v64
	v_lshlrev_b32_e32 v128, 16, v63
	v_and_b32_e32 v129, 0xffff0000, v63
	v_lshlrev_b32_e32 v144, 16, v47
	v_and_b32_e32 v145, 0xffff0000, v47
	v_lshlrev_b32_e32 v148, 16, v46
	v_and_b32_e32 v149, 0xffff0000, v46
	v_lshlrev_b32_e32 v130, 16, v48
	v_and_b32_e32 v131, 0xffff0000, v48
	v_lshlrev_b32_e32 v48, 16, v58
	s_waitcnt vmcnt(7)
	v_lshlrev_b32_e32 v142, 16, v51
	v_and_b32_e32 v143, 0xffff0000, v51
	v_lshlrev_b32_e32 v146, 16, v50
	v_and_b32_e32 v147, 0xffff0000, v50
	s_mov_b64 s[52:53], 0
	s_waitcnt vmcnt(4)
	v_and_b32_e32 v32, 0xffff0000, v55
	v_lshlrev_b32_e32 v33, 16, v55
	v_pk_fma_f32 v[108:109], v[222:223], v[34:35], v[32:33] neg_lo:[1,0,0] neg_hi:[1,0,0]
	v_and_b32_e32 v32, 0xffff0000, v56
	v_lshlrev_b32_e32 v33, 16, v56
	v_and_b32_e32 v34, 0xffff0000, v60
	v_lshlrev_b32_e32 v35, 16, v60
	v_pk_fma_f32 v[102:103], v[222:223], v[34:35], v[32:33] neg_lo:[1,0,0] neg_hi:[1,0,0]
	v_and_b32_e32 v32, 0xffff0000, v57
	v_lshlrev_b32_e32 v33, 16, v57
	v_and_b32_e32 v34, 0xffff0000, v61
	v_lshlrev_b32_e32 v35, 16, v61
	v_pk_fma_f32 v[100:101], v[222:223], v[34:35], v[32:33] neg_lo:[1,0,0] neg_hi:[1,0,0]
	v_lshlrev_b64 v[34:35], 11, v[124:125]
	v_lshl_add_u64 v[60:61], v[122:123], 0, v[34:35]
	global_load_dwordx4 v[72:75], v[60:61], off
	s_waitcnt vmcnt(4)
	v_and_b32_e32 v32, 0xffff0000, v29
	v_lshlrev_b32_e32 v33, 16, v29
	s_waitcnt lgkmcnt(2)
	v_and_b32_e32 v34, 0xffff0000, v25
	v_lshlrev_b32_e32 v35, 16, v25
	v_pk_fma_f32 v[110:111], v[222:223], v[34:35], v[32:33] neg_lo:[1,0,0] neg_hi:[1,0,0]
	v_and_b32_e32 v32, 0xffff0000, v30
	v_lshlrev_b32_e32 v33, 16, v30
	v_and_b32_e32 v34, 0xffff0000, v26
	v_lshlrev_b32_e32 v35, 16, v26
	v_and_b32_e32 v30, 0xffff0000, v31
	v_lshlrev_b32_e32 v31, 16, v31
	v_and_b32_e32 v26, 0xffff0000, v27
	v_lshlrev_b32_e32 v27, 16, v27
	v_pk_fma_f32 v[104:105], v[222:223], v[26:27], v[30:31] neg_lo:[1,0,0] neg_hi:[1,0,0]
	s_waitcnt vmcnt(3)
	v_and_b32_e32 v26, 0xffff0000, v9
	v_lshlrev_b32_e32 v27, 16, v9
	s_waitcnt lgkmcnt(1)
	v_and_b32_e32 v30, 0xffff0000, v13
	v_lshlrev_b32_e32 v31, 16, v13
	v_pk_fma_f32 v[56:57], v[222:223], v[30:31], v[26:27] neg_lo:[1,0,0] neg_hi:[1,0,0]
	v_and_b32_e32 v26, 0xffff0000, v10
	v_lshlrev_b32_e32 v27, 16, v10
	v_and_b32_e32 v30, 0xffff0000, v14
	v_lshlrev_b32_e32 v31, 16, v14
	v_and_b32_e32 v10, 0xffff0000, v11
	v_lshlrev_b32_e32 v11, 16, v11
	v_and_b32_e32 v14, 0xffff0000, v15
	v_lshlrev_b32_e32 v15, 16, v15
	v_pk_fma_f32 v[10:11], v[222:223], v[14:15], v[10:11] neg_lo:[1,0,0] neg_hi:[1,0,0]
	v_lshlrev_b32_e32 v14, 16, v69
	v_and_b32_e32 v15, 0xffff0000, v69
	v_and_b32_e32 v69, 0xffff0000, v64
	v_or_b32_e32 v124, s48, v177
	v_pk_fma_f32 v[116:117], v[222:223], v[68:69], v[80:81] neg_lo:[1,0,0] neg_hi:[1,0,0]
	v_lshlrev_b64 v[80:81], 11, v[124:125]
	v_pk_fma_f32 v[26:27], v[222:223], v[30:31], v[26:27] neg_lo:[1,0,0] neg_hi:[1,0,0]
	v_lshlrev_b32_e32 v9, 2, v36
	v_lshlrev_b32_e32 v30, 16, v65
	v_and_b32_e32 v31, 0xffff0000, v65
	v_lshl_add_u64 v[158:159], v[122:123], 0, v[80:81]
	v_pk_fma_f32 v[106:107], v[222:223], v[34:35], v[32:33] neg_lo:[1,0,0] neg_hi:[1,0,0]
	v_pk_fma_f32 v[14:15], v[222:223], v[30:31], v[14:15] neg_lo:[1,0,0] neg_hi:[1,0,0]
	global_load_dwordx4 v[30:33], v9, s[28:29] offset:16
	global_load_dwordx4 v[34:37], v9, s[28:29]
	global_load_dwordx4 v[80:83], v[158:159], off
	v_lshlrev_b32_e32 v64, 16, v67
	v_and_b32_e32 v65, 0xffff0000, v67
	v_pk_fma_f32 v[152:153], v[222:223], v[128:129], v[64:65] neg_lo:[1,0,0] neg_hi:[1,0,0]
	v_lshlrev_b32_e32 v64, 16, v66
	v_and_b32_e32 v65, 0xffff0000, v66
	v_lshlrev_b32_e32 v66, 16, v62
	v_and_b32_e32 v67, 0xffff0000, v62
	v_pk_fma_f32 v[160:161], v[222:223], v[66:67], v[64:65] neg_lo:[1,0,0] neg_hi:[1,0,0]
	v_pk_mul_f32 v[248:249], v[152:153], v[152:153]
	v_pk_mul_f32 v[250:251], v[160:161], v[160:161]
	v_pk_mul_f32 v[140:141], v[116:117], v[116:117]
	v_add_f32_e32 v13, v250, v251
	v_add_f32_e32 v13, v248, v13
	v_or_b32_e32 v124, s48, v171
	v_add_f32_e32 v13, v249, v13
	v_lshlrev_b64 v[46:47], 11, v[124:125]
	v_add_f32_e32 v13, v140, v13
	v_pk_mul_f32 v[138:139], v[14:15], v[14:15]
	v_lshlrev_b32_e32 v128, 16, v49
	v_and_b32_e32 v129, 0xffff0000, v49
	v_lshl_add_u64 v[164:165], v[122:123], 0, v[46:47]
	v_lshlrev_b32_e32 v46, 16, v54
	v_and_b32_e32 v47, 0xffff0000, v54
	v_and_b32_e32 v49, 0xffff0000, v58
	v_add_f32_e32 v13, v141, v13
	v_add_f32_e32 v13, v138, v13
	v_add_f32_e32 v13, v139, v13
	v_pk_mul_f32 v[118:119], v[108:109], v[108:109]
	v_pk_mul_f32 v[120:121], v[102:103], v[102:103]
	v_pk_mul_f32 v[126:127], v[100:101], v[100:101]
	global_load_dwordx4 v[64:67], v[164:165], off
	s_waitcnt vmcnt(5)
	v_lshlrev_b32_e32 v150, 16, v78
	v_and_b32_e32 v151, 0xffff0000, v78
	v_lshlrev_b32_e32 v154, 16, v77
	v_and_b32_e32 v155, 0xffff0000, v77
	v_lshlrev_b32_e32 v162, 16, v76
	s_waitcnt vmcnt(4)
	v_lshlrev_b32_e32 v132, 16, v74
	v_and_b32_e32 v133, 0xffff0000, v74
	v_lshlrev_b32_e32 v134, 16, v73
	v_and_b32_e32 v135, 0xffff0000, v73
	v_lshlrev_b32_e32 v136, 16, v72
	v_and_b32_e32 v137, 0xffff0000, v72
	v_lshlrev_b32_e32 v72, 16, v75
	v_and_b32_e32 v73, 0xffff0000, v75
	v_pk_fma_f32 v[74:75], v[222:223], v[48:49], v[46:47] neg_lo:[1,0,0] neg_hi:[1,0,0]
	v_and_b32_e32 v163, 0xffff0000, v76
	v_pk_mul_f32 v[46:47], v[74:75], v[74:75]
	v_lshlrev_b32_e32 v156, 16, v79
	v_add_f32_e32 v13, v13, v46
	v_add_f32_e32 v13, v47, v13
	v_add_f32_e32 v13, v119, v13
	v_add_f32_e32 v13, v118, v13
	v_add_f32_e32 v13, v121, v13
	v_add_f32_e32 v13, v120, v13
	v_add_f32_e32 v13, v127, v13
	v_add_f32_e32 v13, v126, v13
	ds_bpermute_b32 v25, v237, v13
	v_and_b32_e32 v157, 0xffff0000, v79
	v_lshlrev_b32_e32 v76, 16, v53
	v_and_b32_e32 v77, 0xffff0000, v53
	v_lshlrev_b32_e32 v78, 16, v52
	s_waitcnt lgkmcnt(0)
	v_add_f32_e32 v13, v13, v25
	ds_bpermute_b32 v25, v238, v13
	v_and_b32_e32 v79, 0xffff0000, v52
	global_load_dwordx4 v[52:55], v[158:159], off offset:128
	v_lshlrev_b32_e32 v120, 16, v41
	v_and_b32_e32 v121, 0xffff0000, v41
	s_waitcnt lgkmcnt(0)
	v_add_f32_e32 v13, v13, v25
	ds_bpermute_b32 v25, v239, v13
	v_lshlrev_b32_e32 v124, 16, v40
	v_and_b32_e32 v125, 0xffff0000, v40
	v_lshlrev_b32_e32 v122, 16, v44
	v_and_b32_e32 v123, 0xffff0000, v44
	s_waitcnt lgkmcnt(0)
	v_add_f32_e32 v13, v13, v25
	v_fmamk_f32 v13, v13, 0x3c000000, v235
	v_lshlrev_b32_e32 v118, 16, v45
	v_and_b32_e32 v119, 0xffff0000, v45
	global_load_dwordx4 v[68:71], v[70:71], off offset:128
	v_pk_fma_f32 v[78:79], v[222:223], v[130:131], v[78:79] neg_lo:[1,0,0] neg_hi:[1,0,0]
	s_waitcnt vmcnt(3)
	v_lshlrev_b32_e32 v58, 16, v82
	v_and_b32_e32 v59, 0xffff0000, v82
	v_rsq_f32_e32 v82, v13
	global_load_dwordx4 v[60:63], v[60:61], off offset:128
	v_pk_fma_f32 v[130:131], v[222:223], v[144:145], v[142:143] neg_lo:[1,0,0] neg_hi:[1,0,0]
	v_pk_fma_f32 v[144:145], v[222:223], v[148:149], v[146:147] neg_lo:[1,0,0] neg_hi:[1,0,0]
	v_pk_mul_f32 v[40:41], v[160:161], v[82:83] op_sel_hi:[1,0]
	v_pk_mul_f32 v[14:15], v[14:15], v[82:83] op_sel_hi:[1,0]
	v_pk_mul_f32 v[40:41], v[34:35], v[40:41]
	v_pk_mul_f32 v[14:15], v[14:15], v[32:33]
	v_pk_mul_f32 v[40:41], v[40:41], v[162:163]
	v_pk_mul_f32 v[14:15], v[14:15], v[156:157]
	v_cvt_pk_bf16_f32 v44, v40, v41
	v_pk_mul_f32 v[40:41], v[152:153], v[82:83] op_sel_hi:[1,0]
	v_cvt_pk_bf16_f32 v47, v14, v15
	v_pk_mul_f32 v[40:41], v[40:41], v[36:37]
	v_lshlrev_b32_e32 v152, 16, v23
	v_pk_mul_f32 v[40:41], v[40:41], v[154:155]
	v_and_b32_e32 v153, 0xffff0000, v23
	v_cvt_pk_bf16_f32 v45, v40, v41
	v_pk_mul_f32 v[40:41], v[116:117], v[82:83] op_sel_hi:[1,0]
	v_lshlrev_b32_e32 v154, 16, v19
	v_pk_mul_f32 v[40:41], v[40:41], v[30:31]
	v_and_b32_e32 v155, 0xffff0000, v19
	v_pk_mul_f32 v[40:41], v[40:41], v[150:151]
	v_lshlrev_b32_e32 v126, 16, v43
	v_cvt_pk_bf16_f32 v46, v40, v41
	global_store_dwordx4 v[98:99], v[44:47], off
	global_load_dwordx4 v[44:47], v9, s[28:29] offset:272
	s_nop 0
	global_load_dwordx4 v[48:51], v9, s[28:29] offset:256
	v_and_b32_e32 v127, 0xffff0000, v43
	v_lshlrev_b32_e32 v138, 16, v39
	v_and_b32_e32 v139, 0xffff0000, v39
	v_lshlrev_b32_e32 v140, 16, v42
	v_and_b32_e32 v141, 0xffff0000, v42
	v_lshlrev_b32_e32 v150, 16, v38
	v_and_b32_e32 v151, 0xffff0000, v38
	v_pk_fma_f32 v[148:149], v[222:223], v[154:155], v[152:153] neg_lo:[1,0,0] neg_hi:[1,0,0]
	v_pk_mul_f32 v[154:155], v[144:145], v[144:145]
	global_load_dwordx4 v[38:41], v[164:165], off offset:128
	v_lshlrev_b32_e32 v160, 16, v21
	v_and_b32_e32 v161, 0xffff0000, v21
	v_lshlrev_b32_e32 v164, 16, v20
	v_and_b32_e32 v165, 0xffff0000, v20
	v_and_b32_e32 v20, 0xffff0000, v1
	v_lshlrev_b32_e32 v21, 16, v1
	v_pk_fma_f32 v[126:127], v[222:223], v[138:139], v[126:127] neg_lo:[1,0,0] neg_hi:[1,0,0]
	v_pk_fma_f32 v[138:139], v[222:223], v[150:151], v[140:141] neg_lo:[1,0,0] neg_hi:[1,0,0]
	v_pk_mul_f32 v[150:151], v[130:131], v[130:131]
	v_add_f32_e32 v1, v154, v155
	v_lshlrev_b32_e32 v162, 16, v17
	v_and_b32_e32 v163, 0xffff0000, v17
	v_lshlrev_b32_e32 v248, 16, v16
	v_and_b32_e32 v249, 0xffff0000, v16
	v_and_b32_e32 v16, 0xffff0000, v5
	v_lshlrev_b32_e32 v17, 16, v5
	v_add_f32_e32 v1, v150, v1
	v_lshlrev_b32_e32 v116, 16, v81
	v_and_b32_e32 v117, 0xffff0000, v81
	v_lshlrev_b32_e32 v42, 16, v80
	v_and_b32_e32 v43, 0xffff0000, v80
	s_waitcnt vmcnt(7)
	v_lshlrev_b32_e32 v80, 16, v65
	v_and_b32_e32 v81, 0xffff0000, v65
	v_lshlrev_b32_e32 v250, 16, v64
	v_and_b32_e32 v251, 0xffff0000, v64
	v_pk_fma_f32 v[20:21], v[222:223], v[20:21], v[16:17] neg_lo:[1,0,0] neg_hi:[1,0,0]
	v_lshlrev_b32_e32 v64, 16, v28
	v_and_b32_e32 v65, 0xffff0000, v28
	v_and_b32_e32 v16, 0xffff0000, v6
	v_lshlrev_b32_e32 v17, 16, v6
	v_and_b32_e32 v28, 0xffff0000, v2
	v_lshlrev_b32_e32 v29, 16, v2
	v_pk_mul_f32 v[140:141], v[78:79], v[78:79]
	v_add_f32_e32 v1, v151, v1
	v_pk_fma_f32 v[16:17], v[222:223], v[28:29], v[16:17] neg_lo:[1,0,0] neg_hi:[1,0,0]
	v_lshlrev_b32_e32 v28, 16, v24
	v_and_b32_e32 v29, 0xffff0000, v24
	v_pk_fma_f32 v[24:25], v[222:223], v[128:129], v[76:77] neg_lo:[1,0,0] neg_hi:[1,0,0]
	v_add_f32_e32 v1, v140, v1
	v_lshlrev_b32_e32 v156, 16, v22
	v_and_b32_e32 v157, 0xffff0000, v22
	v_lshlrev_b32_e32 v158, 16, v18
	v_and_b32_e32 v159, 0xffff0000, v18
	v_lshlrev_b32_e32 v18, 16, v66
	v_and_b32_e32 v19, 0xffff0000, v66
	v_lshlrev_b32_e32 v22, 16, v67
	v_and_b32_e32 v23, 0xffff0000, v67
	v_pk_mul_f32 v[66:67], v[24:25], v[24:25]
	v_add_f32_e32 v1, v141, v1
	v_pk_fma_f32 v[28:29], v[222:223], v[28:29], v[64:65] neg_lo:[1,0,0] neg_hi:[1,0,0]
	v_add_f32_e32 v1, v66, v1
	v_add_f32_e32 v1, v67, v1
	v_pk_mul_f32 v[64:65], v[28:29], v[28:29]
	v_pk_mul_f32 v[112:113], v[110:111], v[110:111]
	v_add_f32_e32 v1, v1, v64
	v_add_f32_e32 v1, v65, v1
	v_add_f32_e32 v1, v113, v1
	v_pk_mul_f32 v[114:115], v[106:107], v[106:107]
	v_add_f32_e32 v1, v112, v1
	v_and_b32_e32 v6, 0xffff0000, v7
	v_lshlrev_b32_e32 v7, 16, v7
	v_and_b32_e32 v2, 0xffff0000, v3
	v_lshlrev_b32_e32 v3, 16, v3
	v_add_f32_e32 v1, v115, v1
	v_pk_fma_f32 v[2:3], v[222:223], v[2:3], v[6:7] neg_lo:[1,0,0] neg_hi:[1,0,0]
	v_pk_mul_f32 v[6:7], v[104:105], v[104:105]
	v_add_f32_e32 v1, v114, v1
	v_add_f32_e32 v1, v7, v1
	v_add_f32_e32 v1, v6, v1
	ds_bpermute_b32 v5, v237, v1
	v_pk_mul_f32 v[6:7], v[102:103], v[82:83] op_sel_hi:[1,0]
	v_pk_mul_f32 v[108:109], v[108:109], v[82:83] op_sel_hi:[1,0]
	s_waitcnt vmcnt(2)
	v_pk_mul_f32 v[6:7], v[6:7], v[44:45] op_sel:[1,0] op_sel_hi:[0,1]
	v_lshlrev_b32_e32 v66, 16, v70
	s_waitcnt lgkmcnt(0)
	v_add_f32_e32 v1, v1, v5
	ds_bpermute_b32 v5, v238, v1
	v_and_b32_e32 v67, 0xffff0000, v70
	v_pk_fma_f32 v[152:153], v[222:223], v[158:159], v[156:157] neg_lo:[1,0,0] neg_hi:[1,0,0]
	v_pk_fma_f32 v[156:157], v[222:223], v[162:163], v[160:161] neg_lo:[1,0,0] neg_hi:[1,0,0]
	v_lshlrev_b32_e32 v162, 16, v68
	s_waitcnt lgkmcnt(0)
	v_add_f32_e32 v1, v1, v5
	ds_bpermute_b32 v5, v239, v1
	v_and_b32_e32 v163, 0xffff0000, v68
	s_waitcnt vmcnt(1)
	v_pk_mul_f32 v[108:109], v[108:109], v[50:51] op_sel:[1,0] op_sel_hi:[0,1]
	v_lshlrev_b32_e32 v68, 16, v69
	v_and_b32_e32 v69, 0xffff0000, v69
	s_waitcnt lgkmcnt(0)
	v_add_f32_e32 v1, v1, v5
	v_fmamk_f32 v1, v1, 0x3c000000, v235
	v_pk_mul_f32 v[6:7], v[6:7], v[66:67]
	v_rsq_f32_e32 v70, v1
	v_pk_mul_f32 v[68:69], v[108:109], v[68:69]
	v_cvt_pk_bf16_f32 v66, v6, v7
	v_pk_mul_f32 v[6:7], v[100:101], v[82:83] op_sel_hi:[1,0]
	v_cvt_pk_bf16_f32 v65, v68, v69
	v_pk_mul_f32 v[6:7], v[6:7], v[46:47] op_sel:[1,0] op_sel_hi:[0,1]
	v_lshlrev_b32_e32 v68, 16, v71
	v_and_b32_e32 v69, 0xffff0000, v71
	v_pk_mul_f32 v[74:75], v[74:75], v[82:83] op_sel_hi:[1,0]
	v_pk_mul_f32 v[6:7], v[6:7], v[68:69]
	v_pk_mul_f32 v[74:75], v[74:75], v[48:49]
	v_cvt_pk_bf16_f32 v67, v6, v7
	v_pk_mul_f32 v[6:7], v[144:145], v[70:71] op_sel_hi:[1,0]
	v_pk_mul_f32 v[74:75], v[74:75], v[162:163]
	v_pk_mul_f32 v[6:7], v[34:35], v[6:7]
	v_cvt_pk_bf16_f32 v64, v74, v75
	v_pk_mul_f32 v[6:7], v[6:7], v[136:137]
	global_store_dwordx4 v[98:99], v[64:67], off offset:128
	v_pk_mul_f32 v[154:155], v[138:139], v[138:139]
	v_pk_mul_f32 v[162:163], v[126:127], v[126:127]
	v_cvt_pk_bf16_f32 v64, v6, v7
	v_pk_mul_f32 v[6:7], v[130:131], v[70:71] op_sel_hi:[1,0]
	v_add_f32_e32 v1, v154, v155
	v_pk_mul_f32 v[6:7], v[36:37], v[6:7]
	v_pk_fma_f32 v[122:123], v[222:223], v[124:125], v[122:123] neg_lo:[1,0,0] neg_hi:[1,0,0]
	v_pk_mul_f32 v[6:7], v[6:7], v[134:135]
	v_add_f32_e32 v1, v162, v1
	v_cvt_pk_bf16_f32 v65, v6, v7
	v_pk_mul_f32 v[6:7], v[78:79], v[70:71] op_sel_hi:[1,0]
	v_pk_mul_f32 v[108:109], v[122:123], v[122:123]
	v_pk_mul_f32 v[6:7], v[6:7], v[30:31]
	v_add_f32_e32 v1, v163, v1
	v_pk_mul_f32 v[6:7], v[6:7], v[132:133]
	v_pk_fma_f32 v[118:119], v[222:223], v[120:121], v[118:119] neg_lo:[1,0,0] neg_hi:[1,0,0]
	v_cvt_pk_bf16_f32 v66, v6, v7
	v_pk_mul_f32 v[6:7], v[24:25], v[70:71] op_sel_hi:[1,0]
	v_add_f32_e32 v1, v108, v1
	v_pk_mul_f32 v[6:7], v[6:7], v[32:33]
	v_pk_mul_f32 v[158:159], v[118:119], v[118:119]
	v_pk_mul_f32 v[6:7], v[6:7], v[72:73]
	v_lshlrev_b32_e32 v24, 16, v60
	v_cvt_pk_bf16_f32 v67, v6, v7
	v_pk_mul_f32 v[6:7], v[28:29], v[70:71] op_sel_hi:[1,0]
	v_and_b32_e32 v25, 0xffff0000, v60
	v_lshlrev_b32_e32 v28, 16, v61
	v_and_b32_e32 v29, 0xffff0000, v61
	v_lshlrev_b32_e32 v60, 16, v8
	v_and_b32_e32 v61, 0xffff0000, v8
	v_lshlrev_b32_e32 v8, 16, v12
	v_and_b32_e32 v9, 0xffff0000, v12
	v_add_f32_e32 v1, v109, v1
	v_pk_fma_f32 v[12:13], v[222:223], v[8:9], v[60:61] neg_lo:[1,0,0] neg_hi:[1,0,0]
	v_add_f32_e32 v1, v158, v1
	v_pk_mul_f32 v[8:9], v[12:13], v[12:13]
	v_add_f32_e32 v1, v159, v1
	v_add_f32_e32 v1, v1, v8
	v_pk_mul_f32 v[76:77], v[56:57], v[56:57]
	v_add_f32_e32 v1, v9, v1
	v_add_f32_e32 v1, v77, v1
	v_pk_mul_f32 v[128:129], v[26:27], v[26:27]
	v_add_f32_e32 v1, v76, v1
	v_add_f32_e32 v1, v129, v1
	v_pk_mul_f32 v[142:143], v[10:11], v[10:11]
	v_add_f32_e32 v1, v128, v1
	v_add_f32_e32 v1, v143, v1
	v_add_f32_e32 v1, v142, v1
	ds_bpermute_b32 v5, v237, v1
	v_pk_mul_f32 v[6:7], v[6:7], v[48:49]
	v_lshlrev_b32_e32 v14, 16, v83
	v_pk_mul_f32 v[6:7], v[6:7], v[24:25]
	v_pk_mul_f32 v[24:25], v[110:111], v[70:71] op_sel_hi:[1,0]
	s_waitcnt lgkmcnt(0)
	v_add_f32_e32 v1, v1, v5
	ds_bpermute_b32 v5, v238, v1
	v_pk_mul_f32 v[24:25], v[24:25], v[50:51] op_sel:[1,0] op_sel_hi:[0,1]
	v_pk_mul_f32 v[8:9], v[24:25], v[28:29]
	v_cvt_pk_bf16_f32 v6, v6, v7
	v_cvt_pk_bf16_f32 v7, v8, v9
	s_waitcnt lgkmcnt(0)
	v_add_f32_e32 v1, v1, v5
	ds_bpermute_b32 v5, v239, v1
	v_pk_mul_f32 v[8:9], v[106:107], v[70:71] op_sel_hi:[1,0]
	v_lshlrev_b32_e32 v24, 16, v62
	v_pk_mul_f32 v[8:9], v[8:9], v[44:45] op_sel:[1,0] op_sel_hi:[0,1]
	v_and_b32_e32 v25, 0xffff0000, v62
	s_waitcnt lgkmcnt(0)
	v_add_f32_e32 v1, v1, v5
	v_fmamk_f32 v1, v1, 0x3c000000, v235
	v_pk_mul_f32 v[8:9], v[8:9], v[24:25]
	v_pk_mul_f32 v[24:25], v[104:105], v[70:71] op_sel_hi:[1,0]
	v_rsq_f32_e32 v60, v1
	v_pk_mul_f32 v[24:25], v[24:25], v[46:47] op_sel:[1,0] op_sel_hi:[0,1]
	v_lshlrev_b32_e32 v28, 16, v63
	v_and_b32_e32 v29, 0xffff0000, v63
	v_pk_mul_f32 v[24:25], v[24:25], v[28:29]
	v_cvt_pk_bf16_f32 v8, v8, v9
	v_cvt_pk_bf16_f32 v9, v24, v25
	global_store_dwordx4 v[96:97], v[6:9], off offset:128
	v_pk_mul_f32 v[24:25], v[118:119], v[60:61] op_sel_hi:[1,0]
	v_and_b32_e32 v15, 0xffff0000, v83
	v_pk_mul_f32 v[6:7], v[138:139], v[60:61] op_sel_hi:[1,0]
	v_pk_mul_f32 v[8:9], v[126:127], v[60:61] op_sel_hi:[1,0]
	v_pk_mul_f32 v[6:7], v[34:35], v[6:7]
	v_pk_mul_f32 v[8:9], v[36:37], v[8:9]
	v_pk_mul_f32 v[6:7], v[6:7], v[42:43]
	v_pk_mul_f32 v[8:9], v[8:9], v[116:117]
	v_cvt_pk_bf16_f32 v6, v6, v7
	v_cvt_pk_bf16_f32 v7, v8, v9
	v_pk_mul_f32 v[8:9], v[122:123], v[60:61] op_sel_hi:[1,0]
	v_pk_mul_f32 v[24:25], v[24:25], v[32:33]
	v_pk_mul_f32 v[8:9], v[30:31], v[8:9]
	v_pk_mul_f32 v[14:15], v[24:25], v[14:15]
	v_pk_mul_f32 v[8:9], v[8:9], v[58:59]
	v_pk_fma_f32 v[160:161], v[222:223], v[248:249], v[164:165] neg_lo:[1,0,0] neg_hi:[1,0,0]
	v_cvt_pk_bf16_f32 v8, v8, v9
	v_cvt_pk_bf16_f32 v9, v14, v15
	global_store_dwordx4 v[94:95], v[6:9], off
	v_pk_mul_f32 v[112:113], v[160:161], v[160:161]
	v_pk_mul_f32 v[164:165], v[156:157], v[156:157]
	v_pk_mul_f32 v[6:7], v[12:13], v[60:61] op_sel_hi:[1,0]
	v_lshlrev_b32_e32 v8, 16, v52
	v_pk_mul_f32 v[6:7], v[6:7], v[48:49]
	v_and_b32_e32 v9, 0xffff0000, v52
	v_pk_mul_f32 v[6:7], v[6:7], v[8:9]
	v_pk_mul_f32 v[140:141], v[152:153], v[152:153]
	v_cvt_pk_bf16_f32 v6, v6, v7
	v_add_f32_e32 v7, v112, v113
	v_add_f32_e32 v7, v164, v7
	v_add_f32_e32 v7, v165, v7
	v_add_f32_e32 v7, v140, v7
	v_pk_mul_f32 v[150:151], v[148:149], v[148:149]
	v_lshlrev_b32_e32 v14, 16, v4
	v_and_b32_e32 v15, 0xffff0000, v4
	v_lshlrev_b32_e32 v4, 16, v0
	v_and_b32_e32 v5, 0xffff0000, v0
	v_add_f32_e32 v7, v141, v7
	v_pk_fma_f32 v[0:1], v[222:223], v[4:5], v[14:15] neg_lo:[1,0,0] neg_hi:[1,0,0]
	v_add_f32_e32 v7, v150, v7
	v_pk_mul_f32 v[4:5], v[0:1], v[0:1]
	v_add_f32_e32 v7, v151, v7
	v_add_f32_e32 v4, v7, v4
	v_pk_mul_f32 v[146:147], v[20:21], v[20:21]
	v_add_f32_e32 v4, v5, v4
	v_add_f32_e32 v4, v147, v4
	v_pk_mul_f32 v[120:121], v[16:17], v[16:17]
	v_add_f32_e32 v4, v146, v4
	v_add_f32_e32 v4, v121, v4
	v_pk_mul_f32 v[124:125], v[2:3], v[2:3]
	v_add_f32_e32 v4, v120, v4
	v_add_f32_e32 v4, v125, v4
	v_add_f32_e32 v14, v124, v4
	ds_bpermute_b32 v15, v237, v14
	v_pk_mul_f32 v[8:9], v[56:57], v[60:61] op_sel_hi:[1,0]
	v_lshlrev_b32_e32 v12, 16, v53
	v_pk_mul_f32 v[8:9], v[8:9], v[50:51] op_sel:[1,0] op_sel_hi:[0,1]
	v_and_b32_e32 v13, 0xffff0000, v53
	v_pk_mul_f32 v[4:5], v[8:9], v[12:13]
	s_waitcnt lgkmcnt(0)
	v_add_f32_e32 v12, v14, v15
	ds_bpermute_b32 v13, v238, v12
	v_cvt_pk_bf16_f32 v7, v4, v5
	v_pk_mul_f32 v[4:5], v[26:27], v[60:61] op_sel_hi:[1,0]
	v_lshlrev_b32_e32 v8, 16, v54
	v_pk_mul_f32 v[4:5], v[4:5], v[44:45] op_sel:[1,0] op_sel_hi:[0,1]
	v_and_b32_e32 v9, 0xffff0000, v54
	v_pk_mul_f32 v[4:5], v[4:5], v[8:9]
	s_waitcnt lgkmcnt(0)
	v_add_f32_e32 v9, v12, v13
	ds_bpermute_b32 v12, v239, v9
	v_cvt_pk_bf16_f32 v8, v4, v5
	v_pk_mul_f32 v[4:5], v[10:11], v[60:61] op_sel_hi:[1,0]
	v_lshlrev_b32_e32 v10, 16, v55
	v_pk_mul_f32 v[4:5], v[4:5], v[46:47] op_sel:[1,0] op_sel_hi:[0,1]
	s_waitcnt lgkmcnt(0)
	v_add_f32_e32 v9, v9, v12
	v_fmamk_f32 v9, v9, 0x3c000000, v235
	v_rsq_f32_e32 v12, v9
	v_and_b32_e32 v11, 0xffff0000, v55
	v_pk_mul_f32 v[4:5], v[4:5], v[10:11]
	global_store_dwordx4 v[96:97], v[64:67], off
	v_cvt_pk_bf16_f32 v9, v4, v5
	global_store_dwordx4 v[94:95], v[6:9], off offset:128
	v_pk_mul_f32 v[4:5], v[160:161], v[12:13] op_sel_hi:[1,0]
	v_pk_mul_f32 v[0:1], v[0:1], v[12:13] op_sel_hi:[1,0]
	v_pk_mul_f32 v[6:7], v[156:157], v[12:13] op_sel_hi:[1,0]
	v_pk_mul_f32 v[4:5], v[34:35], v[4:5]
	v_pk_mul_f32 v[6:7], v[36:37], v[6:7]
	v_pk_mul_f32 v[4:5], v[4:5], v[250:251]
	v_pk_mul_f32 v[6:7], v[6:7], v[80:81]
	v_cvt_pk_bf16_f32 v4, v4, v5
	v_cvt_pk_bf16_f32 v5, v6, v7
	v_pk_mul_f32 v[6:7], v[152:153], v[12:13] op_sel_hi:[1,0]
	v_pk_mul_f32 v[8:9], v[148:149], v[12:13] op_sel_hi:[1,0]
	v_pk_mul_f32 v[6:7], v[30:31], v[6:7]
	v_pk_mul_f32 v[8:9], v[32:33], v[8:9]
	v_pk_mul_f32 v[6:7], v[6:7], v[18:19]
	v_pk_mul_f32 v[8:9], v[8:9], v[22:23]
	v_cvt_pk_bf16_f32 v6, v6, v7
	v_cvt_pk_bf16_f32 v7, v8, v9
	global_store_dwordx4 v[92:93], v[4:7], off
	v_pk_mul_f32 v[0:1], v[0:1], v[48:49]
	s_waitcnt vmcnt(6)
	v_lshlrev_b32_e32 v4, 16, v38
	v_and_b32_e32 v5, 0xffff0000, v38
	v_pk_mul_f32 v[0:1], v[0:1], v[4:5]
	v_lshlrev_b32_e32 v6, 16, v39
	v_cvt_pk_bf16_f32 v4, v0, v1
	v_pk_mul_f32 v[0:1], v[20:21], v[12:13] op_sel_hi:[1,0]
	v_and_b32_e32 v7, 0xffff0000, v39
	v_pk_mul_f32 v[0:1], v[0:1], v[50:51] op_sel:[1,0] op_sel_hi:[0,1]
	v_pk_mul_f32 v[0:1], v[0:1], v[6:7]
	v_lshlrev_b32_e32 v6, 16, v40
	v_cvt_pk_bf16_f32 v5, v0, v1
	v_pk_mul_f32 v[0:1], v[16:17], v[12:13] op_sel_hi:[1,0]
	v_and_b32_e32 v7, 0xffff0000, v40
	v_pk_mul_f32 v[0:1], v[0:1], v[44:45] op_sel:[1,0] op_sel_hi:[0,1]
	v_pk_mul_f32 v[0:1], v[0:1], v[6:7]
	s_nop 0
	v_cvt_pk_bf16_f32 v6, v0, v1
	v_pk_mul_f32 v[0:1], v[2:3], v[12:13] op_sel_hi:[1,0]
	v_lshlrev_b32_e32 v2, 16, v41
	v_pk_mul_f32 v[0:1], v[0:1], v[46:47] op_sel:[1,0] op_sel_hi:[0,1]
	v_and_b32_e32 v3, 0xffff0000, v41
	v_pk_mul_f32 v[0:1], v[0:1], v[2:3]
	s_nop 0
	v_cvt_pk_bf16_f32 v7, v0, v1
	global_store_dwordx4 v[92:93], v[4:7], off offset:128

.LBB0_705:
	s_or_b64 exec, exec, s[0:1]
	s_and_b32 s3, s93, 0x60
	s_lshl_b32 s33, s3, 7
	s_cmpk_lt_i32 s97, 0x200
	v_mov_b32_e32 v8, v234
	s_cselect_b64 s[4:5], -1, 0
	s_cmpk_gt_i32 s97, 0x1ff
	s_barrier
	s_mov_b32 s99, 0
	s_cbranch_scc1 .LBB0_730
	s_ashr_i32 s18, s97, 31
	s_lshr_b32 s0, s18, 29
	s_add_i32 s8, s97, s0
	s_and_b32 s0, s8, -8
	s_sub_i32 s9, s97, s0
	s_cmp_gt_i32 s9, -1
	s_cbranch_scc0 .LBB0_708
	s_lshl_b32 s2, s9, 6
	s_mov_b64 s[0:1], 0
	s_branch .LBB0_709

.LBB0_715:
	s_mov_b32 s99, 1
	s_andn2_b64 vcc, exec, s[0:1]
	s_mov_b32 s2, s16
	s_mov_b32 s38, s28
	s_mov_b64 s[42:43], s[34:35]
	s_mov_b64 s[40:41], s[30:31]
	s_cbranch_vccz .LBB0_729

.LBB0_723:
	ds_read_b128 v[40:43], v167
	ds_read_b128 v[44:47], v167 offset:1024
	ds_read_b128 v[64:67], v167 offset:2048
	ds_read_b128 v[68:71], v167 offset:3072
	ds_read_b128 v[160:163], v168
	ds_read_b128 v[170:173], v168 offset:1024
	ds_read_b128 v[174:177], v168 offset:2048
	ds_read_b128 v[178:181], v168 offset:3072
	s_add_u32 s42, s40, 0xfffc0080
	s_addc_u32 s43, s41, -1
	s_cmp_eq_u32 s55, 12
	s_cselect_b32 s45, s24, s43
	s_cselect_b32 s44, s25, s42
	s_cselect_b32 s43, s17, s54
	s_cselect_b32 s42, s29, s53
	v_lshl_add_u64 v[214:215], s[40:41], 0, v[152:153]
	s_add_i32 m0, s19, 0xc000
	ds_read_b128 v[182:185], v169
	ds_read_b128 v[186:189], v169 offset:1024
	ds_read_b128 v[190:193], v169 offset:2048
	ds_read_b128 v[194:197], v169 offset:3072
	ds_read_b128 v[198:201], v169 offset:4096
	ds_read_b128 v[202:205], v169 offset:5120
	ds_read_b128 v[206:209], v169 offset:6144
	ds_read_b128 v[210:213], v169 offset:7168
	global_load_lds_dwordx4 v[214:215], off
	v_lshl_add_u64 v[214:215], s[40:41], 0, v[154:155]
	s_add_i32 m0, s19, 0xe000
	s_nop 0
	global_load_lds_dwordx4 v[214:215], off
	s_cmp_eq_u32 s99, 0
	s_cbranch_scc1 .Lmy_wb1n
	s_waitcnt vmcnt(24)
	s_branch .Lmy_wb1d

.Lmy_wb1d:
	s_waitcnt lgkmcnt(0)
	s_barrier
	s_setprio 1
	s_waitcnt lgkmcnt(0)
	v_mfma_f32_16x16x32_bf16 v[140:143], v[40:43], v[182:185], v[140:143]
	v_mfma_f32_16x16x32_bf16 v[136:139], v[64:67], v[182:185], v[136:139]
	v_mfma_f32_16x16x32_bf16 v[124:127], v[40:43], v[190:193], v[124:127]
	v_mfma_f32_16x16x32_bf16 v[120:123], v[64:67], v[190:193], v[120:123]
	v_mfma_f32_16x16x32_bf16 v[108:111], v[40:43], v[198:201], v[108:111]
	v_mfma_f32_16x16x32_bf16 v[104:107], v[64:67], v[198:201], v[104:107]
	v_mfma_f32_16x16x32_bf16 v[92:95], v[40:43], v[206:209], v[92:95]
	v_mfma_f32_16x16x32_bf16 v[88:91], v[64:67], v[206:209], v[88:91]
	v_mfma_f32_16x16x32_bf16 v[140:143], v[44:47], v[186:189], v[140:143]
	v_mfma_f32_16x16x32_bf16 v[136:139], v[68:71], v[186:189], v[136:139]
	v_mfma_f32_16x16x32_bf16 v[124:127], v[44:47], v[194:197], v[124:127]
	v_mfma_f32_16x16x32_bf16 v[120:123], v[68:71], v[194:197], v[120:123]
	v_mfma_f32_16x16x32_bf16 v[108:111], v[44:47], v[202:205], v[108:111]
	v_mfma_f32_16x16x32_bf16 v[104:107], v[68:71], v[202:205], v[104:107]
	v_mfma_f32_16x16x32_bf16 v[92:95], v[44:47], v[210:213], v[92:95]
	v_mfma_f32_16x16x32_bf16 v[88:91], v[68:71], v[210:213], v[88:91]
	s_setprio 0
	s_setprio 1
	v_mfma_f32_16x16x32_bf16 v[132:135], v[160:163], v[182:185], v[132:135]
	v_mfma_f32_16x16x32_bf16 v[128:131], v[174:177], v[182:185], v[128:131]
	v_mfma_f32_16x16x32_bf16 v[116:119], v[160:163], v[190:193], v[116:119]
	v_mfma_f32_16x16x32_bf16 v[112:115], v[174:177], v[190:193], v[112:115]
	v_mfma_f32_16x16x32_bf16 v[100:103], v[160:163], v[198:201], v[100:103]
	v_mfma_f32_16x16x32_bf16 v[96:99], v[174:177], v[198:201], v[96:99]
	v_mfma_f32_16x16x32_bf16 v[84:87], v[160:163], v[206:209], v[84:87]
	v_mfma_f32_16x16x32_bf16 v[80:83], v[174:177], v[206:209], v[80:83]
	v_mfma_f32_16x16x32_bf16 v[132:135], v[170:173], v[186:189], v[132:135]
	v_mfma_f32_16x16x32_bf16 v[128:131], v[178:181], v[186:189], v[128:131]
	v_mfma_f32_16x16x32_bf16 v[116:119], v[170:173], v[194:197], v[116:119]
	v_mfma_f32_16x16x32_bf16 v[112:115], v[178:181], v[194:197], v[112:115]
	v_mfma_f32_16x16x32_bf16 v[100:103], v[170:173], v[202:205], v[100:103]
	v_mfma_f32_16x16x32_bf16 v[96:99], v[178:181], v[202:205], v[96:99]
	v_mfma_f32_16x16x32_bf16 v[84:87], v[170:173], v[210:213], v[84:87]
	v_mfma_f32_16x16x32_bf16 v[80:83], v[178:181], v[210:213], v[80:83]
	s_setprio 0
	s_barrier
	s_add_i32 s56, s51, s88
	v_lshl_add_u64 v[214:215], s[42:43], 0, v[146:147]
	s_mov_b32 m0, s56
	ds_read_b128 v[182:185], v169 offset:16384
	ds_read_b128 v[186:189], v169 offset:17408
	ds_read_b128 v[190:193], v169 offset:18432
	ds_read_b128 v[194:197], v169 offset:19456
	ds_read_b128 v[198:201], v169 offset:20480
	ds_read_b128 v[202:205], v169 offset:21504
	ds_read_b128 v[206:209], v169 offset:22528
	ds_read_b128 v[210:213], v169 offset:23552
	global_load_lds_dwordx4 v[214:215], off
	s_add_i32 m0, s56, 0x2000
	s_add_u32 s56, s42, 0x40000
	v_lshl_add_u64 v[216:217], s[42:43], 0, v[150:151]
	s_addc_u32 s57, s43, 0
	s_add_i32 s58, s52, s88
	global_load_lds_dwordx4 v[216:217], off
	v_lshl_add_u64 v[218:219], s[56:57], 0, v[146:147]
	s_mov_b32 m0, s58
	v_lshl_add_u64 v[220:221], s[44:45], 0, v[148:149]
	global_load_lds_dwordx4 v[218:219], off
	v_lshl_add_u64 v[218:219], s[56:57], 0, v[150:151]
	s_add_i32 m0, s58, 0x2000
	s_nop 0
	global_load_lds_dwordx4 v[218:219], off
	v_lshl_add_u64 v[218:219], s[44:45], 0, v[144:145]
	s_mov_b32 m0, s19
	s_nop 0
	global_load_lds_dwordx4 v[218:219], off
	s_mov_b32 m0, s26
	s_nop 0
	global_load_lds_dwordx4 v[220:221], off
	s_cmp_eq_u32 s99, 0
	s_cbranch_scc1 .Lmy_wb2n
	s_waitcnt vmcnt(24)
	s_mov_b32 s99, 0
	s_branch .Lmy_wb2d

.Lmy_wb2d:
	s_waitcnt lgkmcnt(0)
	s_barrier
	s_setprio 1
	s_waitcnt lgkmcnt(0)
	v_mfma_f32_16x16x32_bf16 v[76:79], v[40:43], v[182:185], v[76:79]
	v_mfma_f32_16x16x32_bf16 v[72:75], v[64:67], v[182:185], v[72:75]
	v_mfma_f32_16x16x32_bf16 v[52:55], v[40:43], v[190:193], v[52:55]
	v_mfma_f32_16x16x32_bf16 v[48:51], v[64:67], v[190:193], v[48:51]
	v_mfma_f32_16x16x32_bf16 v[28:31], v[40:43], v[198:201], v[28:31]
	v_mfma_f32_16x16x32_bf16 v[24:27], v[64:67], v[198:201], v[24:27]
	v_mfma_f32_16x16x32_bf16 v[12:15], v[40:43], v[206:209], v[12:15]
	v_mfma_f32_16x16x32_bf16 v[8:11], v[64:67], v[206:209], v[8:11]
	v_mfma_f32_16x16x32_bf16 v[76:79], v[44:47], v[186:189], v[76:79]
	v_mfma_f32_16x16x32_bf16 v[72:75], v[68:71], v[186:189], v[72:75]
	v_mfma_f32_16x16x32_bf16 v[52:55], v[44:47], v[194:197], v[52:55]
	v_mfma_f32_16x16x32_bf16 v[48:51], v[68:71], v[194:197], v[48:51]
	v_mfma_f32_16x16x32_bf16 v[28:31], v[44:47], v[202:205], v[28:31]
	v_mfma_f32_16x16x32_bf16 v[24:27], v[68:71], v[202:205], v[24:27]
	v_mfma_f32_16x16x32_bf16 v[12:15], v[44:47], v[210:213], v[12:15]
	v_mfma_f32_16x16x32_bf16 v[8:11], v[68:71], v[210:213], v[8:11]
	s_setprio 0
	s_setprio 1
	v_mfma_f32_16x16x32_bf16 v[36:39], v[160:163], v[190:193], v[36:39]
	v_mfma_f32_16x16x32_bf16 v[32:35], v[174:177], v[190:193], v[32:35]
	v_mfma_f32_16x16x32_bf16 v[20:23], v[160:163], v[198:201], v[20:23]
	v_mfma_f32_16x16x32_bf16 v[16:19], v[174:177], v[198:201], v[16:19]
	v_mfma_f32_16x16x32_bf16 v[4:7], v[160:163], v[206:209], v[4:7]
	v_mfma_f32_16x16x32_bf16 v[0:3], v[174:177], v[206:209], v[0:3]
	v_mfma_f32_16x16x32_bf16 v[40:43], v[160:163], v[182:185], v[60:63]
	v_mfma_f32_16x16x32_bf16 v[44:47], v[174:177], v[182:185], v[56:59]
	v_mfma_f32_16x16x32_bf16 v[36:39], v[170:173], v[194:197], v[36:39]
	v_mfma_f32_16x16x32_bf16 v[32:35], v[178:181], v[194:197], v[32:35]
	v_mfma_f32_16x16x32_bf16 v[20:23], v[170:173], v[202:205], v[20:23]
	v_mfma_f32_16x16x32_bf16 v[16:19], v[178:181], v[202:205], v[16:19]
	v_mfma_f32_16x16x32_bf16 v[4:7], v[170:173], v[210:213], v[4:7]
	v_mfma_f32_16x16x32_bf16 v[0:3], v[178:181], v[210:213], v[0:3]
	v_mfma_f32_16x16x32_bf16 v[40:43], v[170:173], v[186:189], v[40:43]
	v_mfma_f32_16x16x32_bf16 v[44:47], v[178:181], v[186:189], v[44:47]
	s_setprio 0
	s_barrier
	s_add_i32 s56, 0, 0x18000
	s_add_i32 s57, 0, 0x1c000
	v_add_u32_e32 v68, s56, v165
	v_add_u32_e32 v178, s57, v165
	ds_read_b128 v[56:59], v68
	ds_read_b128 v[60:63], v68 offset:1024
	ds_read_b128 v[64:67], v68 offset:2048
	ds_read_b128 v[68:71], v68 offset:3072
	ds_read_b128 v[160:163], v178
	ds_read_b128 v[170:173], v178 offset:1024
	ds_read_b128 v[174:177], v178 offset:2048
	ds_read_b128 v[178:181], v178 offset:3072
	s_add_u32 s44, s44, 0x40000
	s_addc_u32 s45, s45, 0
	s_mov_b32 m0, s27
	v_lshl_add_u64 v[222:223], s[44:45], 0, v[144:145]
	ds_read_b128 v[182:185], v169 offset:32768
	ds_read_b128 v[186:189], v169 offset:33792
	ds_read_b128 v[190:193], v169 offset:34816
	ds_read_b128 v[194:197], v169 offset:35840
	ds_read_b128 v[198:201], v169 offset:36864
	ds_read_b128 v[202:205], v169 offset:37888
	ds_read_b128 v[206:209], v169 offset:38912
	ds_read_b128 v[210:213], v169 offset:39936
	global_load_lds_dwordx4 v[222:223], off
	v_lshl_add_u64 v[222:223], s[44:45], 0, v[148:149]
	s_mov_b32 m0, s39
	s_nop 0
	global_load_lds_dwordx4 v[222:223], off
	s_waitcnt vmcnt(8)
	s_waitcnt lgkmcnt(0)
	s_barrier
	s_setprio 1
	s_waitcnt lgkmcnt(0)
	v_mfma_f32_16x16x32_bf16 v[140:143], v[56:59], v[182:185], v[140:143]
	v_mfma_f32_16x16x32_bf16 v[136:139], v[64:67], v[182:185], v[136:139]
	v_mfma_f32_16x16x32_bf16 v[124:127], v[56:59], v[190:193], v[124:127]
	v_mfma_f32_16x16x32_bf16 v[120:123], v[64:67], v[190:193], v[120:123]
	v_mfma_f32_16x16x32_bf16 v[108:111], v[56:59], v[198:201], v[108:111]
	v_mfma_f32_16x16x32_bf16 v[104:107], v[64:67], v[198:201], v[104:107]
	v_mfma_f32_16x16x32_bf16 v[92:95], v[56:59], v[206:209], v[92:95]
	v_mfma_f32_16x16x32_bf16 v[88:91], v[64:67], v[206:209], v[88:91]
	v_mfma_f32_16x16x32_bf16 v[140:143], v[60:63], v[186:189], v[140:143]
	v_mfma_f32_16x16x32_bf16 v[136:139], v[68:71], v[186:189], v[136:139]
	v_mfma_f32_16x16x32_bf16 v[124:127], v[60:63], v[194:197], v[124:127]
	v_mfma_f32_16x16x32_bf16 v[120:123], v[68:71], v[194:197], v[120:123]
	v_mfma_f32_16x16x32_bf16 v[108:111], v[60:63], v[202:205], v[108:111]
	v_mfma_f32_16x16x32_bf16 v[104:107], v[68:71], v[202:205], v[104:107]
	v_mfma_f32_16x16x32_bf16 v[92:95], v[60:63], v[210:213], v[92:95]
	v_mfma_f32_16x16x32_bf16 v[88:91], v[68:71], v[210:213], v[88:91]
	s_setprio 0
	s_setprio 1
	v_mfma_f32_16x16x32_bf16 v[132:135], v[160:163], v[182:185], v[132:135]
	v_mfma_f32_16x16x32_bf16 v[128:131], v[174:177], v[182:185], v[128:131]
	v_mfma_f32_16x16x32_bf16 v[116:119], v[160:163], v[190:193], v[116:119]
	v_mfma_f32_16x16x32_bf16 v[112:115], v[174:177], v[190:193], v[112:115]
	v_mfma_f32_16x16x32_bf16 v[100:103], v[160:163], v[198:201], v[100:103]
	v_mfma_f32_16x16x32_bf16 v[96:99], v[174:177], v[198:201], v[96:99]
	v_mfma_f32_16x16x32_bf16 v[84:87], v[160:163], v[206:209], v[84:87]
	v_mfma_f32_16x16x32_bf16 v[80:83], v[174:177], v[206:209], v[80:83]
	v_mfma_f32_16x16x32_bf16 v[132:135], v[170:173], v[186:189], v[132:135]
	v_mfma_f32_16x16x32_bf16 v[128:131], v[178:181], v[186:189], v[128:131]
	v_mfma_f32_16x16x32_bf16 v[116:119], v[170:173], v[194:197], v[116:119]
	v_mfma_f32_16x16x32_bf16 v[112:115], v[178:181], v[194:197], v[112:115]
	v_mfma_f32_16x16x32_bf16 v[100:103], v[170:173], v[202:205], v[100:103]
	v_mfma_f32_16x16x32_bf16 v[96:99], v[178:181], v[202:205], v[96:99]
	v_mfma_f32_16x16x32_bf16 v[84:87], v[170:173], v[210:213], v[84:87]
	v_mfma_f32_16x16x32_bf16 v[80:83], v[178:181], v[210:213], v[80:83]
	s_setprio 0
	s_barrier
	s_add_i32 s44, s56, s88
	v_lshl_add_u64 v[214:215], v[214:215], 0, s[12:13]
	s_mov_b32 m0, s44
	ds_read_b128 v[182:185], v169 offset:49152
	ds_read_b128 v[186:189], v169 offset:50176
	ds_read_b128 v[190:193], v169 offset:51200
	ds_read_b128 v[194:197], v169 offset:52224
	ds_read_b128 v[198:201], v169 offset:53248
	ds_read_b128 v[202:205], v169 offset:54272
	ds_read_b128 v[206:209], v169 offset:55296
	ds_read_b128 v[210:213], v169 offset:56320
	global_load_lds_dwordx4 v[214:215], off
	s_add_i32 m0, s44, 0x2000
	s_add_u32 s42, s42, 0x40080
	v_lshl_add_u64 v[214:215], v[216:217], 0, s[12:13]
	s_addc_u32 s43, s43, 0
	s_add_i32 s44, s57, s88
	global_load_lds_dwordx4 v[214:215], off
	v_lshl_add_u64 v[214:215], s[42:43], 0, v[146:147]
	s_mov_b32 m0, s44
	s_nop 0
	global_load_lds_dwordx4 v[214:215], off
	v_lshl_add_u64 v[214:215], s[42:43], 0, v[150:151]
	s_add_i32 m0, s44, 0x2000
	s_nop 0
	global_load_lds_dwordx4 v[214:215], off
	v_lshl_add_u64 v[214:215], v[218:219], 0, s[12:13]
	s_mov_b32 m0, s47
	s_nop 0
	global_load_lds_dwordx4 v[214:215], off
	v_lshl_add_u64 v[214:215], v[220:221], 0, s[12:13]
	s_mov_b32 m0, s48
	s_nop 0
	global_load_lds_dwordx4 v[214:215], off
	s_waitcnt vmcnt(8)
	s_waitcnt lgkmcnt(0)
	s_barrier
	s_setprio 1
	s_waitcnt lgkmcnt(0)
	v_mfma_f32_16x16x32_bf16 v[76:79], v[56:59], v[182:185], v[76:79]
	v_mfma_f32_16x16x32_bf16 v[72:75], v[64:67], v[182:185], v[72:75]
	v_mfma_f32_16x16x32_bf16 v[52:55], v[56:59], v[190:193], v[52:55]
	v_mfma_f32_16x16x32_bf16 v[48:51], v[64:67], v[190:193], v[48:51]
	v_mfma_f32_16x16x32_bf16 v[28:31], v[56:59], v[198:201], v[28:31]
	v_mfma_f32_16x16x32_bf16 v[24:27], v[64:67], v[198:201], v[24:27]
	v_mfma_f32_16x16x32_bf16 v[12:15], v[56:59], v[206:209], v[12:15]
	v_mfma_f32_16x16x32_bf16 v[8:11], v[64:67], v[206:209], v[8:11]
	v_mfma_f32_16x16x32_bf16 v[76:79], v[60:63], v[186:189], v[76:79]
	v_mfma_f32_16x16x32_bf16 v[72:75], v[68:71], v[186:189], v[72:75]
	v_mfma_f32_16x16x32_bf16 v[52:55], v[60:63], v[194:197], v[52:55]
	v_mfma_f32_16x16x32_bf16 v[48:51], v[68:71], v[194:197], v[48:51]
	v_mfma_f32_16x16x32_bf16 v[28:31], v[60:63], v[202:205], v[28:31]
	v_mfma_f32_16x16x32_bf16 v[24:27], v[68:71], v[202:205], v[24:27]
	v_mfma_f32_16x16x32_bf16 v[12:15], v[60:63], v[210:213], v[12:15]
	v_mfma_f32_16x16x32_bf16 v[8:11], v[68:71], v[210:213], v[8:11]
	s_setprio 0
	s_setprio 1
	v_mfma_f32_16x16x32_bf16 v[40:43], v[160:163], v[182:185], v[40:43]
	v_mfma_f32_16x16x32_bf16 v[60:63], v[170:173], v[186:189], v[40:43]
	v_mfma_f32_16x16x32_bf16 v[40:43], v[174:177], v[182:185], v[44:47]
	v_mfma_f32_16x16x32_bf16 v[36:39], v[160:163], v[190:193], v[36:39]
	v_mfma_f32_16x16x32_bf16 v[32:35], v[174:177], v[190:193], v[32:35]
	v_mfma_f32_16x16x32_bf16 v[20:23], v[160:163], v[198:201], v[20:23]
	v_mfma_f32_16x16x32_bf16 v[16:19], v[174:177], v[198:201], v[16:19]
	v_mfma_f32_16x16x32_bf16 v[4:7], v[160:163], v[206:209], v[4:7]
	v_mfma_f32_16x16x32_bf16 v[0:3], v[174:177], v[206:209], v[0:3]
	v_mfma_f32_16x16x32_bf16 v[56:59], v[178:181], v[186:189], v[40:43]
	v_mfma_f32_16x16x32_bf16 v[36:39], v[170:173], v[194:197], v[36:39]
	v_mfma_f32_16x16x32_bf16 v[32:35], v[178:181], v[194:197], v[32:35]
	v_mfma_f32_16x16x32_bf16 v[20:23], v[170:173], v[202:205], v[20:23]
	v_mfma_f32_16x16x32_bf16 v[16:19], v[178:181], v[202:205], v[16:19]
	v_mfma_f32_16x16x32_bf16 v[4:7], v[170:173], v[210:213], v[4:7]
	v_mfma_f32_16x16x32_bf16 v[0:3], v[178:181], v[210:213], v[0:3]
	s_setprio 0
	s_barrier
	s_add_i32 s55, s55, 2
	s_add_u32 s40, s40, 0x100
	s_addc_u32 s41, s41, 0
	s_add_u32 s53, s53, 0x100
	s_addc_u32 s54, s54, 0
	s_cmp_gt_u32 s55, 13
	s_cbranch_scc0 .LBB0_723
	s_and_b64 vcc, exec, s[14:15]
	s_cbranch_vccz .LBB0_726
	s_barrier

.LBB0_782:
	s_or_b64 exec, exec, s[0:1]
	s_andn2_b64 vcc, exec, s[4:5]
	s_waitcnt lgkmcnt(0)
	s_barrier
	s_mov_b32 s99, 0
	s_cbranch_vccnz .LBB0_806
	s_ashr_i32 s2, s97, 31
	s_lshr_b32 s0, s2, 29
	s_add_i32 s8, s97, s0
	s_and_b32 s0, s8, -8
	s_sub_i32 s5, s97, s0
	s_cmp_gt_i32 s5, -1
	s_cbranch_scc0 .LBB0_785
	s_lshl_b32 s4, s5, 6
	s_ashr_i32 s0, s8, 3
	s_cbranch_execz .LBB0_786
	s_branch .LBB0_787

.LBB0_791:
	s_mov_b32 s99, 1
	s_andn2_b64 vcc, exec, s[0:1]
	s_mov_b32 s54, s28
	s_mov_b32 s40, s30
	s_mov_b64 s[44:45], s[38:39]
	s_mov_b64 s[42:43], s[34:35]
	s_cbranch_vccz .LBB0_805

.LBB0_799:
	ds_read_b128 v[128:131], v169
	ds_read_b128 v[132:135], v169 offset:1024
	ds_read_b128 v[136:139], v169 offset:2048
	ds_read_b128 v[140:143], v169 offset:3072
	ds_read_b128 v[160:163], v170
	ds_read_b128 v[172:175], v170 offset:1024
	ds_read_b128 v[176:179], v170 offset:2048
	ds_read_b128 v[180:183], v170 offset:3072
	s_add_u32 s44, s42, 0xfff80080
	s_addc_u32 s45, s43, -1
	s_cmp_eq_u32 s59, 28
	s_cselect_b32 s47, s31, s45
	s_cselect_b32 s46, s55, s44
	s_cselect_b32 s45, s29, s58
	s_cselect_b32 s44, s56, s57
	v_lshl_add_u64 v[164:165], s[42:43], 0, v[152:153]
	s_add_i32 m0, s24, 0xc000
	ds_read_b128 v[184:187], v171
	ds_read_b128 v[188:191], v171 offset:1024
	ds_read_b128 v[192:195], v171 offset:2048
	ds_read_b128 v[196:199], v171 offset:3072
	ds_read_b128 v[200:203], v171 offset:4096
	ds_read_b128 v[204:207], v171 offset:5120
	ds_read_b128 v[208:211], v171 offset:6144
	ds_read_b128 v[212:215], v171 offset:7168
	global_load_lds_dwordx4 v[164:165], off
	v_lshl_add_u64 v[164:165], s[42:43], 0, v[154:155]
	s_add_i32 m0, s24, 0xe000
	s_nop 0
	global_load_lds_dwordx4 v[164:165], off
	s_cmp_eq_u32 s99, 0
	s_cbranch_scc1 .Lmy_wc1n
	s_waitcnt vmcnt(40)
	s_branch .Lmy_wc1d

.Lmy_wc1d:
	s_waitcnt lgkmcnt(0)
	s_barrier
	s_setprio 1
	s_waitcnt lgkmcnt(0)
	v_mfma_f32_16x16x32_bf16 v[120:123], v[128:131], v[184:187], v[120:123]
	v_mfma_f32_16x16x32_bf16 v[124:127], v[136:139], v[184:187], v[124:127]
	v_mfma_f32_16x16x32_bf16 v[112:115], v[128:131], v[192:195], v[112:115]
	v_mfma_f32_16x16x32_bf16 v[116:119], v[136:139], v[192:195], v[116:119]
	v_mfma_f32_16x16x32_bf16 v[92:95], v[128:131], v[200:203], v[92:95]
	v_mfma_f32_16x16x32_bf16 v[88:91], v[136:139], v[200:203], v[88:91]
	v_mfma_f32_16x16x32_bf16 v[84:87], v[128:131], v[208:211], v[84:87]
	v_mfma_f32_16x16x32_bf16 v[80:83], v[136:139], v[208:211], v[80:83]
	v_mfma_f32_16x16x32_bf16 v[120:123], v[132:135], v[188:191], v[120:123]
	v_mfma_f32_16x16x32_bf16 v[124:127], v[140:143], v[188:191], v[124:127]
	v_mfma_f32_16x16x32_bf16 v[112:115], v[132:135], v[196:199], v[112:115]
	v_mfma_f32_16x16x32_bf16 v[116:119], v[140:143], v[196:199], v[116:119]
	v_mfma_f32_16x16x32_bf16 v[92:95], v[132:135], v[204:207], v[92:95]
	v_mfma_f32_16x16x32_bf16 v[88:91], v[140:143], v[204:207], v[88:91]
	v_mfma_f32_16x16x32_bf16 v[84:87], v[132:135], v[212:215], v[84:87]
	v_mfma_f32_16x16x32_bf16 v[80:83], v[140:143], v[212:215], v[80:83]
	s_setprio 0
	s_setprio 1
	v_mfma_f32_16x16x32_bf16 v[108:111], v[160:163], v[184:187], v[108:111]
	v_mfma_f32_16x16x32_bf16 v[100:103], v[176:179], v[184:187], v[100:103]
	v_mfma_f32_16x16x32_bf16 v[104:107], v[160:163], v[192:195], v[104:107]
	v_mfma_f32_16x16x32_bf16 v[96:99], v[176:179], v[192:195], v[96:99]
	v_mfma_f32_16x16x32_bf16 v[76:79], v[160:163], v[200:203], v[76:79]
	v_mfma_f32_16x16x32_bf16 v[72:75], v[176:179], v[200:203], v[72:75]
	v_mfma_f32_16x16x32_bf16 v[68:71], v[160:163], v[208:211], v[68:71]
	v_mfma_f32_16x16x32_bf16 v[64:67], v[176:179], v[208:211], v[64:67]
	v_mfma_f32_16x16x32_bf16 v[108:111], v[172:175], v[188:191], v[108:111]
	v_mfma_f32_16x16x32_bf16 v[100:103], v[180:183], v[188:191], v[100:103]
	v_mfma_f32_16x16x32_bf16 v[104:107], v[172:175], v[196:199], v[104:107]
	v_mfma_f32_16x16x32_bf16 v[96:99], v[180:183], v[196:199], v[96:99]
	v_mfma_f32_16x16x32_bf16 v[76:79], v[172:175], v[204:207], v[76:79]
	v_mfma_f32_16x16x32_bf16 v[72:75], v[180:183], v[204:207], v[72:75]
	v_mfma_f32_16x16x32_bf16 v[68:71], v[172:175], v[212:215], v[68:71]
	v_mfma_f32_16x16x32_bf16 v[64:67], v[180:183], v[212:215], v[64:67]
	s_setprio 0
	s_barrier
	s_add_i32 s60, s3, s88
	v_lshl_add_u64 v[164:165], s[44:45], 0, v[146:147]
	s_mov_b32 m0, s60
	ds_read_b128 v[184:187], v171 offset:16384
	ds_read_b128 v[188:191], v171 offset:17408
	ds_read_b128 v[192:195], v171 offset:18432
	ds_read_b128 v[196:199], v171 offset:19456
	ds_read_b128 v[200:203], v171 offset:20480
	ds_read_b128 v[204:207], v171 offset:21504
	ds_read_b128 v[208:211], v171 offset:22528
	ds_read_b128 v[212:215], v171 offset:23552
	global_load_lds_dwordx4 v[164:165], off
	s_add_i32 m0, s60, 0x2000
	s_add_u32 s60, s44, 0x80000
	v_lshl_add_u64 v[216:217], s[44:45], 0, v[150:151]
	s_addc_u32 s61, s45, 0
	s_add_i32 s62, s53, s88
	global_load_lds_dwordx4 v[216:217], off
	v_lshl_add_u64 v[218:219], s[60:61], 0, v[146:147]
	s_mov_b32 m0, s62
	v_lshl_add_u64 v[220:221], s[46:47], 0, v[148:149]
	global_load_lds_dwordx4 v[218:219], off
	v_lshl_add_u64 v[218:219], s[60:61], 0, v[150:151]
	s_add_i32 m0, s62, 0x2000
	s_nop 0
	global_load_lds_dwordx4 v[218:219], off
	v_lshl_add_u64 v[218:219], s[46:47], 0, v[144:145]
	s_mov_b32 m0, s24
	s_nop 0
	global_load_lds_dwordx4 v[218:219], off
	s_mov_b32 m0, s25
	s_nop 0
	global_load_lds_dwordx4 v[220:221], off
	s_cmp_eq_u32 s99, 0
	s_cbranch_scc1 .Lmy_wc2n
	s_waitcnt vmcnt(40)
	s_mov_b32 s99, 0
	s_branch .Lmy_wc2d

.Lmy_wc2d:
	s_waitcnt lgkmcnt(0)
	s_barrier
	s_setprio 1
	s_waitcnt lgkmcnt(0)
	v_mfma_f32_16x16x32_bf16 v[60:63], v[128:131], v[184:187], v[60:63]
	v_mfma_f32_16x16x32_bf16 v[56:59], v[136:139], v[184:187], v[56:59]
	v_mfma_f32_16x16x32_bf16 v[52:55], v[128:131], v[192:195], v[52:55]
	v_mfma_f32_16x16x32_bf16 v[48:51], v[136:139], v[192:195], v[48:51]
	v_mfma_f32_16x16x32_bf16 v[28:31], v[128:131], v[200:203], v[28:31]
	v_mfma_f32_16x16x32_bf16 v[24:27], v[136:139], v[200:203], v[24:27]
	v_mfma_f32_16x16x32_bf16 v[20:23], v[128:131], v[208:211], v[20:23]
	v_mfma_f32_16x16x32_bf16 v[16:19], v[136:139], v[208:211], v[16:19]
	v_mfma_f32_16x16x32_bf16 v[60:63], v[132:135], v[188:191], v[60:63]
	v_mfma_f32_16x16x32_bf16 v[56:59], v[140:143], v[188:191], v[56:59]
	v_mfma_f32_16x16x32_bf16 v[52:55], v[132:135], v[196:199], v[52:55]
	v_mfma_f32_16x16x32_bf16 v[48:51], v[140:143], v[196:199], v[48:51]
	v_mfma_f32_16x16x32_bf16 v[28:31], v[132:135], v[204:207], v[28:31]
	v_mfma_f32_16x16x32_bf16 v[24:27], v[140:143], v[204:207], v[24:27]
	v_mfma_f32_16x16x32_bf16 v[20:23], v[132:135], v[212:215], v[20:23]
	v_mfma_f32_16x16x32_bf16 v[16:19], v[140:143], v[212:215], v[16:19]
	s_setprio 0
	s_setprio 1
	v_mfma_f32_16x16x32_bf16 v[44:47], v[160:163], v[184:187], v[44:47]
	v_mfma_f32_16x16x32_bf16 v[40:43], v[176:179], v[184:187], v[40:43]
	v_mfma_f32_16x16x32_bf16 v[36:39], v[160:163], v[192:195], v[36:39]
	v_mfma_f32_16x16x32_bf16 v[32:35], v[176:179], v[192:195], v[32:35]
	v_mfma_f32_16x16x32_bf16 v[12:15], v[160:163], v[200:203], v[12:15]
	v_mfma_f32_16x16x32_bf16 v[8:11], v[176:179], v[200:203], v[8:11]
	v_mfma_f32_16x16x32_bf16 v[4:7], v[160:163], v[208:211], v[4:7]
	v_mfma_f32_16x16x32_bf16 v[0:3], v[176:179], v[208:211], v[0:3]
	v_mfma_f32_16x16x32_bf16 v[44:47], v[172:175], v[188:191], v[44:47]
	v_mfma_f32_16x16x32_bf16 v[40:43], v[180:183], v[188:191], v[40:43]
	v_mfma_f32_16x16x32_bf16 v[36:39], v[172:175], v[196:199], v[36:39]
	v_mfma_f32_16x16x32_bf16 v[32:35], v[180:183], v[196:199], v[32:35]
	v_mfma_f32_16x16x32_bf16 v[12:15], v[172:175], v[204:207], v[12:15]
	v_mfma_f32_16x16x32_bf16 v[8:11], v[180:183], v[204:207], v[8:11]
	v_mfma_f32_16x16x32_bf16 v[4:7], v[172:175], v[212:215], v[4:7]
	v_mfma_f32_16x16x32_bf16 v[0:3], v[180:183], v[212:215], v[0:3]
	s_setprio 0
	s_barrier
	s_add_i32 s60, 0, 0x18000
	s_add_i32 s61, 0, 0x1c000
	v_add_u32_e32 v140, s60, v167
	v_add_u32_e32 v180, s61, v167
	ds_read_b128 v[128:131], v140
	ds_read_b128 v[132:135], v140 offset:1024
	ds_read_b128 v[136:139], v140 offset:2048
	ds_read_b128 v[140:143], v140 offset:3072
	ds_read_b128 v[160:163], v180
	ds_read_b128 v[172:175], v180 offset:1024
	ds_read_b128 v[176:179], v180 offset:2048
	ds_read_b128 v[180:183], v180 offset:3072
	s_add_u32 s46, s46, 0x80000
	s_addc_u32 s47, s47, 0
	s_mov_b32 m0, s41
	v_lshl_add_u64 v[222:223], s[46:47], 0, v[144:145]
	ds_read_b128 v[184:187], v171 offset:32768
	ds_read_b128 v[188:191], v171 offset:33792
	ds_read_b128 v[192:195], v171 offset:34816
	ds_read_b128 v[196:199], v171 offset:35840
	ds_read_b128 v[200:203], v171 offset:36864
	ds_read_b128 v[204:207], v171 offset:37888
	ds_read_b128 v[208:211], v171 offset:38912
	ds_read_b128 v[212:215], v171 offset:39936
	global_load_lds_dwordx4 v[222:223], off
	v_lshl_add_u64 v[222:223], s[46:47], 0, v[148:149]
	s_mov_b32 m0, s48
	s_nop 0
	global_load_lds_dwordx4 v[222:223], off
	s_waitcnt vmcnt(8)
	s_waitcnt lgkmcnt(0)
	s_barrier
	s_setprio 1
	s_waitcnt lgkmcnt(0)
	v_mfma_f32_16x16x32_bf16 v[120:123], v[128:131], v[184:187], v[120:123]
	v_mfma_f32_16x16x32_bf16 v[124:127], v[136:139], v[184:187], v[124:127]
	v_mfma_f32_16x16x32_bf16 v[112:115], v[128:131], v[192:195], v[112:115]
	v_mfma_f32_16x16x32_bf16 v[116:119], v[136:139], v[192:195], v[116:119]
	v_mfma_f32_16x16x32_bf16 v[92:95], v[128:131], v[200:203], v[92:95]
	v_mfma_f32_16x16x32_bf16 v[88:91], v[136:139], v[200:203], v[88:91]
	v_mfma_f32_16x16x32_bf16 v[84:87], v[128:131], v[208:211], v[84:87]
	v_mfma_f32_16x16x32_bf16 v[80:83], v[136:139], v[208:211], v[80:83]
	v_mfma_f32_16x16x32_bf16 v[120:123], v[132:135], v[188:191], v[120:123]
	v_mfma_f32_16x16x32_bf16 v[124:127], v[140:143], v[188:191], v[124:127]
	v_mfma_f32_16x16x32_bf16 v[112:115], v[132:135], v[196:199], v[112:115]
	v_mfma_f32_16x16x32_bf16 v[116:119], v[140:143], v[196:199], v[116:119]
	v_mfma_f32_16x16x32_bf16 v[92:95], v[132:135], v[204:207], v[92:95]
	v_mfma_f32_16x16x32_bf16 v[88:91], v[140:143], v[204:207], v[88:91]
	v_mfma_f32_16x16x32_bf16 v[84:87], v[132:135], v[212:215], v[84:87]
	v_mfma_f32_16x16x32_bf16 v[80:83], v[140:143], v[212:215], v[80:83]
	s_setprio 0
	s_setprio 1
	v_mfma_f32_16x16x32_bf16 v[108:111], v[160:163], v[184:187], v[108:111]
	v_mfma_f32_16x16x32_bf16 v[100:103], v[176:179], v[184:187], v[100:103]
	v_mfma_f32_16x16x32_bf16 v[104:107], v[160:163], v[192:195], v[104:107]
	v_mfma_f32_16x16x32_bf16 v[96:99], v[176:179], v[192:195], v[96:99]
	v_mfma_f32_16x16x32_bf16 v[76:79], v[160:163], v[200:203], v[76:79]
	v_mfma_f32_16x16x32_bf16 v[72:75], v[176:179], v[200:203], v[72:75]
	v_mfma_f32_16x16x32_bf16 v[68:71], v[160:163], v[208:211], v[68:71]
	v_mfma_f32_16x16x32_bf16 v[64:67], v[176:179], v[208:211], v[64:67]
	v_mfma_f32_16x16x32_bf16 v[108:111], v[172:175], v[188:191], v[108:111]
	v_mfma_f32_16x16x32_bf16 v[100:103], v[180:183], v[188:191], v[100:103]
	v_mfma_f32_16x16x32_bf16 v[104:107], v[172:175], v[196:199], v[104:107]
	v_mfma_f32_16x16x32_bf16 v[96:99], v[180:183], v[196:199], v[96:99]
	v_mfma_f32_16x16x32_bf16 v[76:79], v[172:175], v[204:207], v[76:79]
	v_mfma_f32_16x16x32_bf16 v[72:75], v[180:183], v[204:207], v[72:75]
	v_mfma_f32_16x16x32_bf16 v[68:71], v[172:175], v[212:215], v[68:71]
	v_mfma_f32_16x16x32_bf16 v[64:67], v[180:183], v[212:215], v[64:67]
	s_setprio 0
	s_barrier
	s_add_i32 s46, s60, s88
	v_lshl_add_u64 v[164:165], v[164:165], 0, s[10:11]
	s_mov_b32 m0, s46
	ds_read_b128 v[184:187], v171 offset:49152
	ds_read_b128 v[188:191], v171 offset:50176
	ds_read_b128 v[192:195], v171 offset:51200
	ds_read_b128 v[196:199], v171 offset:52224
	ds_read_b128 v[200:203], v171 offset:53248
	ds_read_b128 v[204:207], v171 offset:54272
	ds_read_b128 v[208:211], v171 offset:55296
	ds_read_b128 v[212:215], v171 offset:56320
	global_load_lds_dwordx4 v[164:165], off
	s_add_i32 m0, s46, 0x2000
	s_add_u32 s44, s44, 0x80080
	v_lshl_add_u64 v[164:165], v[216:217], 0, s[10:11]
	s_addc_u32 s45, s45, 0
	s_add_i32 s46, s61, s88
	global_load_lds_dwordx4 v[164:165], off
	v_lshl_add_u64 v[164:165], s[44:45], 0, v[146:147]
	s_mov_b32 m0, s46
	s_nop 0
	global_load_lds_dwordx4 v[164:165], off
	v_lshl_add_u64 v[164:165], s[44:45], 0, v[150:151]
	s_add_i32 m0, s46, 0x2000
	s_nop 0
	global_load_lds_dwordx4 v[164:165], off
	v_lshl_add_u64 v[164:165], v[218:219], 0, s[10:11]
	s_mov_b32 m0, s51
	s_nop 0
	global_load_lds_dwordx4 v[164:165], off
	v_lshl_add_u64 v[164:165], v[220:221], 0, s[10:11]
	s_mov_b32 m0, s52
	s_nop 0
	global_load_lds_dwordx4 v[164:165], off
	s_waitcnt vmcnt(8)
	s_waitcnt lgkmcnt(0)
	s_barrier
	s_setprio 1
	s_waitcnt lgkmcnt(0)
	v_mfma_f32_16x16x32_bf16 v[60:63], v[128:131], v[184:187], v[60:63]
	v_mfma_f32_16x16x32_bf16 v[56:59], v[136:139], v[184:187], v[56:59]
	v_mfma_f32_16x16x32_bf16 v[52:55], v[128:131], v[192:195], v[52:55]
	v_mfma_f32_16x16x32_bf16 v[48:51], v[136:139], v[192:195], v[48:51]
	v_mfma_f32_16x16x32_bf16 v[28:31], v[128:131], v[200:203], v[28:31]
	v_mfma_f32_16x16x32_bf16 v[24:27], v[136:139], v[200:203], v[24:27]
	v_mfma_f32_16x16x32_bf16 v[20:23], v[128:131], v[208:211], v[20:23]
	v_mfma_f32_16x16x32_bf16 v[16:19], v[136:139], v[208:211], v[16:19]
	v_mfma_f32_16x16x32_bf16 v[60:63], v[132:135], v[188:191], v[60:63]
	v_mfma_f32_16x16x32_bf16 v[56:59], v[140:143], v[188:191], v[56:59]
	v_mfma_f32_16x16x32_bf16 v[52:55], v[132:135], v[196:199], v[52:55]
	v_mfma_f32_16x16x32_bf16 v[48:51], v[140:143], v[196:199], v[48:51]
	v_mfma_f32_16x16x32_bf16 v[28:31], v[132:135], v[204:207], v[28:31]
	v_mfma_f32_16x16x32_bf16 v[24:27], v[140:143], v[204:207], v[24:27]
	v_mfma_f32_16x16x32_bf16 v[20:23], v[132:135], v[212:215], v[20:23]
	v_mfma_f32_16x16x32_bf16 v[16:19], v[140:143], v[212:215], v[16:19]
	s_setprio 0
	s_setprio 1
	v_mfma_f32_16x16x32_bf16 v[44:47], v[160:163], v[184:187], v[44:47]
	v_mfma_f32_16x16x32_bf16 v[40:43], v[176:179], v[184:187], v[40:43]
	v_mfma_f32_16x16x32_bf16 v[36:39], v[160:163], v[192:195], v[36:39]
	v_mfma_f32_16x16x32_bf16 v[32:35], v[176:179], v[192:195], v[32:35]
	v_mfma_f32_16x16x32_bf16 v[12:15], v[160:163], v[200:203], v[12:15]
	v_mfma_f32_16x16x32_bf16 v[8:11], v[176:179], v[200:203], v[8:11]
	v_mfma_f32_16x16x32_bf16 v[4:7], v[160:163], v[208:211], v[4:7]
	v_mfma_f32_16x16x32_bf16 v[0:3], v[176:179], v[208:211], v[0:3]
	v_mfma_f32_16x16x32_bf16 v[44:47], v[172:175], v[188:191], v[44:47]
	v_mfma_f32_16x16x32_bf16 v[40:43], v[180:183], v[188:191], v[40:43]
	v_mfma_f32_16x16x32_bf16 v[36:39], v[172:175], v[196:199], v[36:39]
	v_mfma_f32_16x16x32_bf16 v[32:35], v[180:183], v[196:199], v[32:35]
	v_mfma_f32_16x16x32_bf16 v[12:15], v[172:175], v[204:207], v[12:15]
	v_mfma_f32_16x16x32_bf16 v[8:11], v[180:183], v[204:207], v[8:11]
	v_mfma_f32_16x16x32_bf16 v[4:7], v[172:175], v[212:215], v[4:7]
	v_mfma_f32_16x16x32_bf16 v[0:3], v[180:183], v[212:215], v[0:3]
	s_setprio 0
	s_barrier
	s_add_i32 s59, s59, 2
	s_add_u32 s42, s42, 0x100
	s_addc_u32 s43, s43, 0
	s_add_u32 s57, s57, 0x100
	s_addc_u32 s58, s58, 0
	s_cmp_gt_u32 s59, 29
	s_cbranch_scc0 .LBB0_799
	s_and_b64 vcc, exec, s[12:13]
	s_cbranch_vccz .LBB0_802
	s_barrier
